# ds_bpermute butterfly steps (lane^1,2 -> DPP quad_perm add; lane^16,32 -> permlane16/32_swap) in rstd/ssq reductions
# speedup vs baseline: 1.0090x; 1.0041x over previous
.LBB0_162:
	s_waitcnt lgkmcnt(0)
	v_mov_b32_e32 v132, v226
	v_and_b32_e32 v133, 64, v219
	v_ashrrev_i32_e32 v128, 31, v132
	v_lshrrev_b32_e32 v128, 30, v128
	v_add_u32_e32 v128, v132, v128
	v_ashrrev_i32_e32 v144, 2, v128
	v_and_b32_e32 v128, 0x3ffffffc, v128
	v_lshlrev_b32_e32 v130, 1, v144
	v_sub_u32_e32 v128, v132, v128
	v_and_b32_e32 v130, 0xffffff80, v130
	v_and_or_b32 v131, v144, 63, s42
	v_lshlrev_b32_e32 v128, 2, v128
	v_add_u32_e32 v130, v131, v130
	v_ashrrev_i32_e32 v129, 31, v128
	v_ashrrev_i32_e32 v131, 31, v130
	v_lshl_add_u64 v[128:129], v[128:129], 2, s[8:9]
	v_lshlrev_b64 v[134:135], 6, v[130:131]
	v_lshl_add_u64 v[134:135], v[128:129], 0, v[134:135]
	global_load_dwordx4 v[148:151], v[134:135], off offset:1024
	global_load_dwordx4 v[152:155], v[134:135], off offset:2048
	global_load_dwordx4 v[156:159], v[134:135], off offset:3072
	v_add_co_u32_e32 v250, vcc, 0x2000, v134
	v_addc_co_u32_e32 v251, vcc, 0, v135, vcc
	global_load_dwordx4 v[160:163], v[250:251], off
	global_load_dwordx4 v[164:167], v[250:251], off offset:1024
	global_load_dwordx4 v[168:171], v[250:251], off offset:2048
	global_load_dwordx4 v[172:175], v[250:251], off offset:3072
	global_load_dwordx4 v[134:137], v[134:135], off
	v_add_u32_e32 v138, 64, v133
	v_add_u32_e32 v130, 0x80, v130
	s_waitcnt vmcnt(0)
	v_add_f32_e32 v131, v134, v135
	v_add_f32_e32 v134, v136, v137
	v_add_f32_e32 v131, v131, v134
	v_xor_b32_e32 v134, 1, v219
	v_cmp_lt_i32_e32 vcc, v134, v138
	s_nop 1
	v_cndmask_b32_e32 v134, v219, v134, vcc
	v_lshlrev_b32_e32 v136, 2, v134
	s_nop 1
	s_waitcnt lgkmcnt(0)
	v_add_f32_dpp v131, v131, v131 quad_perm:[1,0,3,2] row_mask:0xf bank_mask:0xf
	v_xor_b32_e32 v134, 2, v219
	v_cmp_lt_i32_e32 vcc, v134, v138
	s_nop 1
	v_cndmask_b32_e32 v134, v219, v134, vcc
	v_lshlrev_b32_e32 v135, 2, v134
	s_nop 1
	s_waitcnt lgkmcnt(0)
	v_add_f32_dpp v131, v131, v131 quad_perm:[2,3,0,1] row_mask:0xf bank_mask:0xf
	v_fmamk_f32 v131, v131, 0x3a800000, v220
	v_rsq_f32_e32 v134, v131
	v_add_u32_e32 v131, 16, v144
	v_lshlrev_b32_e32 v137, 1, v131
	v_and_b32_e32 v137, 0xffffff80, v137
	v_and_or_b32 v131, v131, 63, s42
	v_add_u32_e32 v138, v131, v137
	v_ashrrev_i32_e32 v139, 31, v138
	v_lshlrev_b64 v[138:139], 6, v[138:139]
	v_lshl_add_u64 v[138:139], v[128:129], 0, v[138:139]
	s_waitcnt vmcnt(0)
	v_add_f32_e32 v131, v148, v149
	v_add_f32_e32 v137, v150, v151
	v_add_f32_e32 v131, v131, v137
	s_nop 1
	s_waitcnt lgkmcnt(0)
	v_add_f32_dpp v131, v131, v131 quad_perm:[1,0,3,2] row_mask:0xf bank_mask:0xf
	s_nop 1
	s_waitcnt lgkmcnt(0)
	v_add_f32_dpp v131, v131, v131 quad_perm:[2,3,0,1] row_mask:0xf bank_mask:0xf
	v_fmamk_f32 v131, v131, 0x3a800000, v220
	v_rsq_f32_e32 v137, v131
	v_add_u32_e32 v131, 32, v144
	v_lshlrev_b32_e32 v138, 1, v131
	v_and_b32_e32 v138, 0xffffff80, v138
	v_and_or_b32 v131, v131, 63, s42
	v_add_u32_e32 v138, v131, v138
	v_ashrrev_i32_e32 v139, 31, v138
	v_lshlrev_b64 v[138:139], 6, v[138:139]
	v_lshl_add_u64 v[138:139], v[128:129], 0, v[138:139]
	s_waitcnt vmcnt(0)
	v_add_f32_e32 v131, v152, v153
	v_add_f32_e32 v138, v154, v155
	v_add_f32_e32 v131, v131, v138
	s_nop 1
	s_waitcnt lgkmcnt(0)
	v_add_f32_dpp v131, v131, v131 quad_perm:[1,0,3,2] row_mask:0xf bank_mask:0xf
	s_nop 1
	s_waitcnt lgkmcnt(0)
	v_add_f32_dpp v131, v131, v131 quad_perm:[2,3,0,1] row_mask:0xf bank_mask:0xf
	v_fmamk_f32 v131, v131, 0x3a800000, v220
	v_rsq_f32_e32 v138, v131
	v_add_u32_e32 v131, 48, v144
	v_lshlrev_b32_e32 v139, 1, v131
	v_and_b32_e32 v139, 0xffffff80, v139
	v_and_or_b32 v131, v131, 63, s42
	v_add_u32_e32 v140, v131, v139
	v_ashrrev_i32_e32 v141, 31, v140
	v_lshlrev_b64 v[140:141], 6, v[140:141]
	v_lshl_add_u64 v[140:141], v[128:129], 0, v[140:141]
	s_waitcnt vmcnt(0)
	v_add_f32_e32 v131, v156, v157
	v_add_f32_e32 v139, v158, v159
	v_add_f32_e32 v131, v131, v139
	s_nop 1
	s_waitcnt lgkmcnt(0)
	v_add_f32_dpp v131, v131, v131 quad_perm:[1,0,3,2] row_mask:0xf bank_mask:0xf
	s_nop 1
	s_waitcnt lgkmcnt(0)
	v_add_f32_dpp v131, v131, v131 quad_perm:[2,3,0,1] row_mask:0xf bank_mask:0xf
	v_fmamk_f32 v131, v131, 0x3a800000, v220
	v_rsq_f32_e32 v139, v131
	v_ashrrev_i32_e32 v131, 31, v130
	v_lshlrev_b64 v[130:131], 6, v[130:131]
	v_lshl_add_u64 v[130:131], v[128:129], 0, v[130:131]
	s_waitcnt vmcnt(0)
	v_add_f32_e32 v130, v160, v161
	v_add_f32_e32 v131, v162, v163
	v_add_f32_e32 v130, v130, v131
	s_nop 1
	s_waitcnt lgkmcnt(0)
	v_add_f32_dpp v130, v130, v130 quad_perm:[1,0,3,2] row_mask:0xf bank_mask:0xf
	s_nop 1
	s_waitcnt lgkmcnt(0)
	v_add_f32_dpp v130, v130, v130 quad_perm:[2,3,0,1] row_mask:0xf bank_mask:0xf
	v_fmamk_f32 v130, v130, 0x3a800000, v220
	v_rsq_f32_e32 v145, v130
	v_add_u32_e32 v130, 0x50, v144
	v_lshlrev_b32_e32 v131, 1, v130
	v_and_b32_e32 v131, 0xffffff80, v131
	v_and_or_b32 v130, v130, 63, s42
	v_add_u32_e32 v130, v130, v131
	v_ashrrev_i32_e32 v131, 31, v130
	v_lshlrev_b64 v[130:131], 6, v[130:131]
	v_lshl_add_u64 v[130:131], v[128:129], 0, v[130:131]
	s_waitcnt vmcnt(0)
	v_add_f32_e32 v130, v164, v165
	v_add_f32_e32 v131, v166, v167
	v_add_f32_e32 v130, v130, v131
	s_nop 1
	s_waitcnt lgkmcnt(0)
	v_add_f32_dpp v130, v130, v130 quad_perm:[1,0,3,2] row_mask:0xf bank_mask:0xf
	s_nop 1
	s_waitcnt lgkmcnt(0)
	v_add_f32_dpp v130, v130, v130 quad_perm:[2,3,0,1] row_mask:0xf bank_mask:0xf
	v_fmamk_f32 v130, v130, 0x3a800000, v220
	v_rsq_f32_e32 v146, v130
	v_add_u32_e32 v130, 0x60, v144
	v_lshlrev_b32_e32 v131, 1, v130
	v_and_b32_e32 v131, 0xffffff80, v131
	v_and_or_b32 v130, v130, 63, s42
	v_add_u32_e32 v130, v130, v131
	v_ashrrev_i32_e32 v131, 31, v130
	v_lshlrev_b64 v[130:131], 6, v[130:131]
	v_lshl_add_u64 v[130:131], v[128:129], 0, v[130:131]
	s_waitcnt vmcnt(0)
	v_add_f32_e32 v130, v168, v169
	v_add_f32_e32 v131, v170, v171
	v_add_f32_e32 v130, v130, v131
	s_nop 1
	s_waitcnt lgkmcnt(0)
	v_add_f32_dpp v130, v130, v130 quad_perm:[1,0,3,2] row_mask:0xf bank_mask:0xf
	s_nop 1
	s_waitcnt lgkmcnt(0)
	v_add_f32_dpp v130, v130, v130 quad_perm:[2,3,0,1] row_mask:0xf bank_mask:0xf
	v_fmamk_f32 v130, v130, 0x3a800000, v220
	v_rsq_f32_e32 v140, v130
	v_add_u32_e32 v130, 0x70, v144
	v_lshlrev_b32_e32 v131, 1, v130
	v_and_b32_e32 v131, 0xffffff80, v131
	v_and_or_b32 v130, v130, 63, s42
	v_add_u32_e32 v130, v130, v131
	v_ashrrev_i32_e32 v131, 31, v130
	v_lshlrev_b64 v[130:131], 6, v[130:131]
	v_lshl_add_u64 v[128:129], v[128:129], 0, v[130:131]
	s_waitcnt vmcnt(0)
	v_add_f32_e32 v128, v172, v173
	v_add_f32_e32 v129, v174, v175
	v_add_f32_e32 v128, v128, v129
	s_nop 1
	s_waitcnt lgkmcnt(0)
	v_add_f32_dpp v128, v128, v128 quad_perm:[1,0,3,2] row_mask:0xf bank_mask:0xf
	s_nop 1
	s_waitcnt lgkmcnt(0)
	v_add_f32_dpp v128, v128, v128 quad_perm:[2,3,0,1] row_mask:0xf bank_mask:0xf
	v_fmamk_f32 v128, v128, 0x3a800000, v220
	v_rsq_f32_e32 v135, v128
	v_lshlrev_b32_e32 v128, 2, v132
	v_and_or_b32 v128, v128, 60, v133
	v_lshlrev_b32_e32 v136, 2, v128
	ds_bpermute_b32 v128, v136, v134
	ds_bpermute_b32 v129, v136, v137
	ds_bpermute_b32 v130, v136, v138
	ds_bpermute_b32 v131, v136, v139
	ds_bpermute_b32 v132, v136, v145
	ds_bpermute_b32 v133, v136, v146
	ds_bpermute_b32 v134, v136, v140
	ds_bpermute_b32 v135, v136, v135
	s_and_saveexec_b64 s[10:11], s[38:39]
	s_cbranch_execz .LBB0_164
	s_waitcnt lgkmcnt(6)
	ds_write2_b32 v227, v128, v129 offset1:16
	s_waitcnt lgkmcnt(5)
	ds_write2_b32 v227, v130, v131 offset0:32 offset1:48
	s_waitcnt lgkmcnt(4)
	ds_write2_b32 v227, v132, v133 offset0:64 offset1:80
	s_waitcnt lgkmcnt(3)
	ds_write2_b32 v227, v134, v135 offset0:96 offset1:112

.LBB0_265:
	v_lshl_or_b32 v166, s16, 8, v196
	v_lshl_add_u32 v170, s68, 8, v194
	v_ashrrev_i32_e32 v167, 31, v166
	v_lshlrev_b64 v[204:205], 1, v[166:167]
	v_ashrrev_i32_e32 v171, 31, v170
	v_lshl_add_u64 v[168:169], s[18:19], 0, v[204:205]
	v_lshlrev_b64 v[206:207], 11, v[170:171]
	v_lshl_add_u64 v[128:129], v[168:169], 0, v[206:207]
	global_load_dwordx4 v[200:203], v[128:129], off
	global_load_dwordx4 v[152:155], v[128:129], off offset:256
	v_or_b32_e32 v190, 16, v170
	v_ashrrev_i32_e32 v191, 31, v190
	v_or_b32_e32 v186, 32, v170
	v_lshlrev_b64 v[192:193], 11, v[190:191]
	v_ashrrev_i32_e32 v187, 31, v186
	v_or_b32_e32 v172, 48, v170
	v_lshl_add_u64 v[128:129], v[168:169], 0, v[192:193]
	v_lshlrev_b64 v[188:189], 11, v[186:187]
	v_ashrrev_i32_e32 v173, 31, v172
	global_load_dwordx4 v[148:151], v[128:129], off
	global_load_dwordx4 v[144:147], v[128:129], off offset:256
	v_lshl_add_u64 v[128:129], v[168:169], 0, v[188:189]
	v_lshlrev_b64 v[174:175], 11, v[172:173]
	global_load_dwordx4 v[140:143], v[128:129], off
	global_load_dwordx4 v[136:139], v[128:129], off offset:256
	v_lshl_add_u64 v[128:129], v[168:169], 0, v[174:175]
	global_load_dwordx4 v[132:135], v[128:129], off
	s_nop 0
	global_load_dwordx4 v[128:131], v[128:129], off offset:256
	v_add_u32_e32 v216, 0x80, v170
	v_ashrrev_i32_e32 v217, 31, v216
	v_lshlrev_b64 v[216:217], 11, v[216:217]
	v_lshl_add_u64 v[216:217], v[168:169], 0, v[216:217]
	global_load_dwordx4 v[212:215], v[216:217], off
	global_load_dwordx4 v[222:225], v[216:217], off offset:256
	v_add_u32_e32 v216, 0x90, v170
	v_ashrrev_i32_e32 v217, 31, v216
	v_lshlrev_b64 v[216:217], 11, v[216:217]
	v_lshl_add_u64 v[216:217], v[168:169], 0, v[216:217]
	global_load_dwordx4 v[226:229], v[216:217], off
	global_load_dwordx4 v[230:233], v[216:217], off offset:256
	v_add_u32_e32 v216, 0xa0, v170
	v_ashrrev_i32_e32 v217, 31, v216
	v_lshlrev_b64 v[216:217], 11, v[216:217]
	v_lshl_add_u64 v[216:217], v[168:169], 0, v[216:217]
	global_load_dwordx4 v[234:237], v[216:217], off
	global_load_dwordx4 v[238:241], v[216:217], off offset:256
	v_add_u32_e32 v216, 0xb0, v170
	v_ashrrev_i32_e32 v217, 31, v216
	v_lshlrev_b64 v[216:217], 11, v[216:217]
	v_lshl_add_u64 v[216:217], v[168:169], 0, v[216:217]
	global_load_dwordx4 v[242:245], v[216:217], off
	global_load_dwordx4 v[246:249], v[216:217], off offset:256
	v_and_b32_e32 v199, 64, v219
	v_xor_b32_e32 v198, 16, v219
	v_add_u32_e32 v199, 64, v199
	v_cmp_lt_i32_e32 vcc, v198, v199
	v_xor_b32_e32 v208, 32, v219
	s_lshl_b32 s30, s16, 2
	v_cndmask_b32_e32 v198, v219, v198, vcc
	v_cmp_lt_i32_e32 vcc, v208, v199
	v_lshlrev_b32_e32 v198, 2, v198
	s_ashr_i32 s31, s30, 31
	v_cndmask_b32_e32 v199, v219, v208, vcc
	v_lshlrev_b32_e32 v199, 2, v199
	s_waitcnt vmcnt(0)
	v_lshlrev_b32_e32 v208, 16, v200
	v_and_b32_e32 v209, 0xffff0000, v200
	v_lshlrev_b32_e32 v200, 16, v201
	v_and_b32_e32 v201, 0xffff0000, v201
	v_lshlrev_b32_e32 v210, 16, v202
	v_and_b32_e32 v211, 0xffff0000, v202
	v_lshlrev_b32_e32 v202, 16, v203
	v_and_b32_e32 v203, 0xffff0000, v203
	v_pk_add_f32 v[200:201], v[122:123], v[200:201]
	v_pk_add_f32 v[208:209], v[120:121], v[208:209]
	v_pk_add_f32 v[126:127], v[126:127], v[202:203]
	v_pk_add_f32 v[124:125], v[124:125], v[210:211]
	v_lshl_add_u64 v[202:203], s[18:19], 0, v[206:207]
	v_cvt_pk_bf16_f32 v120, v208, v209
	v_cvt_pk_bf16_f32 v121, v200, v201
	v_cvt_pk_bf16_f32 v122, v124, v125
	v_cvt_pk_bf16_f32 v123, v126, v127
	v_lshl_add_u64 v[202:203], v[202:203], 0, v[204:205]
	global_store_dwordx4 v[202:203], v[120:123], off
	s_nop 1
	v_mul_f32_e32 v120, v209, v209
	v_mul_f32_e32 v121, v201, v201
	v_fmac_f32_e32 v120, v208, v208
	v_fmac_f32_e32 v121, v200, v200
	v_add_f32_e32 v120, v120, v121
	v_mul_f32_e32 v121, v125, v125
	v_mul_f32_e32 v122, v127, v127
	v_fmac_f32_e32 v121, v124, v124
	v_fmac_f32_e32 v122, v126, v126
	v_add_f32_e32 v121, v121, v122
	v_add_f32_e32 v200, v120, v121
	v_lshlrev_b32_e32 v120, 16, v152
	v_and_b32_e32 v121, 0xffff0000, v152
	v_lshlrev_b32_e32 v122, 16, v153
	v_and_b32_e32 v123, 0xffff0000, v153
	v_lshlrev_b32_e32 v124, 16, v154
	v_and_b32_e32 v125, 0xffff0000, v154
	v_lshlrev_b32_e32 v126, 16, v155
	v_and_b32_e32 v127, 0xffff0000, v155
	v_pk_add_f32 v[118:119], v[118:119], v[122:123]
	v_pk_add_f32 v[116:117], v[116:117], v[120:121]
	v_pk_add_f32 v[120:121], v[114:115], v[126:127]
	v_pk_add_f32 v[122:123], v[112:113], v[124:125]
	v_cvt_pk_bf16_f32 v112, v116, v117
	v_cvt_pk_bf16_f32 v113, v118, v119
	v_cvt_pk_bf16_f32 v114, v122, v123
	v_cvt_pk_bf16_f32 v115, v120, v121
	global_store_dwordx4 v[202:203], v[112:115], off offset:256
	s_nop 1
	v_mul_f32_e32 v112, v117, v117
	v_mul_f32_e32 v113, v119, v119
	v_fmac_f32_e32 v112, v116, v116
	v_fmac_f32_e32 v113, v118, v118
	v_add_f32_e32 v112, v112, v113
	v_mul_f32_e32 v113, v123, v123
	v_mul_f32_e32 v114, v121, v121
	v_fmac_f32_e32 v113, v122, v122
	v_fmac_f32_e32 v114, v120, v120
	v_add_f32_e32 v113, v113, v114
	v_add_f32_e32 v112, v112, v113
	v_add_f32_e32 v112, v200, v112
	v_mov_b32_e32 v113, v112
	v_mov_b32_e32 v252, v112
	s_nop 1
	v_permlane16_swap_b32_e32 v113, v252
	s_waitcnt lgkmcnt(0)
	v_add_f32_e32 v112, v113, v252
	v_mov_b32_e32 v113, v112
	v_mov_b32_e32 v252, v112
	s_nop 1
	v_permlane32_swap_b32_e32 v113, v252
	s_and_saveexec_b64 s[10:11], s[40:41]
	s_cbranch_execz .LBB0_267
	s_waitcnt lgkmcnt(0)
	v_add_f32_e32 v114, v113, v252
	v_lshlrev_b64 v[112:113], 6, v[170:171]
	v_lshl_add_u64 v[112:113], s[6:7], 0, v[112:113]
	v_lshl_add_u64 v[112:113], s[30:31], 2, v[112:113]
	s_lshl_b32 s16, s58, 2
	v_lshl_add_u64 v[112:113], v[112:113], 0, s[16:17]
	global_store_dword v[112:113], v114, off
.LBB0_267:
	s_or_b64 exec, exec, s[10:11]
	v_lshlrev_b32_e32 v112, 16, v148
	s_waitcnt lgkmcnt(0)
	v_and_b32_e32 v113, 0xffff0000, v148
	v_lshlrev_b32_e32 v114, 16, v149
	v_and_b32_e32 v115, 0xffff0000, v149
	v_lshlrev_b32_e32 v116, 16, v150
	v_and_b32_e32 v117, 0xffff0000, v150
	v_pk_add_f32 v[108:109], v[108:109], v[112:113]
	v_pk_add_f32 v[110:111], v[110:111], v[114:115]
	v_pk_add_f32 v[114:115], v[104:105], v[116:117]
	v_cvt_pk_bf16_f32 v104, v108, v109
	v_mul_f32_e32 v109, v109, v109
	v_lshlrev_b32_e32 v118, 16, v151
	v_and_b32_e32 v119, 0xffff0000, v151
	v_fmac_f32_e32 v109, v108, v108
	v_mul_f32_e32 v108, v111, v111
	v_pk_add_f32 v[112:113], v[106:107], v[118:119]
	v_fmac_f32_e32 v108, v110, v110
	v_cvt_pk_bf16_f32 v105, v110, v111
	v_add_f32_e32 v108, v109, v108
	v_mul_f32_e32 v109, v115, v115
	v_mul_f32_e32 v110, v113, v113
	v_fmac_f32_e32 v109, v114, v114
	v_fmac_f32_e32 v110, v112, v112
	v_add_f32_e32 v109, v109, v110
	v_add_f32_e32 v116, v108, v109
	v_lshlrev_b32_e32 v108, 16, v144
	v_and_b32_e32 v109, 0xffff0000, v144
	v_lshlrev_b32_e32 v110, 16, v145
	v_and_b32_e32 v111, 0xffff0000, v145
	v_cvt_pk_bf16_f32 v107, v112, v113
	v_lshlrev_b32_e32 v112, 16, v146
	v_and_b32_e32 v113, 0xffff0000, v146
	v_pk_add_f32 v[102:103], v[102:103], v[110:111]
	v_pk_add_f32 v[100:101], v[100:101], v[108:109]
	v_cvt_pk_bf16_f32 v106, v114, v115
	v_lshlrev_b32_e32 v114, 16, v147
	v_and_b32_e32 v115, 0xffff0000, v147
	v_pk_add_f32 v[110:111], v[96:97], v[112:113]
	v_mul_f32_e32 v96, v101, v101
	v_mul_f32_e32 v97, v103, v103
	v_pk_add_f32 v[108:109], v[98:99], v[114:115]
	v_fmac_f32_e32 v96, v100, v100
	v_fmac_f32_e32 v97, v102, v102
	v_add_f32_e32 v96, v96, v97
	v_mul_f32_e32 v97, v111, v111
	v_mul_f32_e32 v98, v109, v109
	v_fmac_f32_e32 v97, v110, v110
	v_fmac_f32_e32 v98, v108, v108
	v_add_f32_e32 v97, v97, v98
	v_add_f32_e32 v96, v96, v97
	v_add_f32_e32 v99, v116, v96
	v_mov_b32_e32 v114, v99
	v_mov_b32_e32 v252, v99
	s_nop 1
	v_permlane16_swap_b32_e32 v114, v252
	v_lshl_add_u64 v[96:97], s[18:19], 0, v[192:193]
	v_lshl_add_u64 v[112:113], v[166:167], 1, v[96:97]
	v_cvt_pk_bf16_f32 v98, v100, v101
	v_cvt_pk_bf16_f32 v100, v110, v111
	s_waitcnt lgkmcnt(0)
	v_add_f32_e32 v96, v114, v252
	v_mov_b32_e32 v97, v96
	v_mov_b32_e32 v252, v96
	s_nop 1
	v_permlane32_swap_b32_e32 v97, v252
	v_cvt_pk_bf16_f32 v99, v102, v103
	v_cvt_pk_bf16_f32 v101, v108, v109
	global_store_dwordx4 v[112:113], v[104:107], off
	global_store_dwordx4 v[112:113], v[98:101], off offset:256
	s_and_saveexec_b64 s[10:11], s[40:41]
	s_cbranch_execz .LBB0_269
	s_waitcnt lgkmcnt(0)
	v_add_f32_e32 v98, v97, v252
	v_lshlrev_b64 v[96:97], 6, v[190:191]
	v_lshl_add_u64 v[96:97], s[6:7], 0, v[96:97]
	v_lshl_add_u64 v[96:97], s[30:31], 2, v[96:97]
	s_lshl_b32 s16, s58, 2
	v_lshl_add_u64 v[96:97], v[96:97], 0, s[16:17]
	global_store_dword v[96:97], v98, off
.LBB0_269:
	s_or_b64 exec, exec, s[10:11]
	v_lshlrev_b32_e32 v96, 16, v140
	s_waitcnt lgkmcnt(0)
	v_and_b32_e32 v97, 0xffff0000, v140
	v_lshlrev_b32_e32 v98, 16, v141
	v_and_b32_e32 v99, 0xffff0000, v141
	v_lshlrev_b32_e32 v100, 16, v142
	v_and_b32_e32 v101, 0xffff0000, v142
	v_pk_add_f32 v[92:93], v[92:93], v[96:97]
	v_pk_add_f32 v[94:95], v[94:95], v[98:99]
	v_pk_add_f32 v[98:99], v[88:89], v[100:101]
	v_cvt_pk_bf16_f32 v88, v92, v93
	v_mul_f32_e32 v93, v93, v93
	v_lshlrev_b32_e32 v102, 16, v143
	v_and_b32_e32 v103, 0xffff0000, v143
	v_fmac_f32_e32 v93, v92, v92
	v_mul_f32_e32 v92, v95, v95
	v_pk_add_f32 v[96:97], v[90:91], v[102:103]
	v_fmac_f32_e32 v92, v94, v94
	v_cvt_pk_bf16_f32 v89, v94, v95
	v_add_f32_e32 v92, v93, v92
	v_mul_f32_e32 v93, v99, v99
	v_mul_f32_e32 v94, v97, v97
	v_fmac_f32_e32 v93, v98, v98
	v_fmac_f32_e32 v94, v96, v96
	v_add_f32_e32 v93, v93, v94
	v_add_f32_e32 v100, v92, v93
	v_lshlrev_b32_e32 v92, 16, v136
	v_and_b32_e32 v93, 0xffff0000, v136
	v_lshlrev_b32_e32 v94, 16, v137
	v_and_b32_e32 v95, 0xffff0000, v137
	v_cvt_pk_bf16_f32 v91, v96, v97
	v_lshlrev_b32_e32 v96, 16, v138
	v_and_b32_e32 v97, 0xffff0000, v138
	v_pk_add_f32 v[86:87], v[86:87], v[94:95]
	v_pk_add_f32 v[84:85], v[84:85], v[92:93]
	v_cvt_pk_bf16_f32 v90, v98, v99
	v_lshlrev_b32_e32 v98, 16, v139
	v_and_b32_e32 v99, 0xffff0000, v139
	v_pk_add_f32 v[94:95], v[80:81], v[96:97]
	v_mul_f32_e32 v80, v85, v85
	v_mul_f32_e32 v81, v87, v87
	v_pk_add_f32 v[92:93], v[82:83], v[98:99]
	v_fmac_f32_e32 v80, v84, v84
	v_fmac_f32_e32 v81, v86, v86
	v_add_f32_e32 v80, v80, v81
	v_mul_f32_e32 v81, v95, v95
	v_mul_f32_e32 v82, v93, v93
	v_fmac_f32_e32 v81, v94, v94
	v_fmac_f32_e32 v82, v92, v92
	v_add_f32_e32 v81, v81, v82
	v_add_f32_e32 v80, v80, v81
	v_add_f32_e32 v83, v100, v80
	v_mov_b32_e32 v98, v83
	v_mov_b32_e32 v252, v83
	s_nop 1
	v_permlane16_swap_b32_e32 v98, v252
	v_lshl_add_u64 v[80:81], s[18:19], 0, v[188:189]
	v_lshl_add_u64 v[96:97], v[166:167], 1, v[80:81]
	v_cvt_pk_bf16_f32 v82, v84, v85
	v_cvt_pk_bf16_f32 v84, v94, v95
	s_waitcnt lgkmcnt(0)
	v_add_f32_e32 v80, v98, v252
	v_mov_b32_e32 v81, v80
	v_mov_b32_e32 v252, v80
	s_nop 1
	v_permlane32_swap_b32_e32 v81, v252
	v_cvt_pk_bf16_f32 v83, v86, v87
	v_cvt_pk_bf16_f32 v85, v92, v93
	global_store_dwordx4 v[96:97], v[88:91], off
	global_store_dwordx4 v[96:97], v[82:85], off offset:256
	s_and_saveexec_b64 s[10:11], s[40:41]
	s_cbranch_execz .LBB0_271
	s_waitcnt lgkmcnt(0)
	v_add_f32_e32 v82, v81, v252
	v_lshlrev_b64 v[80:81], 6, v[186:187]
	v_lshl_add_u64 v[80:81], s[6:7], 0, v[80:81]
	v_lshl_add_u64 v[80:81], s[30:31], 2, v[80:81]
	s_lshl_b32 s16, s58, 2
	v_lshl_add_u64 v[80:81], v[80:81], 0, s[16:17]
	global_store_dword v[80:81], v82, off
.LBB0_271:
	s_or_b64 exec, exec, s[10:11]
	v_lshlrev_b32_e32 v80, 16, v132
	s_waitcnt lgkmcnt(0)
	v_and_b32_e32 v81, 0xffff0000, v132
	v_lshlrev_b32_e32 v82, 16, v133
	v_and_b32_e32 v83, 0xffff0000, v133
	v_lshlrev_b32_e32 v84, 16, v134
	v_and_b32_e32 v85, 0xffff0000, v134
	v_pk_add_f32 v[76:77], v[76:77], v[80:81]
	v_pk_add_f32 v[78:79], v[78:79], v[82:83]
	v_pk_add_f32 v[82:83], v[72:73], v[84:85]
	v_cvt_pk_bf16_f32 v72, v76, v77
	v_mul_f32_e32 v77, v77, v77
	v_lshlrev_b32_e32 v86, 16, v135
	v_and_b32_e32 v87, 0xffff0000, v135
	v_fmac_f32_e32 v77, v76, v76
	v_mul_f32_e32 v76, v79, v79
	v_pk_add_f32 v[80:81], v[74:75], v[86:87]
	v_fmac_f32_e32 v76, v78, v78
	v_cvt_pk_bf16_f32 v73, v78, v79
	v_add_f32_e32 v76, v77, v76
	v_mul_f32_e32 v77, v83, v83
	v_mul_f32_e32 v78, v81, v81
	v_fmac_f32_e32 v77, v82, v82
	v_fmac_f32_e32 v78, v80, v80
	v_add_f32_e32 v77, v77, v78
	v_add_f32_e32 v84, v76, v77
	v_lshlrev_b32_e32 v76, 16, v128
	v_and_b32_e32 v77, 0xffff0000, v128
	v_lshlrev_b32_e32 v78, 16, v129
	v_and_b32_e32 v79, 0xffff0000, v129
	v_cvt_pk_bf16_f32 v75, v80, v81
	v_lshlrev_b32_e32 v80, 16, v130
	v_and_b32_e32 v81, 0xffff0000, v130
	v_pk_add_f32 v[70:71], v[70:71], v[78:79]
	v_pk_add_f32 v[68:69], v[68:69], v[76:77]
	v_cvt_pk_bf16_f32 v74, v82, v83
	v_lshlrev_b32_e32 v82, 16, v131
	v_and_b32_e32 v83, 0xffff0000, v131
	v_pk_add_f32 v[78:79], v[64:65], v[80:81]
	v_mul_f32_e32 v64, v69, v69
	v_mul_f32_e32 v65, v71, v71
	v_pk_add_f32 v[76:77], v[66:67], v[82:83]
	v_fmac_f32_e32 v64, v68, v68
	v_fmac_f32_e32 v65, v70, v70
	v_add_f32_e32 v64, v64, v65
	v_mul_f32_e32 v65, v79, v79
	v_mul_f32_e32 v66, v77, v77
	v_fmac_f32_e32 v65, v78, v78
	v_fmac_f32_e32 v66, v76, v76
	v_add_f32_e32 v65, v65, v66
	v_add_f32_e32 v64, v64, v65
	v_add_f32_e32 v67, v84, v64
	v_mov_b32_e32 v82, v67
	v_mov_b32_e32 v252, v67
	s_nop 1
	v_permlane16_swap_b32_e32 v82, v252
	v_lshl_add_u64 v[64:65], s[18:19], 0, v[174:175]
	v_lshl_add_u64 v[80:81], v[166:167], 1, v[64:65]
	v_cvt_pk_bf16_f32 v66, v68, v69
	v_cvt_pk_bf16_f32 v68, v78, v79
	s_waitcnt lgkmcnt(0)
	v_add_f32_e32 v64, v82, v252
	v_mov_b32_e32 v65, v64
	v_mov_b32_e32 v252, v64
	s_nop 1
	v_permlane32_swap_b32_e32 v65, v252
	v_cvt_pk_bf16_f32 v67, v70, v71
	v_cvt_pk_bf16_f32 v69, v76, v77
	global_store_dwordx4 v[80:81], v[72:75], off
	global_store_dwordx4 v[80:81], v[66:69], off offset:256
	s_and_saveexec_b64 s[10:11], s[40:41]
	s_cbranch_execz .LBB0_273
	s_waitcnt lgkmcnt(0)
	v_add_f32_e32 v66, v65, v252
	v_lshlrev_b64 v[64:65], 6, v[172:173]
	v_lshl_add_u64 v[64:65], s[6:7], 0, v[64:65]
	v_lshl_add_u64 v[64:65], s[30:31], 2, v[64:65]
	s_lshl_b32 s16, s58, 2
	v_lshl_add_u64 v[64:65], v[64:65], 0, s[16:17]
	global_store_dword v[64:65], v66, off
.LBB0_273:
	s_or_b64 exec, exec, s[10:11]
	v_add_u32_e32 v104, 0x80, v170
	v_ashrrev_i32_e32 v105, 31, v104
	v_lshlrev_b64 v[110:111], 11, v[104:105]
	s_waitcnt lgkmcnt(0)
	v_lshl_add_u64 v[64:65], v[168:169], 0, v[110:111]
	v_add_u32_e32 v100, 0x90, v170
	v_ashrrev_i32_e32 v101, 31, v100
	v_add_u32_e32 v96, 0xa0, v170
	v_lshlrev_b64 v[102:103], 11, v[100:101]
	v_ashrrev_i32_e32 v97, 31, v96
	v_add_u32_e32 v92, 0xb0, v170
	v_lshl_add_u64 v[64:65], v[168:169], 0, v[102:103]
	v_lshlrev_b64 v[98:99], 11, v[96:97]
	v_ashrrev_i32_e32 v93, 31, v92
	v_lshl_add_u64 v[64:65], v[168:169], 0, v[98:99]
	v_lshlrev_b64 v[94:95], 11, v[92:93]
	v_lshl_add_u64 v[64:65], v[168:169], 0, v[94:95]
	s_nop 0
	v_lshl_add_u64 v[110:111], s[18:19], 0, v[110:111]
	v_lshl_add_u64 v[110:111], v[166:167], 1, v[110:111]
	v_lshlrev_b32_e32 v112, 16, v212
	v_and_b32_e32 v113, 0xffff0000, v212
	v_lshlrev_b32_e32 v106, 16, v213
	v_and_b32_e32 v107, 0xffff0000, v213
	v_lshlrev_b32_e32 v114, 16, v214
	v_and_b32_e32 v115, 0xffff0000, v214
	v_lshlrev_b32_e32 v108, 16, v215
	v_and_b32_e32 v109, 0xffff0000, v215
	v_pk_add_f32 v[62:63], v[62:63], v[106:107]
	v_pk_add_f32 v[60:61], v[60:61], v[112:113]
	v_pk_add_f32 v[106:107], v[58:59], v[108:109]
	v_pk_add_f32 v[108:109], v[56:57], v[114:115]
	v_cvt_pk_bf16_f32 v56, v60, v61
	v_cvt_pk_bf16_f32 v57, v62, v63
	v_cvt_pk_bf16_f32 v58, v108, v109
	v_cvt_pk_bf16_f32 v59, v106, v107
	global_store_dwordx4 v[110:111], v[56:59], off
	s_nop 1
	v_mul_f32_e32 v56, v61, v61
	v_mul_f32_e32 v57, v63, v63
	v_fmac_f32_e32 v56, v60, v60
	v_fmac_f32_e32 v57, v62, v62
	v_add_f32_e32 v56, v56, v57
	v_mul_f32_e32 v57, v109, v109
	v_mul_f32_e32 v58, v107, v107
	v_fmac_f32_e32 v57, v108, v108
	v_fmac_f32_e32 v58, v106, v106
	v_add_f32_e32 v57, v57, v58
	v_add_f32_e32 v106, v56, v57
	v_lshlrev_b32_e32 v56, 16, v222
	v_and_b32_e32 v57, 0xffff0000, v222
	v_lshlrev_b32_e32 v58, 16, v223
	v_and_b32_e32 v59, 0xffff0000, v223
	v_lshlrev_b32_e32 v60, 16, v224
	v_and_b32_e32 v61, 0xffff0000, v224
	v_lshlrev_b32_e32 v62, 16, v225
	v_and_b32_e32 v63, 0xffff0000, v225
	v_pk_add_f32 v[54:55], v[54:55], v[58:59]
	v_pk_add_f32 v[52:53], v[52:53], v[56:57]
	v_pk_add_f32 v[56:57], v[50:51], v[62:63]
	v_pk_add_f32 v[58:59], v[48:49], v[60:61]
	v_cvt_pk_bf16_f32 v48, v52, v53
	v_cvt_pk_bf16_f32 v49, v54, v55
	v_cvt_pk_bf16_f32 v50, v58, v59
	v_cvt_pk_bf16_f32 v51, v56, v57
	global_store_dwordx4 v[110:111], v[48:51], off offset:256
	s_nop 1
	v_mul_f32_e32 v48, v53, v53
	v_mul_f32_e32 v49, v55, v55
	v_fmac_f32_e32 v48, v52, v52
	v_fmac_f32_e32 v49, v54, v54
	v_add_f32_e32 v48, v48, v49
	v_mul_f32_e32 v49, v59, v59
	v_mul_f32_e32 v50, v57, v57
	v_fmac_f32_e32 v49, v58, v58
	v_fmac_f32_e32 v50, v56, v56
	v_add_f32_e32 v49, v49, v50
	v_add_f32_e32 v48, v48, v49
	v_add_f32_e32 v48, v106, v48
	v_mov_b32_e32 v49, v48
	v_mov_b32_e32 v252, v48
	s_nop 1
	v_permlane16_swap_b32_e32 v49, v252
	s_waitcnt lgkmcnt(0)
	v_add_f32_e32 v48, v49, v252
	v_mov_b32_e32 v49, v48
	v_mov_b32_e32 v252, v48
	s_nop 1
	v_permlane32_swap_b32_e32 v49, v252
	s_and_saveexec_b64 s[10:11], s[40:41]
	s_cbranch_execz .LBB0_275
	s_waitcnt lgkmcnt(0)
	v_add_f32_e32 v50, v49, v252
	v_lshlrev_b64 v[48:49], 6, v[104:105]
	v_lshl_add_u64 v[48:49], s[6:7], 0, v[48:49]
	v_lshl_add_u64 v[48:49], s[30:31], 2, v[48:49]
	s_lshl_b32 s16, s58, 2
	v_lshl_add_u64 v[48:49], v[48:49], 0, s[16:17]
	global_store_dword v[48:49], v50, off
.LBB0_275:
	s_or_b64 exec, exec, s[10:11]
	v_lshlrev_b32_e32 v48, 16, v226
	s_waitcnt lgkmcnt(0)
	v_and_b32_e32 v49, 0xffff0000, v226
	v_lshlrev_b32_e32 v50, 16, v227
	v_and_b32_e32 v51, 0xffff0000, v227
	v_lshlrev_b32_e32 v52, 16, v228
	v_and_b32_e32 v53, 0xffff0000, v228
	v_pk_add_f32 v[44:45], v[44:45], v[48:49]
	v_pk_add_f32 v[46:47], v[46:47], v[50:51]
	v_pk_add_f32 v[50:51], v[40:41], v[52:53]
	v_cvt_pk_bf16_f32 v40, v44, v45
	v_mul_f32_e32 v45, v45, v45
	v_lshlrev_b32_e32 v54, 16, v229
	v_and_b32_e32 v55, 0xffff0000, v229
	v_fmac_f32_e32 v45, v44, v44
	v_mul_f32_e32 v44, v47, v47
	v_pk_add_f32 v[48:49], v[42:43], v[54:55]
	v_fmac_f32_e32 v44, v46, v46
	v_cvt_pk_bf16_f32 v41, v46, v47
	v_add_f32_e32 v44, v45, v44
	v_mul_f32_e32 v45, v51, v51
	v_mul_f32_e32 v46, v49, v49
	v_fmac_f32_e32 v45, v50, v50
	v_fmac_f32_e32 v46, v48, v48
	v_add_f32_e32 v45, v45, v46
	v_add_f32_e32 v52, v44, v45
	v_lshlrev_b32_e32 v44, 16, v230
	v_and_b32_e32 v45, 0xffff0000, v230
	v_lshlrev_b32_e32 v46, 16, v231
	v_and_b32_e32 v47, 0xffff0000, v231
	v_cvt_pk_bf16_f32 v43, v48, v49
	v_lshlrev_b32_e32 v48, 16, v232
	v_and_b32_e32 v49, 0xffff0000, v232
	v_pk_add_f32 v[38:39], v[38:39], v[46:47]
	v_pk_add_f32 v[36:37], v[36:37], v[44:45]
	v_cvt_pk_bf16_f32 v42, v50, v51
	v_lshlrev_b32_e32 v50, 16, v233
	v_and_b32_e32 v51, 0xffff0000, v233
	v_pk_add_f32 v[46:47], v[32:33], v[48:49]
	v_mul_f32_e32 v32, v37, v37
	v_mul_f32_e32 v33, v39, v39
	v_pk_add_f32 v[44:45], v[34:35], v[50:51]
	v_fmac_f32_e32 v32, v36, v36
	v_fmac_f32_e32 v33, v38, v38
	v_add_f32_e32 v32, v32, v33
	v_mul_f32_e32 v33, v47, v47
	v_mul_f32_e32 v34, v45, v45
	v_fmac_f32_e32 v33, v46, v46
	v_fmac_f32_e32 v34, v44, v44
	v_add_f32_e32 v33, v33, v34
	v_add_f32_e32 v32, v32, v33
	v_add_f32_e32 v35, v52, v32
	v_mov_b32_e32 v50, v35
	v_mov_b32_e32 v252, v35
	s_nop 1
	v_permlane16_swap_b32_e32 v50, v252
	v_lshl_add_u64 v[32:33], s[18:19], 0, v[102:103]
	v_lshl_add_u64 v[48:49], v[166:167], 1, v[32:33]
	v_cvt_pk_bf16_f32 v34, v36, v37
	v_cvt_pk_bf16_f32 v36, v46, v47
	s_waitcnt lgkmcnt(0)
	v_add_f32_e32 v32, v50, v252
	v_mov_b32_e32 v33, v32
	v_mov_b32_e32 v252, v32
	s_nop 1
	v_permlane32_swap_b32_e32 v33, v252
	v_cvt_pk_bf16_f32 v35, v38, v39
	v_cvt_pk_bf16_f32 v37, v44, v45
	global_store_dwordx4 v[48:49], v[40:43], off
	global_store_dwordx4 v[48:49], v[34:37], off offset:256
	s_and_saveexec_b64 s[10:11], s[40:41]
	s_cbranch_execz .LBB0_277
	s_waitcnt lgkmcnt(0)
	v_add_f32_e32 v34, v33, v252
	v_lshlrev_b64 v[32:33], 6, v[100:101]
	v_lshl_add_u64 v[32:33], s[6:7], 0, v[32:33]
	v_lshl_add_u64 v[32:33], s[30:31], 2, v[32:33]
	s_lshl_b32 s16, s58, 2
	v_lshl_add_u64 v[32:33], v[32:33], 0, s[16:17]
	global_store_dword v[32:33], v34, off
.LBB0_277:
	s_or_b64 exec, exec, s[10:11]
	v_lshlrev_b32_e32 v32, 16, v234
	s_waitcnt lgkmcnt(0)
	v_and_b32_e32 v33, 0xffff0000, v234
	v_lshlrev_b32_e32 v34, 16, v235
	v_and_b32_e32 v35, 0xffff0000, v235
	v_lshlrev_b32_e32 v36, 16, v236
	v_and_b32_e32 v37, 0xffff0000, v236
	v_pk_add_f32 v[28:29], v[28:29], v[32:33]
	v_pk_add_f32 v[30:31], v[30:31], v[34:35]
	v_pk_add_f32 v[34:35], v[24:25], v[36:37]
	v_cvt_pk_bf16_f32 v24, v28, v29
	v_mul_f32_e32 v29, v29, v29
	v_lshlrev_b32_e32 v38, 16, v237
	v_and_b32_e32 v39, 0xffff0000, v237
	v_fmac_f32_e32 v29, v28, v28
	v_mul_f32_e32 v28, v31, v31
	v_pk_add_f32 v[32:33], v[26:27], v[38:39]
	v_fmac_f32_e32 v28, v30, v30
	v_cvt_pk_bf16_f32 v25, v30, v31
	v_add_f32_e32 v28, v29, v28
	v_mul_f32_e32 v29, v35, v35
	v_mul_f32_e32 v30, v33, v33
	v_fmac_f32_e32 v29, v34, v34
	v_fmac_f32_e32 v30, v32, v32
	v_add_f32_e32 v29, v29, v30
	v_add_f32_e32 v36, v28, v29
	v_lshlrev_b32_e32 v28, 16, v238
	v_and_b32_e32 v29, 0xffff0000, v238
	v_lshlrev_b32_e32 v30, 16, v239
	v_and_b32_e32 v31, 0xffff0000, v239
	v_cvt_pk_bf16_f32 v27, v32, v33
	v_lshlrev_b32_e32 v32, 16, v240
	v_and_b32_e32 v33, 0xffff0000, v240
	v_pk_add_f32 v[22:23], v[22:23], v[30:31]
	v_pk_add_f32 v[20:21], v[20:21], v[28:29]
	v_cvt_pk_bf16_f32 v26, v34, v35
	v_lshlrev_b32_e32 v34, 16, v241
	v_and_b32_e32 v35, 0xffff0000, v241
	v_pk_add_f32 v[30:31], v[16:17], v[32:33]
	v_mul_f32_e32 v16, v21, v21
	v_mul_f32_e32 v17, v23, v23
	v_pk_add_f32 v[28:29], v[18:19], v[34:35]
	v_fmac_f32_e32 v16, v20, v20
	v_fmac_f32_e32 v17, v22, v22
	v_add_f32_e32 v16, v16, v17
	v_mul_f32_e32 v17, v31, v31
	v_mul_f32_e32 v18, v29, v29
	v_fmac_f32_e32 v17, v30, v30
	v_fmac_f32_e32 v18, v28, v28
	v_add_f32_e32 v17, v17, v18
	v_add_f32_e32 v16, v16, v17
	v_add_f32_e32 v19, v36, v16
	v_mov_b32_e32 v34, v19
	v_mov_b32_e32 v252, v19
	s_nop 1
	v_permlane16_swap_b32_e32 v34, v252
	v_lshl_add_u64 v[16:17], s[18:19], 0, v[98:99]
	v_lshl_add_u64 v[32:33], v[166:167], 1, v[16:17]
	v_cvt_pk_bf16_f32 v18, v20, v21
	v_cvt_pk_bf16_f32 v20, v30, v31
	s_waitcnt lgkmcnt(0)
	v_add_f32_e32 v16, v34, v252
	v_mov_b32_e32 v17, v16
	v_mov_b32_e32 v252, v16
	s_nop 1
	v_permlane32_swap_b32_e32 v17, v252
	v_cvt_pk_bf16_f32 v19, v22, v23
	v_cvt_pk_bf16_f32 v21, v28, v29
	global_store_dwordx4 v[32:33], v[24:27], off
	global_store_dwordx4 v[32:33], v[18:21], off offset:256
	s_and_saveexec_b64 s[10:11], s[40:41]
	s_cbranch_execz .LBB0_279
	s_waitcnt lgkmcnt(0)
	v_add_f32_e32 v18, v17, v252
	v_lshlrev_b64 v[16:17], 6, v[96:97]
	v_lshl_add_u64 v[16:17], s[6:7], 0, v[16:17]
	v_lshl_add_u64 v[16:17], s[30:31], 2, v[16:17]
	s_lshl_b32 s16, s58, 2
	v_lshl_add_u64 v[16:17], v[16:17], 0, s[16:17]
	global_store_dword v[16:17], v18, off
.LBB0_279:
	s_or_b64 exec, exec, s[10:11]
	v_lshlrev_b32_e32 v16, 16, v242
	s_waitcnt lgkmcnt(0)
	v_and_b32_e32 v17, 0xffff0000, v242
	v_lshlrev_b32_e32 v18, 16, v243
	v_and_b32_e32 v19, 0xffff0000, v243
	v_lshlrev_b32_e32 v20, 16, v244
	v_and_b32_e32 v21, 0xffff0000, v244
	v_pk_add_f32 v[12:13], v[12:13], v[16:17]
	v_pk_add_f32 v[14:15], v[14:15], v[18:19]
	v_pk_add_f32 v[18:19], v[8:9], v[20:21]
	v_cvt_pk_bf16_f32 v8, v12, v13
	v_mul_f32_e32 v13, v13, v13
	v_lshlrev_b32_e32 v22, 16, v245
	v_and_b32_e32 v23, 0xffff0000, v245
	v_fmac_f32_e32 v13, v12, v12
	v_mul_f32_e32 v12, v15, v15
	v_pk_add_f32 v[16:17], v[10:11], v[22:23]
	v_fmac_f32_e32 v12, v14, v14
	v_cvt_pk_bf16_f32 v9, v14, v15
	v_add_f32_e32 v12, v13, v12
	v_mul_f32_e32 v13, v19, v19
	v_mul_f32_e32 v14, v17, v17
	v_fmac_f32_e32 v13, v18, v18
	v_fmac_f32_e32 v14, v16, v16
	v_add_f32_e32 v13, v13, v14
	v_add_f32_e32 v20, v12, v13
	v_lshlrev_b32_e32 v12, 16, v246
	v_and_b32_e32 v13, 0xffff0000, v246
	v_lshlrev_b32_e32 v14, 16, v247
	v_and_b32_e32 v15, 0xffff0000, v247
	v_cvt_pk_bf16_f32 v11, v16, v17
	v_lshlrev_b32_e32 v16, 16, v248
	v_and_b32_e32 v17, 0xffff0000, v248
	v_pk_add_f32 v[6:7], v[6:7], v[14:15]
	v_pk_add_f32 v[4:5], v[4:5], v[12:13]
	v_cvt_pk_bf16_f32 v10, v18, v19
	v_lshlrev_b32_e32 v18, 16, v249
	v_and_b32_e32 v19, 0xffff0000, v249
	v_pk_add_f32 v[14:15], v[0:1], v[16:17]
	v_mul_f32_e32 v0, v5, v5
	v_mul_f32_e32 v1, v7, v7
	v_pk_add_f32 v[12:13], v[2:3], v[18:19]
	v_fmac_f32_e32 v0, v4, v4
	v_fmac_f32_e32 v1, v6, v6
	v_add_f32_e32 v0, v0, v1
	v_mul_f32_e32 v1, v15, v15
	v_mul_f32_e32 v2, v13, v13
	v_fmac_f32_e32 v1, v14, v14
	v_fmac_f32_e32 v2, v12, v12
	v_add_f32_e32 v1, v1, v2
	v_add_f32_e32 v0, v0, v1
	v_add_f32_e32 v3, v20, v0
	v_mov_b32_e32 v18, v3
	v_mov_b32_e32 v252, v3
	s_nop 1
	v_permlane16_swap_b32_e32 v18, v252
	v_lshl_add_u64 v[0:1], s[18:19], 0, v[94:95]
	v_lshl_add_u64 v[16:17], v[166:167], 1, v[0:1]
	v_cvt_pk_bf16_f32 v2, v4, v5
	v_cvt_pk_bf16_f32 v4, v14, v15
	s_waitcnt lgkmcnt(0)
	v_add_f32_e32 v0, v18, v252
	v_mov_b32_e32 v1, v0
	v_mov_b32_e32 v252, v0
	s_nop 1
	v_permlane32_swap_b32_e32 v1, v252
	v_cvt_pk_bf16_f32 v3, v6, v7
	v_cvt_pk_bf16_f32 v5, v12, v13
	global_store_dwordx4 v[16:17], v[8:11], off
	global_store_dwordx4 v[16:17], v[2:5], off offset:256
	s_and_saveexec_b64 s[10:11], s[40:41]
	s_cbranch_execz .LBB0_281
	s_waitcnt lgkmcnt(0)
	v_add_f32_e32 v2, v1, v252
	v_lshlrev_b64 v[0:1], 6, v[92:93]
	v_lshl_add_u64 v[0:1], s[6:7], 0, v[0:1]
	v_lshl_add_u64 v[0:1], s[30:31], 2, v[0:1]
	s_lshl_b32 s16, s58, 2
	v_lshl_add_u64 v[0:1], v[0:1], 0, s[16:17]
	global_store_dword v[0:1], v2, off

.LBB0_308:
	v_lshl_add_u32 v156, s16, 8, v162
	v_lshl_or_b32 v154, s66, 8, v164
	v_readlane_b32 s76, v253, 0
	v_ashrrev_i32_e32 v155, 31, v154
	v_readlane_b32 s77, v253, 1
	v_ashrrev_i32_e32 v157, 31, v156
	v_lshlrev_b64 v[128:129], 12, v[156:157]
	v_lshl_add_u64 v[158:159], v[154:155], 2, s[76:77]
	v_lshl_add_u64 v[128:129], v[158:159], 0, v[128:129]
	global_load_dwordx4 v[168:171], v[128:129], off
	global_load_dwordx4 v[172:175], v[128:129], off offset:16
	global_load_dwordx4 v[186:189], v[128:129], off offset:512
	global_load_dwordx4 v[190:193], v[128:129], off offset:528
	v_or_b32_e32 v160, 16, v156
	v_ashrrev_i32_e32 v161, 31, v160
	v_lshlrev_b64 v[128:129], 12, v[160:161]
	v_lshl_add_u64 v[132:133], v[158:159], 0, v[128:129]
	global_load_dwordx4 v[136:139], v[132:133], off offset:16
	global_load_dwordx4 v[140:143], v[132:133], off
	global_load_dwordx4 v[128:131], v[132:133], off offset:528
	s_nop 0
	global_load_dwordx4 v[132:135], v[132:133], off offset:512
	v_and_b32_e32 v167, 64, v219
	v_xor_b32_e32 v166, 16, v219
	v_add_u32_e32 v167, 64, v167
	v_cmp_lt_i32_e32 vcc, v166, v167
	v_xor_b32_e32 v194, 32, v219
	v_readlane_b32 s78, v253, 2
	v_cndmask_b32_e32 v166, v219, v166, vcc
	v_cmp_lt_i32_e32 vcc, v194, v167
	v_lshlrev_b32_e32 v167, 2, v166
	v_readlane_b32 s79, v253, 3
	v_cndmask_b32_e32 v196, v219, v194, vcc
	v_lshlrev_b64 v[194:195], 11, v[156:157]
	v_lshlrev_b32_e32 v166, 2, v196
	v_readlane_b32 s80, v253, 4
	v_readlane_b32 s81, v253, 5
	v_readlane_b32 s82, v253, 6
	v_readlane_b32 s83, v253, 7
	v_readlane_b32 s84, v253, 8
	v_readlane_b32 s85, v253, 9
	v_readlane_b32 s86, v253, 10
	v_readlane_b32 s87, v253, 11
	v_readlane_b32 s88, v253, 12
	v_readlane_b32 s89, v253, 13
	v_readlane_b32 s90, v253, 14
	v_readlane_b32 s91, v253, 15
	s_waitcnt vmcnt(0)
	v_pk_add_f32 v[126:127], v[126:127], v[170:171]
	v_pk_add_f32 v[124:125], v[124:125], v[168:169]
	v_pk_add_f32 v[122:123], v[122:123], v[174:175]
	v_pk_add_f32 v[120:121], v[120:121], v[172:173]
	v_pk_add_f32 v[118:119], v[118:119], v[188:189]
	v_pk_add_f32 v[116:117], v[116:117], v[186:187]
	v_pk_add_f32 v[168:169], v[114:115], v[192:193]
	v_pk_add_f32 v[170:171], v[112:113], v[190:191]
	v_cvt_pk_bf16_f32 v112, v124, v125
	v_cvt_pk_bf16_f32 v113, v126, v127
	v_cvt_pk_bf16_f32 v114, v120, v121
	v_cvt_pk_bf16_f32 v115, v122, v123
	v_mul_f32_e32 v125, v125, v125
	v_mul_f32_e32 v127, v127, v127
	v_mul_f32_e32 v121, v121, v121
	v_mul_f32_e32 v123, v123, v123
	v_mul_f32_e32 v172, v117, v117
	v_mul_f32_e32 v173, v119, v119
	v_mul_f32_e32 v174, v171, v171
	v_mul_f32_e32 v175, v169, v169
	v_fmac_f32_e32 v125, v124, v124
	v_fmac_f32_e32 v127, v126, v126
	v_fmac_f32_e32 v121, v120, v120
	v_fmac_f32_e32 v123, v122, v122
	v_fmac_f32_e32 v172, v116, v116
	v_fmac_f32_e32 v173, v118, v118
	v_fmac_f32_e32 v174, v170, v170
	v_fmac_f32_e32 v175, v168, v168
	v_add_f32_e32 v120, v125, v127
	v_add_f32_e32 v121, v121, v123
	v_add_f32_e32 v122, v172, v173
	v_add_f32_e32 v123, v174, v175
	v_add_f32_e32 v120, v120, v121
	v_add_f32_e32 v121, v122, v123
	v_add_f32_e32 v122, v120, v121
	v_mov_b32_e32 v123, v122
	v_mov_b32_e32 v252, v122
	s_nop 1
	v_permlane16_swap_b32_e32 v123, v252
	v_lshl_add_u64 v[120:121], s[18:19], 0, v[194:195]
	v_lshl_add_u64 v[120:121], v[154:155], 1, v[120:121]
	global_store_dwordx4 v[120:121], v[112:115], off
	s_waitcnt lgkmcnt(0)
	s_nop 0
	v_add_f32_e32 v112, v123, v252
	v_mov_b32_e32 v113, v112
	v_mov_b32_e32 v252, v112
	s_nop 1
	v_permlane32_swap_b32_e32 v113, v252
	v_cvt_pk_bf16_f32 v114, v116, v117
	v_cvt_pk_bf16_f32 v115, v118, v119
	v_cvt_pk_bf16_f32 v116, v170, v171
	v_cvt_pk_bf16_f32 v117, v168, v169
	global_store_dwordx4 v[120:121], v[114:117], off offset:256
	s_and_saveexec_b64 s[10:11], s[40:41]
	s_cbranch_execz .LBB0_310
	s_waitcnt lgkmcnt(0)
	v_add_f32_e32 v114, v113, v252
	s_lshl_b32 s4, s66, 2
	v_lshlrev_b64 v[112:113], 6, v[156:157]
	s_ashr_i32 s5, s4, 31
	v_lshl_add_u64 v[112:113], s[6:7], 0, v[112:113]
	v_lshl_add_u64 v[112:113], s[4:5], 2, v[112:113]
	s_lshl_b32 s16, s58, 2
	v_lshl_add_u64 v[112:113], v[112:113], 0, s[16:17]
	global_store_dword v[112:113], v114, off
.LBB0_310:
	s_or_b64 exec, exec, s[10:11]
	v_pk_add_f32 v[108:109], v[108:109], v[140:141]
	v_pk_add_f32 v[110:111], v[110:111], v[142:143]
	v_pk_add_f32 v[116:117], v[104:105], v[136:137]
	v_cvt_pk_bf16_f32 v104, v108, v109
	v_mul_f32_e32 v109, v109, v109
	v_fmac_f32_e32 v109, v108, v108
	v_mul_f32_e32 v108, v111, v111
	v_pk_add_f32 v[114:115], v[106:107], v[138:139]
	v_fmac_f32_e32 v108, v110, v110
	v_cvt_pk_bf16_f32 v105, v110, v111
	v_add_f32_e32 v108, v109, v108
	v_mul_f32_e32 v109, v117, v117
	v_mul_f32_e32 v110, v115, v115
	v_fmac_f32_e32 v109, v116, v116
	v_fmac_f32_e32 v110, v114, v114
	v_pk_add_f32 v[102:103], v[102:103], v[134:135]
	v_pk_add_f32 v[100:101], v[100:101], v[132:133]
	v_add_f32_e32 v109, v109, v110
	v_pk_add_f32 v[110:111], v[96:97], v[128:129]
	v_mul_f32_e32 v96, v101, v101
	v_mul_f32_e32 v97, v103, v103
	v_cvt_pk_bf16_f32 v107, v114, v115
	v_add_f32_e32 v114, v108, v109
	v_pk_add_f32 v[108:109], v[98:99], v[130:131]
	v_fmac_f32_e32 v96, v100, v100
	v_fmac_f32_e32 v97, v102, v102
	v_add_f32_e32 v96, v96, v97
	v_mul_f32_e32 v97, v111, v111
	v_mul_f32_e32 v98, v109, v109
	v_fmac_f32_e32 v97, v110, v110
	v_fmac_f32_e32 v98, v108, v108
	v_add_f32_e32 v97, v97, v98
	v_add_f32_e32 v96, v96, v97
	v_add_f32_e32 v99, v114, v96
	v_mov_b32_e32 v114, v99
	v_mov_b32_e32 v252, v99
	s_nop 1
	v_permlane16_swap_b32_e32 v114, v252
	s_waitcnt lgkmcnt(1)
	v_lshlrev_b64 v[112:113], 11, v[160:161]
	v_lshl_add_u64 v[96:97], s[18:19], 0, v[112:113]
	v_lshl_add_u64 v[112:113], v[154:155], 1, v[96:97]
	v_cvt_pk_bf16_f32 v106, v116, v117
	s_waitcnt lgkmcnt(0)
	v_add_f32_e32 v96, v114, v252
	v_mov_b32_e32 v97, v96
	v_mov_b32_e32 v252, v96
	s_nop 1
	v_permlane32_swap_b32_e32 v97, v252
	v_cvt_pk_bf16_f32 v98, v100, v101
	v_cvt_pk_bf16_f32 v99, v102, v103
	v_cvt_pk_bf16_f32 v100, v110, v111
	v_cvt_pk_bf16_f32 v101, v108, v109
	global_store_dwordx4 v[112:113], v[104:107], off
	global_store_dwordx4 v[112:113], v[98:101], off offset:256
	s_and_saveexec_b64 s[10:11], s[40:41]
	s_cbranch_execz .LBB0_312
	s_waitcnt lgkmcnt(0)
	v_add_f32_e32 v98, v97, v252
	s_lshl_b32 s4, s66, 2
	v_lshlrev_b64 v[96:97], 6, v[160:161]
	s_ashr_i32 s5, s4, 31
	v_lshl_add_u64 v[96:97], s[6:7], 0, v[96:97]
	v_lshl_add_u64 v[96:97], s[4:5], 2, v[96:97]
	s_lshl_b32 s16, s58, 2
	v_lshl_add_u64 v[96:97], v[96:97], 0, s[16:17]
	global_store_dword v[96:97], v98, off
.LBB0_312:
	s_or_b64 exec, exec, s[10:11]
	v_or_b32_e32 v114, 32, v156
	v_ashrrev_i32_e32 v115, 31, v114
	s_waitcnt lgkmcnt(0)
	v_lshlrev_b64 v[96:97], 12, v[114:115]
	v_lshl_add_u64 v[96:97], v[158:159], 0, v[96:97]
	global_load_dwordx4 v[116:119], v[96:97], off
	global_load_dwordx4 v[120:123], v[96:97], off offset:16
	global_load_dwordx4 v[124:127], v[96:97], off offset:512
	global_load_dwordx4 v[128:131], v[96:97], off offset:528
	v_or_b32_e32 v112, 48, v156
	v_ashrrev_i32_e32 v113, 31, v112
	v_lshlrev_b64 v[96:97], 12, v[112:113]
	v_lshl_add_u64 v[100:101], v[158:159], 0, v[96:97]
	global_load_dwordx4 v[104:107], v[100:101], off offset:16
	global_load_dwordx4 v[108:111], v[100:101], off
	global_load_dwordx4 v[96:99], v[100:101], off offset:528
	s_nop 0
	global_load_dwordx4 v[100:103], v[100:101], off offset:512
	v_lshlrev_b64 v[132:133], 11, v[114:115]
	s_waitcnt vmcnt(7)
	v_pk_add_f32 v[94:95], v[94:95], v[118:119]
	v_pk_add_f32 v[92:93], v[92:93], v[116:117]
	s_waitcnt vmcnt(6)
	v_pk_add_f32 v[90:91], v[90:91], v[122:123]
	v_pk_add_f32 v[88:89], v[88:89], v[120:121]
	s_waitcnt vmcnt(5)
	v_pk_add_f32 v[86:87], v[86:87], v[126:127]
	v_pk_add_f32 v[84:85], v[84:85], v[124:125]
	s_waitcnt vmcnt(4)
	v_pk_add_f32 v[116:117], v[82:83], v[130:131]
	v_pk_add_f32 v[118:119], v[80:81], v[128:129]
	v_cvt_pk_bf16_f32 v80, v92, v93
	v_cvt_pk_bf16_f32 v81, v94, v95
	v_cvt_pk_bf16_f32 v82, v88, v89
	v_cvt_pk_bf16_f32 v83, v90, v91
	v_mul_f32_e32 v93, v93, v93
	v_mul_f32_e32 v95, v95, v95
	v_mul_f32_e32 v89, v89, v89
	v_mul_f32_e32 v91, v91, v91
	v_mul_f32_e32 v120, v85, v85
	v_mul_f32_e32 v121, v87, v87
	v_mul_f32_e32 v122, v119, v119
	v_mul_f32_e32 v123, v117, v117
	v_fmac_f32_e32 v93, v92, v92
	v_fmac_f32_e32 v95, v94, v94
	v_fmac_f32_e32 v89, v88, v88
	v_fmac_f32_e32 v91, v90, v90
	v_fmac_f32_e32 v120, v84, v84
	v_fmac_f32_e32 v121, v86, v86
	v_fmac_f32_e32 v122, v118, v118
	v_fmac_f32_e32 v123, v116, v116
	v_add_f32_e32 v88, v93, v95
	v_add_f32_e32 v89, v89, v91
	v_add_f32_e32 v90, v120, v121
	v_add_f32_e32 v91, v122, v123
	v_add_f32_e32 v88, v88, v89
	v_add_f32_e32 v89, v90, v91
	v_add_f32_e32 v90, v88, v89
	v_mov_b32_e32 v91, v90
	v_mov_b32_e32 v252, v90
	s_nop 1
	v_permlane16_swap_b32_e32 v91, v252
	v_lshl_add_u64 v[88:89], s[18:19], 0, v[132:133]
	v_lshl_add_u64 v[88:89], v[154:155], 1, v[88:89]
	global_store_dwordx4 v[88:89], v[80:83], off
	s_waitcnt lgkmcnt(0)
	s_nop 0
	v_add_f32_e32 v80, v91, v252
	ds_bpermute_b32 v81, v166, v80
	v_cvt_pk_bf16_f32 v82, v84, v85
	v_cvt_pk_bf16_f32 v83, v86, v87
	v_cvt_pk_bf16_f32 v84, v118, v119
	v_cvt_pk_bf16_f32 v85, v116, v117
	global_store_dwordx4 v[88:89], v[82:85], off offset:256
	s_and_saveexec_b64 s[10:11], s[40:41]
	s_mov_b64 s[76:77], s[30:31]
	s_mov_b64 s[78:79], s[34:35]
	s_mov_b64 s[80:81], s[44:45]
	s_mov_b64 s[82:83], s[64:65]
	s_mov_b64 s[84:85], s[70:71]
	s_mov_b64 s[86:87], s[54:55]
	s_mov_b64 s[88:89], s[96:97]
	s_mov_b64 s[90:91], s[46:47]
	s_cbranch_execz .LBB0_314
	s_waitcnt lgkmcnt(0)
	v_add_f32_e32 v82, v80, v81
	s_lshl_b32 s4, s66, 2
	v_lshlrev_b64 v[80:81], 6, v[114:115]
	s_ashr_i32 s5, s4, 31
	v_lshl_add_u64 v[80:81], s[6:7], 0, v[80:81]
	v_lshl_add_u64 v[80:81], s[4:5], 2, v[80:81]
	s_lshl_b32 s16, s58, 2
	v_lshl_add_u64 v[80:81], v[80:81], 0, s[16:17]
	global_store_dword v[80:81], v82, off
.LBB0_314:
	s_or_b64 exec, exec, s[10:11]
	s_waitcnt vmcnt(4)
	v_pk_add_f32 v[76:77], v[76:77], v[108:109]
	v_pk_add_f32 v[78:79], v[78:79], v[110:111]
	v_pk_add_f32 v[84:85], v[72:73], v[104:105]
	v_cvt_pk_bf16_f32 v72, v76, v77
	v_mul_f32_e32 v77, v77, v77
	v_fmac_f32_e32 v77, v76, v76
	v_mul_f32_e32 v76, v79, v79
	v_pk_add_f32 v[82:83], v[74:75], v[106:107]
	v_fmac_f32_e32 v76, v78, v78
	v_cvt_pk_bf16_f32 v73, v78, v79
	v_add_f32_e32 v76, v77, v76
	v_mul_f32_e32 v77, v85, v85
	v_mul_f32_e32 v78, v83, v83
	v_fmac_f32_e32 v77, v84, v84
	v_fmac_f32_e32 v78, v82, v82
	s_waitcnt vmcnt(2)
	v_pk_add_f32 v[70:71], v[70:71], v[102:103]
	v_pk_add_f32 v[68:69], v[68:69], v[100:101]
	v_add_f32_e32 v77, v77, v78
	v_pk_add_f32 v[78:79], v[64:65], v[96:97]
	v_mul_f32_e32 v64, v69, v69
	v_mul_f32_e32 v65, v71, v71
	v_cvt_pk_bf16_f32 v75, v82, v83
	v_add_f32_e32 v82, v76, v77
	v_pk_add_f32 v[76:77], v[66:67], v[98:99]
	v_fmac_f32_e32 v64, v68, v68
	v_fmac_f32_e32 v65, v70, v70
	v_add_f32_e32 v64, v64, v65
	v_mul_f32_e32 v65, v79, v79
	v_mul_f32_e32 v66, v77, v77
	v_fmac_f32_e32 v65, v78, v78
	v_fmac_f32_e32 v66, v76, v76
	v_add_f32_e32 v65, v65, v66
	v_add_f32_e32 v64, v64, v65
	v_add_f32_e32 v67, v82, v64
	v_mov_b32_e32 v82, v67
	v_mov_b32_e32 v252, v67
	s_nop 1
	v_permlane16_swap_b32_e32 v82, v252
	s_waitcnt lgkmcnt(1)
	v_lshlrev_b64 v[80:81], 11, v[112:113]
	v_lshl_add_u64 v[64:65], s[18:19], 0, v[80:81]
	v_lshl_add_u64 v[80:81], v[154:155], 1, v[64:65]
	v_cvt_pk_bf16_f32 v74, v84, v85
	s_waitcnt lgkmcnt(0)
	v_add_f32_e32 v64, v82, v252
	v_mov_b32_e32 v65, v64
	v_mov_b32_e32 v252, v64
	s_nop 1
	v_permlane32_swap_b32_e32 v65, v252
	v_cvt_pk_bf16_f32 v66, v68, v69
	v_cvt_pk_bf16_f32 v67, v70, v71
	v_cvt_pk_bf16_f32 v68, v78, v79
	v_cvt_pk_bf16_f32 v69, v76, v77
	global_store_dwordx4 v[80:81], v[72:75], off
	global_store_dwordx4 v[80:81], v[66:69], off offset:256
	s_and_saveexec_b64 s[10:11], s[40:41]
	s_cbranch_execz .LBB0_316
	s_waitcnt lgkmcnt(0)
	v_add_f32_e32 v66, v65, v252
	s_lshl_b32 s4, s66, 2
	v_lshlrev_b64 v[64:65], 6, v[112:113]
	s_ashr_i32 s5, s4, 31
	v_lshl_add_u64 v[64:65], s[6:7], 0, v[64:65]
	v_lshl_add_u64 v[64:65], s[4:5], 2, v[64:65]
	s_lshl_b32 s16, s58, 2
	v_lshl_add_u64 v[64:65], v[64:65], 0, s[16:17]
	global_store_dword v[64:65], v66, off
.LBB0_316:
	s_or_b64 exec, exec, s[10:11]
	v_add_u32_e32 v82, 0x80, v156
	v_ashrrev_i32_e32 v83, 31, v82
	s_waitcnt lgkmcnt(0)
	v_lshlrev_b64 v[64:65], 12, v[82:83]
	v_lshl_add_u64 v[64:65], v[158:159], 0, v[64:65]
	global_load_dwordx4 v[84:87], v[64:65], off
	global_load_dwordx4 v[88:91], v[64:65], off offset:16
	global_load_dwordx4 v[92:95], v[64:65], off offset:512
	global_load_dwordx4 v[96:99], v[64:65], off offset:528
	v_add_u32_e32 v80, 0x90, v156
	v_ashrrev_i32_e32 v81, 31, v80
	v_lshlrev_b64 v[64:65], 12, v[80:81]
	v_lshl_add_u64 v[68:69], v[158:159], 0, v[64:65]
	global_load_dwordx4 v[72:75], v[68:69], off offset:16
	global_load_dwordx4 v[76:79], v[68:69], off
	global_load_dwordx4 v[64:67], v[68:69], off offset:528
	s_nop 0
	global_load_dwordx4 v[68:71], v[68:69], off offset:512
	v_lshlrev_b64 v[100:101], 11, v[82:83]
	s_waitcnt vmcnt(7)
	v_pk_add_f32 v[62:63], v[62:63], v[86:87]
	v_pk_add_f32 v[60:61], v[60:61], v[84:85]
	s_waitcnt vmcnt(6)
	v_pk_add_f32 v[58:59], v[58:59], v[90:91]
	v_pk_add_f32 v[56:57], v[56:57], v[88:89]
	s_waitcnt vmcnt(5)
	v_pk_add_f32 v[54:55], v[54:55], v[94:95]
	v_pk_add_f32 v[52:53], v[52:53], v[92:93]
	s_waitcnt vmcnt(4)
	v_pk_add_f32 v[84:85], v[50:51], v[98:99]
	v_pk_add_f32 v[86:87], v[48:49], v[96:97]
	v_cvt_pk_bf16_f32 v48, v60, v61
	v_cvt_pk_bf16_f32 v49, v62, v63
	v_cvt_pk_bf16_f32 v50, v56, v57
	v_cvt_pk_bf16_f32 v51, v58, v59
	v_mul_f32_e32 v61, v61, v61
	v_mul_f32_e32 v63, v63, v63
	v_mul_f32_e32 v57, v57, v57
	v_mul_f32_e32 v59, v59, v59
	v_mul_f32_e32 v88, v53, v53
	v_mul_f32_e32 v89, v55, v55
	v_mul_f32_e32 v90, v87, v87
	v_mul_f32_e32 v91, v85, v85
	v_fmac_f32_e32 v61, v60, v60
	v_fmac_f32_e32 v63, v62, v62
	v_fmac_f32_e32 v57, v56, v56
	v_fmac_f32_e32 v59, v58, v58
	v_fmac_f32_e32 v88, v52, v52
	v_fmac_f32_e32 v89, v54, v54
	v_fmac_f32_e32 v90, v86, v86
	v_fmac_f32_e32 v91, v84, v84
	v_add_f32_e32 v56, v61, v63
	v_add_f32_e32 v57, v57, v59
	v_add_f32_e32 v58, v88, v89
	v_add_f32_e32 v59, v90, v91
	v_add_f32_e32 v56, v56, v57
	v_add_f32_e32 v57, v58, v59
	v_add_f32_e32 v58, v56, v57
	v_mov_b32_e32 v59, v58
	v_mov_b32_e32 v252, v58
	s_nop 1
	v_permlane16_swap_b32_e32 v59, v252
	v_lshl_add_u64 v[56:57], s[18:19], 0, v[100:101]
	v_lshl_add_u64 v[56:57], v[154:155], 1, v[56:57]
	global_store_dwordx4 v[56:57], v[48:51], off
	s_waitcnt lgkmcnt(0)
	s_nop 0
	v_add_f32_e32 v48, v59, v252
	v_mov_b32_e32 v49, v48
	v_mov_b32_e32 v252, v48
	s_nop 1
	v_permlane32_swap_b32_e32 v49, v252
	v_cvt_pk_bf16_f32 v50, v52, v53
	v_cvt_pk_bf16_f32 v51, v54, v55
	v_cvt_pk_bf16_f32 v52, v86, v87
	v_cvt_pk_bf16_f32 v53, v84, v85
	global_store_dwordx4 v[56:57], v[50:53], off offset:256
	s_and_saveexec_b64 s[10:11], s[40:41]
	s_cbranch_execz .LBB0_318
	s_waitcnt lgkmcnt(0)
	v_add_f32_e32 v50, v49, v252
	s_lshl_b32 s4, s66, 2
	v_lshlrev_b64 v[48:49], 6, v[82:83]
	s_ashr_i32 s5, s4, 31
	v_lshl_add_u64 v[48:49], s[6:7], 0, v[48:49]
	v_lshl_add_u64 v[48:49], s[4:5], 2, v[48:49]
	s_lshl_b32 s16, s58, 2
	v_lshl_add_u64 v[48:49], v[48:49], 0, s[16:17]
	global_store_dword v[48:49], v50, off
.LBB0_318:
	s_or_b64 exec, exec, s[10:11]
	s_waitcnt vmcnt(4)
	v_pk_add_f32 v[44:45], v[44:45], v[76:77]
	v_pk_add_f32 v[46:47], v[46:47], v[78:79]
	v_pk_add_f32 v[52:53], v[40:41], v[72:73]
	v_cvt_pk_bf16_f32 v40, v44, v45
	v_mul_f32_e32 v45, v45, v45
	v_fmac_f32_e32 v45, v44, v44
	v_mul_f32_e32 v44, v47, v47
	v_pk_add_f32 v[50:51], v[42:43], v[74:75]
	v_fmac_f32_e32 v44, v46, v46
	v_cvt_pk_bf16_f32 v41, v46, v47
	v_add_f32_e32 v44, v45, v44
	v_mul_f32_e32 v45, v53, v53
	v_mul_f32_e32 v46, v51, v51
	v_fmac_f32_e32 v45, v52, v52
	v_fmac_f32_e32 v46, v50, v50
	s_waitcnt vmcnt(2)
	v_pk_add_f32 v[38:39], v[38:39], v[70:71]
	v_pk_add_f32 v[36:37], v[36:37], v[68:69]
	v_add_f32_e32 v45, v45, v46
	v_pk_add_f32 v[46:47], v[32:33], v[64:65]
	v_mul_f32_e32 v32, v37, v37
	v_mul_f32_e32 v33, v39, v39
	v_cvt_pk_bf16_f32 v43, v50, v51
	v_add_f32_e32 v50, v44, v45
	v_pk_add_f32 v[44:45], v[34:35], v[66:67]
	v_fmac_f32_e32 v32, v36, v36
	v_fmac_f32_e32 v33, v38, v38
	v_add_f32_e32 v32, v32, v33
	v_mul_f32_e32 v33, v47, v47
	v_mul_f32_e32 v34, v45, v45
	v_fmac_f32_e32 v33, v46, v46
	v_fmac_f32_e32 v34, v44, v44
	v_add_f32_e32 v33, v33, v34
	v_add_f32_e32 v32, v32, v33
	v_add_f32_e32 v35, v50, v32
	v_mov_b32_e32 v50, v35
	v_mov_b32_e32 v252, v35
	s_nop 1
	v_permlane16_swap_b32_e32 v50, v252
	s_waitcnt lgkmcnt(1)
	v_lshlrev_b64 v[48:49], 11, v[80:81]
	v_lshl_add_u64 v[32:33], s[18:19], 0, v[48:49]
	v_lshl_add_u64 v[48:49], v[154:155], 1, v[32:33]
	v_cvt_pk_bf16_f32 v42, v52, v53
	s_waitcnt lgkmcnt(0)
	v_add_f32_e32 v32, v50, v252
	v_mov_b32_e32 v33, v32
	v_mov_b32_e32 v252, v32
	s_nop 1
	v_permlane32_swap_b32_e32 v33, v252
	v_cvt_pk_bf16_f32 v34, v36, v37
	v_cvt_pk_bf16_f32 v35, v38, v39
	v_cvt_pk_bf16_f32 v36, v46, v47
	v_cvt_pk_bf16_f32 v37, v44, v45
	global_store_dwordx4 v[48:49], v[40:43], off
	global_store_dwordx4 v[48:49], v[34:37], off offset:256
	s_and_saveexec_b64 s[10:11], s[40:41]
	s_cbranch_execz .LBB0_320
	s_waitcnt lgkmcnt(0)
	v_add_f32_e32 v34, v33, v252
	s_lshl_b32 s4, s66, 2
	v_lshlrev_b64 v[32:33], 6, v[80:81]
	s_ashr_i32 s5, s4, 31
	v_lshl_add_u64 v[32:33], s[6:7], 0, v[32:33]
	v_lshl_add_u64 v[32:33], s[4:5], 2, v[32:33]
	s_lshl_b32 s16, s58, 2
	v_lshl_add_u64 v[32:33], v[32:33], 0, s[16:17]
	global_store_dword v[32:33], v34, off
.LBB0_320:
	s_or_b64 exec, exec, s[10:11]
	v_add_u32_e32 v50, 0xa0, v156
	v_ashrrev_i32_e32 v51, 31, v50
	s_waitcnt lgkmcnt(0)
	v_lshlrev_b64 v[32:33], 12, v[50:51]
	v_lshl_add_u64 v[32:33], v[158:159], 0, v[32:33]
	global_load_dwordx4 v[52:55], v[32:33], off
	global_load_dwordx4 v[56:59], v[32:33], off offset:16
	global_load_dwordx4 v[60:63], v[32:33], off offset:512
	global_load_dwordx4 v[64:67], v[32:33], off offset:528
	v_add_u32_e32 v48, 0xb0, v156
	v_ashrrev_i32_e32 v49, 31, v48
	v_lshlrev_b64 v[32:33], 12, v[48:49]
	v_lshl_add_u64 v[36:37], v[158:159], 0, v[32:33]
	global_load_dwordx4 v[40:43], v[36:37], off offset:16
	global_load_dwordx4 v[44:47], v[36:37], off
	global_load_dwordx4 v[32:35], v[36:37], off offset:528
	s_nop 0
	global_load_dwordx4 v[36:39], v[36:37], off offset:512
	v_lshlrev_b64 v[68:69], 11, v[50:51]
	s_waitcnt vmcnt(7)
	v_pk_add_f32 v[30:31], v[30:31], v[54:55]
	v_pk_add_f32 v[28:29], v[28:29], v[52:53]
	s_waitcnt vmcnt(6)
	v_pk_add_f32 v[26:27], v[26:27], v[58:59]
	v_pk_add_f32 v[24:25], v[24:25], v[56:57]
	s_waitcnt vmcnt(5)
	v_pk_add_f32 v[22:23], v[22:23], v[62:63]
	v_pk_add_f32 v[20:21], v[20:21], v[60:61]
	s_waitcnt vmcnt(4)
	v_pk_add_f32 v[52:53], v[18:19], v[66:67]
	v_pk_add_f32 v[54:55], v[16:17], v[64:65]
	v_cvt_pk_bf16_f32 v16, v28, v29
	v_cvt_pk_bf16_f32 v17, v30, v31
	v_cvt_pk_bf16_f32 v18, v24, v25
	v_cvt_pk_bf16_f32 v19, v26, v27
	v_mul_f32_e32 v29, v29, v29
	v_mul_f32_e32 v31, v31, v31
	v_mul_f32_e32 v25, v25, v25
	v_mul_f32_e32 v27, v27, v27
	v_mul_f32_e32 v56, v21, v21
	v_mul_f32_e32 v57, v23, v23
	v_mul_f32_e32 v58, v55, v55
	v_mul_f32_e32 v59, v53, v53
	v_fmac_f32_e32 v29, v28, v28
	v_fmac_f32_e32 v31, v30, v30
	v_fmac_f32_e32 v25, v24, v24
	v_fmac_f32_e32 v27, v26, v26
	v_fmac_f32_e32 v56, v20, v20
	v_fmac_f32_e32 v57, v22, v22
	v_fmac_f32_e32 v58, v54, v54
	v_fmac_f32_e32 v59, v52, v52
	v_add_f32_e32 v24, v29, v31
	v_add_f32_e32 v25, v25, v27
	v_add_f32_e32 v26, v56, v57
	v_add_f32_e32 v27, v58, v59
	v_add_f32_e32 v24, v24, v25
	v_add_f32_e32 v25, v26, v27
	v_add_f32_e32 v26, v24, v25
	v_mov_b32_e32 v27, v26
	v_mov_b32_e32 v252, v26
	s_nop 1
	v_permlane16_swap_b32_e32 v27, v252
	v_lshl_add_u64 v[24:25], s[18:19], 0, v[68:69]
	v_lshl_add_u64 v[24:25], v[154:155], 1, v[24:25]
	global_store_dwordx4 v[24:25], v[16:19], off
	s_waitcnt lgkmcnt(0)
	s_nop 0
	v_add_f32_e32 v16, v27, v252
	v_mov_b32_e32 v17, v16
	v_mov_b32_e32 v252, v16
	s_nop 1
	v_permlane32_swap_b32_e32 v17, v252
	v_cvt_pk_bf16_f32 v18, v20, v21
	v_cvt_pk_bf16_f32 v19, v22, v23
	v_cvt_pk_bf16_f32 v20, v54, v55
	v_cvt_pk_bf16_f32 v21, v52, v53
	global_store_dwordx4 v[24:25], v[18:21], off offset:256
	s_and_saveexec_b64 s[10:11], s[40:41]
	s_cbranch_execz .LBB0_322
	s_waitcnt lgkmcnt(0)
	v_add_f32_e32 v18, v17, v252
	s_lshl_b32 s4, s66, 2
	v_lshlrev_b64 v[16:17], 6, v[50:51]
	s_ashr_i32 s5, s4, 31
	v_lshl_add_u64 v[16:17], s[6:7], 0, v[16:17]
	v_lshl_add_u64 v[16:17], s[4:5], 2, v[16:17]
	s_lshl_b32 s16, s58, 2
	v_lshl_add_u64 v[16:17], v[16:17], 0, s[16:17]
	global_store_dword v[16:17], v18, off
.LBB0_322:
	s_or_b64 exec, exec, s[10:11]
	s_waitcnt vmcnt(4)
	v_pk_add_f32 v[12:13], v[12:13], v[44:45]
	v_pk_add_f32 v[14:15], v[14:15], v[46:47]
	v_pk_add_f32 v[20:21], v[8:9], v[40:41]
	v_cvt_pk_bf16_f32 v8, v12, v13
	v_mul_f32_e32 v13, v13, v13
	v_fmac_f32_e32 v13, v12, v12
	v_mul_f32_e32 v12, v15, v15
	v_pk_add_f32 v[18:19], v[10:11], v[42:43]
	v_fmac_f32_e32 v12, v14, v14
	v_cvt_pk_bf16_f32 v9, v14, v15
	v_add_f32_e32 v12, v13, v12
	v_mul_f32_e32 v13, v21, v21
	v_mul_f32_e32 v14, v19, v19
	v_fmac_f32_e32 v13, v20, v20
	v_fmac_f32_e32 v14, v18, v18
	s_waitcnt vmcnt(2)
	v_pk_add_f32 v[6:7], v[6:7], v[38:39]
	v_pk_add_f32 v[4:5], v[4:5], v[36:37]
	v_add_f32_e32 v13, v13, v14
	v_pk_add_f32 v[14:15], v[0:1], v[32:33]
	v_mul_f32_e32 v0, v5, v5
	v_mul_f32_e32 v1, v7, v7
	v_cvt_pk_bf16_f32 v11, v18, v19
	v_add_f32_e32 v18, v12, v13
	v_pk_add_f32 v[12:13], v[2:3], v[34:35]
	v_fmac_f32_e32 v0, v4, v4
	v_fmac_f32_e32 v1, v6, v6
	v_add_f32_e32 v0, v0, v1
	v_mul_f32_e32 v1, v15, v15
	v_mul_f32_e32 v2, v13, v13
	v_fmac_f32_e32 v1, v14, v14
	v_fmac_f32_e32 v2, v12, v12
	v_add_f32_e32 v1, v1, v2
	v_add_f32_e32 v0, v0, v1
	v_add_f32_e32 v3, v18, v0
	v_mov_b32_e32 v18, v3
	v_mov_b32_e32 v252, v3
	s_nop 1
	v_permlane16_swap_b32_e32 v18, v252
	s_waitcnt lgkmcnt(1)
	v_lshlrev_b64 v[16:17], 11, v[48:49]
	v_lshl_add_u64 v[0:1], s[18:19], 0, v[16:17]
	v_lshl_add_u64 v[16:17], v[154:155], 1, v[0:1]
	v_cvt_pk_bf16_f32 v10, v20, v21
	s_waitcnt lgkmcnt(0)
	v_add_f32_e32 v0, v18, v252
	v_mov_b32_e32 v1, v0
	v_mov_b32_e32 v252, v0
	s_nop 1
	v_permlane32_swap_b32_e32 v1, v252
	v_cvt_pk_bf16_f32 v2, v4, v5
	v_cvt_pk_bf16_f32 v3, v6, v7
	v_cvt_pk_bf16_f32 v4, v14, v15
	v_cvt_pk_bf16_f32 v5, v12, v13
	global_store_dwordx4 v[16:17], v[8:11], off
	global_store_dwordx4 v[16:17], v[2:5], off offset:256
	s_and_saveexec_b64 s[10:11], s[40:41]
	s_cbranch_execz .LBB0_324
	s_waitcnt lgkmcnt(0)
	v_add_f32_e32 v2, v1, v252
	s_lshl_b32 s4, s66, 2
	v_lshlrev_b64 v[0:1], 6, v[48:49]
	s_ashr_i32 s5, s4, 31
	v_lshl_add_u64 v[0:1], s[6:7], 0, v[0:1]
	v_lshl_add_u64 v[0:1], s[4:5], 2, v[0:1]
	s_lshl_b32 s16, s58, 2
	v_lshl_add_u64 v[0:1], v[0:1], 0, s[16:17]
	global_store_dword v[0:1], v2, off

.LBB0_397:
	s_lshl_b32 s10, s68, 8
	s_add_i32 s10, s10, s58
	s_cmp_eq_u32 s68, s69
	s_cbranch_scc1 .LBB0_401
	v_mov_b32_e32 v142, v152
	v_and_b32_e32 v143, 64, v219
	v_ashrrev_i32_e32 v128, 31, v142
	v_lshrrev_b32_e32 v128, 30, v128
	v_add_u32_e32 v128, v142, v128
	v_ashrrev_i32_e32 v160, 2, v128
	v_and_b32_e32 v128, 0x3ffffffc, v128
	v_lshlrev_b32_e32 v130, 1, v160
	v_sub_u32_e32 v128, v142, v128
	v_and_b32_e32 v130, 0xffffff80, v130
	v_and_or_b32 v131, v160, 63, s10
	v_lshlrev_b32_e32 v128, 2, v128
	v_add_u32_e32 v130, v131, v130
	v_ashrrev_i32_e32 v129, 31, v128
	v_ashrrev_i32_e32 v131, 31, v130
	v_lshl_add_u64 v[128:129], v[128:129], 2, s[0:1]
	v_lshlrev_b64 v[144:145], 6, v[130:131]
	v_lshl_add_u64 v[144:145], v[128:129], 0, v[144:145]
	global_load_dwordx4 v[164:167], v[144:145], off offset:1024
	global_load_dwordx4 v[168:171], v[144:145], off offset:2048
	global_load_dwordx4 v[172:175], v[144:145], off offset:3072
	v_add_co_u32_e32 v250, vcc, 0x2000, v144
	v_addc_co_u32_e32 v251, vcc, 0, v145, vcc
	global_load_dwordx4 v[186:189], v[250:251], off
	global_load_dwordx4 v[190:193], v[250:251], off offset:1024
	global_load_dwordx4 v[194:197], v[250:251], off offset:2048
	global_load_dwordx4 v[198:201], v[250:251], off offset:3072
	global_load_dwordx4 v[144:147], v[144:145], off
	v_add_u32_e32 v148, 64, v143
	v_add_u32_e32 v130, 0x80, v130
	s_waitcnt vmcnt(0)
	v_add_f32_e32 v131, v144, v145
	v_add_f32_e32 v144, v146, v147
	v_add_f32_e32 v131, v131, v144
	v_xor_b32_e32 v144, 1, v219
	v_cmp_lt_i32_e32 vcc, v144, v148
	s_nop 1
	v_cndmask_b32_e32 v144, v219, v144, vcc
	v_lshlrev_b32_e32 v146, 2, v144
	s_nop 1
	s_waitcnt lgkmcnt(0)
	v_add_f32_dpp v131, v131, v131 quad_perm:[1,0,3,2] row_mask:0xf bank_mask:0xf
	v_xor_b32_e32 v144, 2, v219
	v_cmp_lt_i32_e32 vcc, v144, v148
	s_nop 1
	v_cndmask_b32_e32 v144, v219, v144, vcc
	v_lshlrev_b32_e32 v145, 2, v144
	s_nop 1
	s_waitcnt lgkmcnt(0)
	v_add_f32_dpp v131, v131, v131 quad_perm:[2,3,0,1] row_mask:0xf bank_mask:0xf
	v_fmamk_f32 v131, v131, 0x3a800000, v220
	v_rsq_f32_e32 v144, v131
	v_add_u32_e32 v131, 16, v160
	v_lshlrev_b32_e32 v147, 1, v131
	v_and_b32_e32 v147, 0xffffff80, v147
	v_and_or_b32 v131, v131, 63, s10
	v_add_u32_e32 v148, v131, v147
	v_ashrrev_i32_e32 v149, 31, v148
	v_lshlrev_b64 v[148:149], 6, v[148:149]
	v_lshl_add_u64 v[148:149], v[128:129], 0, v[148:149]
	s_waitcnt vmcnt(0)
	v_add_f32_e32 v131, v164, v165
	v_add_f32_e32 v147, v166, v167
	v_add_f32_e32 v131, v131, v147
	s_nop 1
	s_waitcnt lgkmcnt(0)
	v_add_f32_dpp v131, v131, v131 quad_perm:[1,0,3,2] row_mask:0xf bank_mask:0xf
	s_nop 1
	s_waitcnt lgkmcnt(0)
	v_add_f32_dpp v131, v131, v131 quad_perm:[2,3,0,1] row_mask:0xf bank_mask:0xf
	v_fmamk_f32 v131, v131, 0x3a800000, v220
	v_rsq_f32_e32 v147, v131
	v_add_u32_e32 v131, 32, v160
	v_lshlrev_b32_e32 v148, 1, v131
	v_and_b32_e32 v148, 0xffffff80, v148
	v_and_or_b32 v131, v131, 63, s10
	v_add_u32_e32 v148, v131, v148
	v_ashrrev_i32_e32 v149, 31, v148
	v_lshlrev_b64 v[148:149], 6, v[148:149]
	v_lshl_add_u64 v[148:149], v[128:129], 0, v[148:149]
	s_waitcnt vmcnt(0)
	v_add_f32_e32 v131, v168, v169
	v_add_f32_e32 v148, v170, v171
	v_add_f32_e32 v131, v131, v148
	s_nop 1
	s_waitcnt lgkmcnt(0)
	v_add_f32_dpp v131, v131, v131 quad_perm:[1,0,3,2] row_mask:0xf bank_mask:0xf
	s_nop 1
	s_waitcnt lgkmcnt(0)
	v_add_f32_dpp v131, v131, v131 quad_perm:[2,3,0,1] row_mask:0xf bank_mask:0xf
	v_fmamk_f32 v131, v131, 0x3a800000, v220
	v_rsq_f32_e32 v148, v131
	v_add_u32_e32 v131, 48, v160
	v_lshlrev_b32_e32 v149, 1, v131
	v_and_b32_e32 v149, 0xffffff80, v149
	v_and_or_b32 v131, v131, 63, s10
	v_add_u32_e32 v156, v131, v149
	v_ashrrev_i32_e32 v157, 31, v156
	v_lshlrev_b64 v[156:157], 6, v[156:157]
	v_lshl_add_u64 v[156:157], v[128:129], 0, v[156:157]
	s_waitcnt vmcnt(0)
	v_add_f32_e32 v131, v172, v173
	v_add_f32_e32 v149, v174, v175
	v_add_f32_e32 v131, v131, v149
	s_nop 1
	s_waitcnt lgkmcnt(0)
	v_add_f32_dpp v131, v131, v131 quad_perm:[1,0,3,2] row_mask:0xf bank_mask:0xf
	s_nop 1
	s_waitcnt lgkmcnt(0)
	v_add_f32_dpp v131, v131, v131 quad_perm:[2,3,0,1] row_mask:0xf bank_mask:0xf
	v_fmamk_f32 v131, v131, 0x3a800000, v220
	v_rsq_f32_e32 v149, v131
	v_ashrrev_i32_e32 v131, 31, v130
	v_lshlrev_b64 v[130:131], 6, v[130:131]
	v_lshl_add_u64 v[130:131], v[128:129], 0, v[130:131]
	s_waitcnt vmcnt(0)
	v_add_f32_e32 v130, v186, v187
	v_add_f32_e32 v131, v188, v189
	v_add_f32_e32 v130, v130, v131
	s_nop 1
	s_waitcnt lgkmcnt(0)
	v_add_f32_dpp v130, v130, v130 quad_perm:[1,0,3,2] row_mask:0xf bank_mask:0xf
	s_nop 1
	s_waitcnt lgkmcnt(0)
	v_add_f32_dpp v130, v130, v130 quad_perm:[2,3,0,1] row_mask:0xf bank_mask:0xf
	v_fmamk_f32 v130, v130, 0x3a800000, v220
	v_rsq_f32_e32 v161, v130
	v_add_u32_e32 v130, 0x50, v160
	v_lshlrev_b32_e32 v131, 1, v130
	v_and_b32_e32 v131, 0xffffff80, v131
	v_and_or_b32 v130, v130, 63, s10
	v_add_u32_e32 v130, v130, v131
	v_ashrrev_i32_e32 v131, 31, v130
	v_lshlrev_b64 v[130:131], 6, v[130:131]
	v_lshl_add_u64 v[130:131], v[128:129], 0, v[130:131]
	s_waitcnt vmcnt(0)
	v_add_f32_e32 v130, v190, v191
	v_add_f32_e32 v131, v192, v193
	v_add_f32_e32 v130, v130, v131
	s_nop 1
	s_waitcnt lgkmcnt(0)
	v_add_f32_dpp v130, v130, v130 quad_perm:[1,0,3,2] row_mask:0xf bank_mask:0xf
	s_nop 1
	s_waitcnt lgkmcnt(0)
	v_add_f32_dpp v130, v130, v130 quad_perm:[2,3,0,1] row_mask:0xf bank_mask:0xf
	v_fmamk_f32 v130, v130, 0x3a800000, v220
	v_rsq_f32_e32 v162, v130
	v_add_u32_e32 v130, 0x60, v160
	v_lshlrev_b32_e32 v131, 1, v130
	v_and_b32_e32 v131, 0xffffff80, v131
	v_and_or_b32 v130, v130, 63, s10
	v_add_u32_e32 v130, v130, v131
	v_ashrrev_i32_e32 v131, 31, v130
	v_lshlrev_b64 v[130:131], 6, v[130:131]
	v_lshl_add_u64 v[130:131], v[128:129], 0, v[130:131]
	s_waitcnt vmcnt(0)
	v_add_f32_e32 v130, v194, v195
	v_add_f32_e32 v131, v196, v197
	v_add_f32_e32 v130, v130, v131
	s_nop 1
	s_waitcnt lgkmcnt(0)
	v_add_f32_dpp v130, v130, v130 quad_perm:[1,0,3,2] row_mask:0xf bank_mask:0xf
	s_nop 1
	s_waitcnt lgkmcnt(0)
	v_add_f32_dpp v130, v130, v130 quad_perm:[2,3,0,1] row_mask:0xf bank_mask:0xf
	v_fmamk_f32 v130, v130, 0x3a800000, v220
	v_rsq_f32_e32 v156, v130
	v_add_u32_e32 v130, 0x70, v160
	v_lshlrev_b32_e32 v131, 1, v130
	v_and_b32_e32 v131, 0xffffff80, v131
	v_and_or_b32 v130, v130, 63, s10
	v_add_u32_e32 v130, v130, v131
	v_ashrrev_i32_e32 v131, 31, v130
	v_lshlrev_b64 v[130:131], 6, v[130:131]
	v_lshl_add_u64 v[128:129], v[128:129], 0, v[130:131]
	s_waitcnt vmcnt(0)
	v_add_f32_e32 v128, v198, v199
	v_add_f32_e32 v129, v200, v201
	v_add_f32_e32 v128, v128, v129
	s_nop 1
	s_waitcnt lgkmcnt(0)
	v_add_f32_dpp v128, v128, v128 quad_perm:[1,0,3,2] row_mask:0xf bank_mask:0xf
	s_nop 1
	s_waitcnt lgkmcnt(0)
	v_add_f32_dpp v128, v128, v128 quad_perm:[2,3,0,1] row_mask:0xf bank_mask:0xf
	v_fmamk_f32 v128, v128, 0x3a800000, v220
	v_rsq_f32_e32 v128, v128
	v_lshlrev_b32_e32 v129, 2, v142
	v_and_or_b32 v129, v129, 60, v143
	v_lshlrev_b32_e32 v146, 2, v129
	ds_bpermute_b32 v145, v146, v144
	ds_bpermute_b32 v144, v146, v147
	ds_bpermute_b32 v143, v146, v148
	ds_bpermute_b32 v142, v146, v149
	ds_bpermute_b32 v131, v146, v161
	ds_bpermute_b32 v130, v146, v162
	ds_bpermute_b32 v129, v146, v156
	ds_bpermute_b32 v128, v146, v128
	s_and_saveexec_b64 s[28:29], s[40:41]
	s_cbranch_execz .LBB0_400
	s_waitcnt lgkmcnt(7)
	v_mul_f32_e32 v146, 0xbfb8aa3b, v145
	v_mul_f32_e32 v145, v145, v145
	s_waitcnt lgkmcnt(6)
	v_mul_f32_e32 v147, 0xbfb8aa3b, v144
	v_mul_f32_e32 v144, v144, v144
	v_rcp_f32_e32 v145, v145
	v_rcp_f32_e32 v144, v144
	ds_write2_b32 v153, v146, v147 offset1:16
	v_add_u32_e32 v146, 0x1000, v153
	ds_write2_b32 v146, v145, v144 offset1:16
	s_waitcnt lgkmcnt(7)
	v_mul_f32_e32 v144, 0xbfb8aa3b, v143
	v_mul_f32_e32 v143, v143, v143
	s_waitcnt lgkmcnt(6)
	v_mul_f32_e32 v145, 0xbfb8aa3b, v142
	v_mul_f32_e32 v142, v142, v142
	v_rcp_f32_e32 v143, v143
	v_rcp_f32_e32 v142, v142
	ds_write2_b32 v153, v144, v145 offset0:32 offset1:48
	ds_write2_b32 v146, v143, v142 offset0:32 offset1:48
	s_waitcnt lgkmcnt(7)
	v_mul_f32_e32 v142, 0xbfb8aa3b, v131
	v_mul_f32_e32 v131, v131, v131
	s_waitcnt lgkmcnt(6)
	v_mul_f32_e32 v143, 0xbfb8aa3b, v130
	v_mul_f32_e32 v130, v130, v130
	v_rcp_f32_e32 v131, v131
	v_rcp_f32_e32 v130, v130
	ds_write2_b32 v153, v142, v143 offset0:64 offset1:80
	ds_write2_b32 v146, v131, v130 offset0:64 offset1:80
	s_waitcnt lgkmcnt(7)
	v_mul_f32_e32 v130, 0xbfb8aa3b, v129
	v_mul_f32_e32 v129, v129, v129
	s_waitcnt lgkmcnt(6)
	v_mul_f32_e32 v131, 0xbfb8aa3b, v128
	v_mul_f32_e32 v128, v128, v128
	v_rcp_f32_e32 v129, v129
	v_rcp_f32_e32 v128, v128
	ds_write2_b32 v153, v130, v131 offset0:96 offset1:112
	ds_write2_b32 v146, v129, v128 offset0:96 offset1:112

.LBB0_478:
	v_lshl_or_b32 v166, s16, 8, v196
	v_lshl_add_u32 v170, s67, 8, v194
	v_ashrrev_i32_e32 v167, 31, v166
	v_lshlrev_b64 v[204:205], 1, v[166:167]
	v_ashrrev_i32_e32 v171, 31, v170
	v_lshl_add_u64 v[168:169], s[18:19], 0, v[204:205]
	v_lshlrev_b64 v[206:207], 11, v[170:171]
	v_lshl_add_u64 v[128:129], v[168:169], 0, v[206:207]
	global_load_dwordx4 v[200:203], v[128:129], off
	global_load_dwordx4 v[152:155], v[128:129], off offset:256
	v_or_b32_e32 v190, 16, v170
	v_ashrrev_i32_e32 v191, 31, v190
	v_or_b32_e32 v186, 32, v170
	v_lshlrev_b64 v[192:193], 11, v[190:191]
	v_ashrrev_i32_e32 v187, 31, v186
	v_or_b32_e32 v172, 48, v170
	v_lshl_add_u64 v[128:129], v[168:169], 0, v[192:193]
	v_lshlrev_b64 v[188:189], 11, v[186:187]
	v_ashrrev_i32_e32 v173, 31, v172
	global_load_dwordx4 v[148:151], v[128:129], off
	global_load_dwordx4 v[144:147], v[128:129], off offset:256
	v_lshl_add_u64 v[128:129], v[168:169], 0, v[188:189]
	v_lshlrev_b64 v[174:175], 11, v[172:173]
	global_load_dwordx4 v[140:143], v[128:129], off
	global_load_dwordx4 v[136:139], v[128:129], off offset:256
	v_lshl_add_u64 v[128:129], v[168:169], 0, v[174:175]
	global_load_dwordx4 v[132:135], v[128:129], off
	s_nop 0
	global_load_dwordx4 v[128:131], v[128:129], off offset:256
	v_add_u32_e32 v216, 0x80, v170
	v_ashrrev_i32_e32 v217, 31, v216
	v_lshlrev_b64 v[216:217], 11, v[216:217]
	v_lshl_add_u64 v[216:217], v[168:169], 0, v[216:217]
	global_load_dwordx4 v[212:215], v[216:217], off
	global_load_dwordx4 v[222:225], v[216:217], off offset:256
	v_add_u32_e32 v216, 0x90, v170
	v_ashrrev_i32_e32 v217, 31, v216
	v_lshlrev_b64 v[216:217], 11, v[216:217]
	v_lshl_add_u64 v[216:217], v[168:169], 0, v[216:217]
	global_load_dwordx4 v[226:229], v[216:217], off
	global_load_dwordx4 v[230:233], v[216:217], off offset:256
	v_add_u32_e32 v216, 0xa0, v170
	v_ashrrev_i32_e32 v217, 31, v216
	v_lshlrev_b64 v[216:217], 11, v[216:217]
	v_lshl_add_u64 v[216:217], v[168:169], 0, v[216:217]
	global_load_dwordx4 v[234:237], v[216:217], off
	global_load_dwordx4 v[238:241], v[216:217], off offset:256
	v_add_u32_e32 v216, 0xb0, v170
	v_ashrrev_i32_e32 v217, 31, v216
	v_lshlrev_b64 v[216:217], 11, v[216:217]
	v_lshl_add_u64 v[216:217], v[168:169], 0, v[216:217]
	global_load_dwordx4 v[242:245], v[216:217], off
	global_load_dwordx4 v[246:249], v[216:217], off offset:256
	v_and_b32_e32 v199, 64, v219
	v_xor_b32_e32 v198, 16, v219
	v_add_u32_e32 v199, 64, v199
	v_cmp_lt_i32_e32 vcc, v198, v199
	v_xor_b32_e32 v208, 32, v219
	s_lshl_b32 s28, s16, 2
	v_cndmask_b32_e32 v198, v219, v198, vcc
	v_cmp_lt_i32_e32 vcc, v208, v199
	v_lshlrev_b32_e32 v198, 2, v198
	s_ashr_i32 s29, s28, 31
	v_cndmask_b32_e32 v199, v219, v208, vcc
	v_lshlrev_b32_e32 v199, 2, v199
	s_waitcnt vmcnt(0)
	v_lshlrev_b32_e32 v208, 16, v200
	v_and_b32_e32 v209, 0xffff0000, v200
	v_lshlrev_b32_e32 v200, 16, v201
	v_and_b32_e32 v201, 0xffff0000, v201
	v_lshlrev_b32_e32 v210, 16, v202
	v_and_b32_e32 v211, 0xffff0000, v202
	v_lshlrev_b32_e32 v202, 16, v203
	v_and_b32_e32 v203, 0xffff0000, v203
	v_pk_add_f32 v[200:201], v[122:123], v[200:201]
	v_pk_add_f32 v[208:209], v[120:121], v[208:209]
	v_pk_add_f32 v[126:127], v[126:127], v[202:203]
	v_pk_add_f32 v[124:125], v[124:125], v[210:211]
	v_lshl_add_u64 v[202:203], s[18:19], 0, v[206:207]
	v_cvt_pk_bf16_f32 v120, v208, v209
	v_cvt_pk_bf16_f32 v121, v200, v201
	v_cvt_pk_bf16_f32 v122, v124, v125
	v_cvt_pk_bf16_f32 v123, v126, v127
	v_lshl_add_u64 v[202:203], v[202:203], 0, v[204:205]
	global_store_dwordx4 v[202:203], v[120:123], off
	s_nop 1
	v_mul_f32_e32 v120, v209, v209
	v_mul_f32_e32 v121, v201, v201
	v_fmac_f32_e32 v120, v208, v208
	v_fmac_f32_e32 v121, v200, v200
	v_add_f32_e32 v120, v120, v121
	v_mul_f32_e32 v121, v125, v125
	v_mul_f32_e32 v122, v127, v127
	v_fmac_f32_e32 v121, v124, v124
	v_fmac_f32_e32 v122, v126, v126
	v_add_f32_e32 v121, v121, v122
	v_add_f32_e32 v200, v120, v121
	v_lshlrev_b32_e32 v120, 16, v152
	v_and_b32_e32 v121, 0xffff0000, v152
	v_lshlrev_b32_e32 v122, 16, v153
	v_and_b32_e32 v123, 0xffff0000, v153
	v_lshlrev_b32_e32 v124, 16, v154
	v_and_b32_e32 v125, 0xffff0000, v154
	v_lshlrev_b32_e32 v126, 16, v155
	v_and_b32_e32 v127, 0xffff0000, v155
	v_pk_add_f32 v[118:119], v[118:119], v[122:123]
	v_pk_add_f32 v[116:117], v[116:117], v[120:121]
	v_pk_add_f32 v[120:121], v[114:115], v[126:127]
	v_pk_add_f32 v[122:123], v[112:113], v[124:125]
	v_cvt_pk_bf16_f32 v112, v116, v117
	v_cvt_pk_bf16_f32 v113, v118, v119
	v_cvt_pk_bf16_f32 v114, v122, v123
	v_cvt_pk_bf16_f32 v115, v120, v121
	global_store_dwordx4 v[202:203], v[112:115], off offset:256
	s_nop 1
	v_mul_f32_e32 v112, v117, v117
	v_mul_f32_e32 v113, v119, v119
	v_fmac_f32_e32 v112, v116, v116
	v_fmac_f32_e32 v113, v118, v118
	v_add_f32_e32 v112, v112, v113
	v_mul_f32_e32 v113, v123, v123
	v_mul_f32_e32 v114, v121, v121
	v_fmac_f32_e32 v113, v122, v122
	v_fmac_f32_e32 v114, v120, v120
	v_add_f32_e32 v113, v113, v114
	v_add_f32_e32 v112, v112, v113
	v_add_f32_e32 v112, v200, v112
	v_mov_b32_e32 v113, v112
	v_mov_b32_e32 v252, v112
	s_nop 1
	v_permlane16_swap_b32_e32 v113, v252
	s_waitcnt lgkmcnt(0)
	v_add_f32_e32 v112, v113, v252
	v_mov_b32_e32 v113, v112
	v_mov_b32_e32 v252, v112
	s_nop 1
	v_permlane32_swap_b32_e32 v113, v252
	s_and_saveexec_b64 s[10:11], s[40:41]
	s_cbranch_execz .LBB0_480
	s_waitcnt lgkmcnt(0)
	v_add_f32_e32 v114, v113, v252
	v_lshlrev_b64 v[112:113], 6, v[170:171]
	v_lshl_add_u64 v[112:113], s[0:1], 0, v[112:113]
	v_lshl_add_u64 v[112:113], s[28:29], 2, v[112:113]
	s_lshl_b32 s16, s51, 2
	v_lshl_add_u64 v[112:113], v[112:113], 0, s[16:17]
	global_store_dword v[112:113], v114, off
.LBB0_480:
	s_or_b64 exec, exec, s[10:11]
	v_lshlrev_b32_e32 v112, 16, v148
	s_waitcnt lgkmcnt(0)
	v_and_b32_e32 v113, 0xffff0000, v148
	v_lshlrev_b32_e32 v114, 16, v149
	v_and_b32_e32 v115, 0xffff0000, v149
	v_lshlrev_b32_e32 v116, 16, v150
	v_and_b32_e32 v117, 0xffff0000, v150
	v_pk_add_f32 v[108:109], v[108:109], v[112:113]
	v_pk_add_f32 v[110:111], v[110:111], v[114:115]
	v_pk_add_f32 v[114:115], v[104:105], v[116:117]
	v_cvt_pk_bf16_f32 v104, v108, v109
	v_mul_f32_e32 v109, v109, v109
	v_lshlrev_b32_e32 v118, 16, v151
	v_and_b32_e32 v119, 0xffff0000, v151
	v_fmac_f32_e32 v109, v108, v108
	v_mul_f32_e32 v108, v111, v111
	v_pk_add_f32 v[112:113], v[106:107], v[118:119]
	v_fmac_f32_e32 v108, v110, v110
	v_cvt_pk_bf16_f32 v105, v110, v111
	v_add_f32_e32 v108, v109, v108
	v_mul_f32_e32 v109, v115, v115
	v_mul_f32_e32 v110, v113, v113
	v_fmac_f32_e32 v109, v114, v114
	v_fmac_f32_e32 v110, v112, v112
	v_add_f32_e32 v109, v109, v110
	v_add_f32_e32 v116, v108, v109
	v_lshlrev_b32_e32 v108, 16, v144
	v_and_b32_e32 v109, 0xffff0000, v144
	v_lshlrev_b32_e32 v110, 16, v145
	v_and_b32_e32 v111, 0xffff0000, v145
	v_cvt_pk_bf16_f32 v107, v112, v113
	v_lshlrev_b32_e32 v112, 16, v146
	v_and_b32_e32 v113, 0xffff0000, v146
	v_pk_add_f32 v[102:103], v[102:103], v[110:111]
	v_pk_add_f32 v[100:101], v[100:101], v[108:109]
	v_cvt_pk_bf16_f32 v106, v114, v115
	v_lshlrev_b32_e32 v114, 16, v147
	v_and_b32_e32 v115, 0xffff0000, v147
	v_pk_add_f32 v[110:111], v[96:97], v[112:113]
	v_mul_f32_e32 v96, v101, v101
	v_mul_f32_e32 v97, v103, v103
	v_pk_add_f32 v[108:109], v[98:99], v[114:115]
	v_fmac_f32_e32 v96, v100, v100
	v_fmac_f32_e32 v97, v102, v102
	v_add_f32_e32 v96, v96, v97
	v_mul_f32_e32 v97, v111, v111
	v_mul_f32_e32 v98, v109, v109
	v_fmac_f32_e32 v97, v110, v110
	v_fmac_f32_e32 v98, v108, v108
	v_add_f32_e32 v97, v97, v98
	v_add_f32_e32 v96, v96, v97
	v_add_f32_e32 v99, v116, v96
	v_mov_b32_e32 v114, v99
	v_mov_b32_e32 v252, v99
	s_nop 1
	v_permlane16_swap_b32_e32 v114, v252
	v_lshl_add_u64 v[96:97], s[18:19], 0, v[192:193]
	v_lshl_add_u64 v[112:113], v[166:167], 1, v[96:97]
	v_cvt_pk_bf16_f32 v98, v100, v101
	v_cvt_pk_bf16_f32 v100, v110, v111
	s_waitcnt lgkmcnt(0)
	v_add_f32_e32 v96, v114, v252
	v_mov_b32_e32 v97, v96
	v_mov_b32_e32 v252, v96
	s_nop 1
	v_permlane32_swap_b32_e32 v97, v252
	v_cvt_pk_bf16_f32 v99, v102, v103
	v_cvt_pk_bf16_f32 v101, v108, v109
	global_store_dwordx4 v[112:113], v[104:107], off
	global_store_dwordx4 v[112:113], v[98:101], off offset:256
	s_and_saveexec_b64 s[10:11], s[40:41]
	s_cbranch_execz .LBB0_482
	s_waitcnt lgkmcnt(0)
	v_add_f32_e32 v98, v97, v252
	v_lshlrev_b64 v[96:97], 6, v[190:191]
	v_lshl_add_u64 v[96:97], s[0:1], 0, v[96:97]
	v_lshl_add_u64 v[96:97], s[28:29], 2, v[96:97]
	s_lshl_b32 s16, s51, 2
	v_lshl_add_u64 v[96:97], v[96:97], 0, s[16:17]
	global_store_dword v[96:97], v98, off
.LBB0_482:
	s_or_b64 exec, exec, s[10:11]
	v_lshlrev_b32_e32 v96, 16, v140
	s_waitcnt lgkmcnt(0)
	v_and_b32_e32 v97, 0xffff0000, v140
	v_lshlrev_b32_e32 v98, 16, v141
	v_and_b32_e32 v99, 0xffff0000, v141
	v_lshlrev_b32_e32 v100, 16, v142
	v_and_b32_e32 v101, 0xffff0000, v142
	v_pk_add_f32 v[92:93], v[92:93], v[96:97]
	v_pk_add_f32 v[94:95], v[94:95], v[98:99]
	v_pk_add_f32 v[98:99], v[88:89], v[100:101]
	v_cvt_pk_bf16_f32 v88, v92, v93
	v_mul_f32_e32 v93, v93, v93
	v_lshlrev_b32_e32 v102, 16, v143
	v_and_b32_e32 v103, 0xffff0000, v143
	v_fmac_f32_e32 v93, v92, v92
	v_mul_f32_e32 v92, v95, v95
	v_pk_add_f32 v[96:97], v[90:91], v[102:103]
	v_fmac_f32_e32 v92, v94, v94
	v_cvt_pk_bf16_f32 v89, v94, v95
	v_add_f32_e32 v92, v93, v92
	v_mul_f32_e32 v93, v99, v99
	v_mul_f32_e32 v94, v97, v97
	v_fmac_f32_e32 v93, v98, v98
	v_fmac_f32_e32 v94, v96, v96
	v_add_f32_e32 v93, v93, v94
	v_add_f32_e32 v100, v92, v93
	v_lshlrev_b32_e32 v92, 16, v136
	v_and_b32_e32 v93, 0xffff0000, v136
	v_lshlrev_b32_e32 v94, 16, v137
	v_and_b32_e32 v95, 0xffff0000, v137
	v_cvt_pk_bf16_f32 v91, v96, v97
	v_lshlrev_b32_e32 v96, 16, v138
	v_and_b32_e32 v97, 0xffff0000, v138
	v_pk_add_f32 v[86:87], v[86:87], v[94:95]
	v_pk_add_f32 v[84:85], v[84:85], v[92:93]
	v_cvt_pk_bf16_f32 v90, v98, v99
	v_lshlrev_b32_e32 v98, 16, v139
	v_and_b32_e32 v99, 0xffff0000, v139
	v_pk_add_f32 v[94:95], v[80:81], v[96:97]
	v_mul_f32_e32 v80, v85, v85
	v_mul_f32_e32 v81, v87, v87
	v_pk_add_f32 v[92:93], v[82:83], v[98:99]
	v_fmac_f32_e32 v80, v84, v84
	v_fmac_f32_e32 v81, v86, v86
	v_add_f32_e32 v80, v80, v81
	v_mul_f32_e32 v81, v95, v95
	v_mul_f32_e32 v82, v93, v93
	v_fmac_f32_e32 v81, v94, v94
	v_fmac_f32_e32 v82, v92, v92
	v_add_f32_e32 v81, v81, v82
	v_add_f32_e32 v80, v80, v81
	v_add_f32_e32 v83, v100, v80
	v_mov_b32_e32 v98, v83
	v_mov_b32_e32 v252, v83
	s_nop 1
	v_permlane16_swap_b32_e32 v98, v252
	v_lshl_add_u64 v[80:81], s[18:19], 0, v[188:189]
	v_lshl_add_u64 v[96:97], v[166:167], 1, v[80:81]
	v_cvt_pk_bf16_f32 v82, v84, v85
	v_cvt_pk_bf16_f32 v84, v94, v95
	s_waitcnt lgkmcnt(0)
	v_add_f32_e32 v80, v98, v252
	v_mov_b32_e32 v81, v80
	v_mov_b32_e32 v252, v80
	s_nop 1
	v_permlane32_swap_b32_e32 v81, v252
	v_cvt_pk_bf16_f32 v83, v86, v87
	v_cvt_pk_bf16_f32 v85, v92, v93
	global_store_dwordx4 v[96:97], v[88:91], off
	global_store_dwordx4 v[96:97], v[82:85], off offset:256
	s_and_saveexec_b64 s[10:11], s[40:41]
	s_cbranch_execz .LBB0_484
	s_waitcnt lgkmcnt(0)
	v_add_f32_e32 v82, v81, v252
	v_lshlrev_b64 v[80:81], 6, v[186:187]
	v_lshl_add_u64 v[80:81], s[0:1], 0, v[80:81]
	v_lshl_add_u64 v[80:81], s[28:29], 2, v[80:81]
	s_lshl_b32 s16, s51, 2
	v_lshl_add_u64 v[80:81], v[80:81], 0, s[16:17]
	global_store_dword v[80:81], v82, off
.LBB0_484:
	s_or_b64 exec, exec, s[10:11]
	v_lshlrev_b32_e32 v80, 16, v132
	s_waitcnt lgkmcnt(0)
	v_and_b32_e32 v81, 0xffff0000, v132
	v_lshlrev_b32_e32 v82, 16, v133
	v_and_b32_e32 v83, 0xffff0000, v133
	v_lshlrev_b32_e32 v84, 16, v134
	v_and_b32_e32 v85, 0xffff0000, v134
	v_pk_add_f32 v[76:77], v[76:77], v[80:81]
	v_pk_add_f32 v[78:79], v[78:79], v[82:83]
	v_pk_add_f32 v[82:83], v[72:73], v[84:85]
	v_cvt_pk_bf16_f32 v72, v76, v77
	v_mul_f32_e32 v77, v77, v77
	v_lshlrev_b32_e32 v86, 16, v135
	v_and_b32_e32 v87, 0xffff0000, v135
	v_fmac_f32_e32 v77, v76, v76
	v_mul_f32_e32 v76, v79, v79
	v_pk_add_f32 v[80:81], v[74:75], v[86:87]
	v_fmac_f32_e32 v76, v78, v78
	v_cvt_pk_bf16_f32 v73, v78, v79
	v_add_f32_e32 v76, v77, v76
	v_mul_f32_e32 v77, v83, v83
	v_mul_f32_e32 v78, v81, v81
	v_fmac_f32_e32 v77, v82, v82
	v_fmac_f32_e32 v78, v80, v80
	v_add_f32_e32 v77, v77, v78
	v_add_f32_e32 v84, v76, v77
	v_lshlrev_b32_e32 v76, 16, v128
	v_and_b32_e32 v77, 0xffff0000, v128
	v_lshlrev_b32_e32 v78, 16, v129
	v_and_b32_e32 v79, 0xffff0000, v129
	v_cvt_pk_bf16_f32 v75, v80, v81
	v_lshlrev_b32_e32 v80, 16, v130
	v_and_b32_e32 v81, 0xffff0000, v130
	v_pk_add_f32 v[70:71], v[70:71], v[78:79]
	v_pk_add_f32 v[68:69], v[68:69], v[76:77]
	v_cvt_pk_bf16_f32 v74, v82, v83
	v_lshlrev_b32_e32 v82, 16, v131
	v_and_b32_e32 v83, 0xffff0000, v131
	v_pk_add_f32 v[78:79], v[64:65], v[80:81]
	v_mul_f32_e32 v64, v69, v69
	v_mul_f32_e32 v65, v71, v71
	v_pk_add_f32 v[76:77], v[66:67], v[82:83]
	v_fmac_f32_e32 v64, v68, v68
	v_fmac_f32_e32 v65, v70, v70
	v_add_f32_e32 v64, v64, v65
	v_mul_f32_e32 v65, v79, v79
	v_mul_f32_e32 v66, v77, v77
	v_fmac_f32_e32 v65, v78, v78
	v_fmac_f32_e32 v66, v76, v76
	v_add_f32_e32 v65, v65, v66
	v_add_f32_e32 v64, v64, v65
	v_add_f32_e32 v67, v84, v64
	v_mov_b32_e32 v82, v67
	v_mov_b32_e32 v252, v67
	s_nop 1
	v_permlane16_swap_b32_e32 v82, v252
	v_lshl_add_u64 v[64:65], s[18:19], 0, v[174:175]
	v_lshl_add_u64 v[80:81], v[166:167], 1, v[64:65]
	v_cvt_pk_bf16_f32 v66, v68, v69
	v_cvt_pk_bf16_f32 v68, v78, v79
	s_waitcnt lgkmcnt(0)
	v_add_f32_e32 v64, v82, v252
	v_mov_b32_e32 v65, v64
	v_mov_b32_e32 v252, v64
	s_nop 1
	v_permlane32_swap_b32_e32 v65, v252
	v_cvt_pk_bf16_f32 v67, v70, v71
	v_cvt_pk_bf16_f32 v69, v76, v77
	global_store_dwordx4 v[80:81], v[72:75], off
	global_store_dwordx4 v[80:81], v[66:69], off offset:256
	s_and_saveexec_b64 s[10:11], s[40:41]
	s_cbranch_execz .LBB0_486
	s_waitcnt lgkmcnt(0)
	v_add_f32_e32 v66, v65, v252
	v_lshlrev_b64 v[64:65], 6, v[172:173]
	v_lshl_add_u64 v[64:65], s[0:1], 0, v[64:65]
	v_lshl_add_u64 v[64:65], s[28:29], 2, v[64:65]
	s_lshl_b32 s16, s51, 2
	v_lshl_add_u64 v[64:65], v[64:65], 0, s[16:17]
	global_store_dword v[64:65], v66, off
.LBB0_486:
	s_or_b64 exec, exec, s[10:11]
	v_add_u32_e32 v104, 0x80, v170
	v_ashrrev_i32_e32 v105, 31, v104
	v_lshlrev_b64 v[110:111], 11, v[104:105]
	s_waitcnt lgkmcnt(0)
	v_lshl_add_u64 v[64:65], v[168:169], 0, v[110:111]
	v_add_u32_e32 v100, 0x90, v170
	v_ashrrev_i32_e32 v101, 31, v100
	v_add_u32_e32 v96, 0xa0, v170
	v_lshlrev_b64 v[102:103], 11, v[100:101]
	v_ashrrev_i32_e32 v97, 31, v96
	v_add_u32_e32 v92, 0xb0, v170
	v_lshl_add_u64 v[64:65], v[168:169], 0, v[102:103]
	v_lshlrev_b64 v[98:99], 11, v[96:97]
	v_ashrrev_i32_e32 v93, 31, v92
	v_lshl_add_u64 v[64:65], v[168:169], 0, v[98:99]
	v_lshlrev_b64 v[94:95], 11, v[92:93]
	v_lshl_add_u64 v[64:65], v[168:169], 0, v[94:95]
	s_nop 0
	v_lshl_add_u64 v[110:111], s[18:19], 0, v[110:111]
	v_lshl_add_u64 v[110:111], v[166:167], 1, v[110:111]
	v_lshlrev_b32_e32 v112, 16, v212
	v_and_b32_e32 v113, 0xffff0000, v212
	v_lshlrev_b32_e32 v106, 16, v213
	v_and_b32_e32 v107, 0xffff0000, v213
	v_lshlrev_b32_e32 v114, 16, v214
	v_and_b32_e32 v115, 0xffff0000, v214
	v_lshlrev_b32_e32 v108, 16, v215
	v_and_b32_e32 v109, 0xffff0000, v215
	v_pk_add_f32 v[62:63], v[62:63], v[106:107]
	v_pk_add_f32 v[60:61], v[60:61], v[112:113]
	v_pk_add_f32 v[106:107], v[58:59], v[108:109]
	v_pk_add_f32 v[108:109], v[56:57], v[114:115]
	v_cvt_pk_bf16_f32 v56, v60, v61
	v_cvt_pk_bf16_f32 v57, v62, v63
	v_cvt_pk_bf16_f32 v58, v108, v109
	v_cvt_pk_bf16_f32 v59, v106, v107
	global_store_dwordx4 v[110:111], v[56:59], off
	s_nop 1
	v_mul_f32_e32 v56, v61, v61
	v_mul_f32_e32 v57, v63, v63
	v_fmac_f32_e32 v56, v60, v60
	v_fmac_f32_e32 v57, v62, v62
	v_add_f32_e32 v56, v56, v57
	v_mul_f32_e32 v57, v109, v109
	v_mul_f32_e32 v58, v107, v107
	v_fmac_f32_e32 v57, v108, v108
	v_fmac_f32_e32 v58, v106, v106
	v_add_f32_e32 v57, v57, v58
	v_add_f32_e32 v106, v56, v57
	v_lshlrev_b32_e32 v56, 16, v222
	v_and_b32_e32 v57, 0xffff0000, v222
	v_lshlrev_b32_e32 v58, 16, v223
	v_and_b32_e32 v59, 0xffff0000, v223
	v_lshlrev_b32_e32 v60, 16, v224
	v_and_b32_e32 v61, 0xffff0000, v224
	v_lshlrev_b32_e32 v62, 16, v225
	v_and_b32_e32 v63, 0xffff0000, v225
	v_pk_add_f32 v[54:55], v[54:55], v[58:59]
	v_pk_add_f32 v[52:53], v[52:53], v[56:57]
	v_pk_add_f32 v[56:57], v[50:51], v[62:63]
	v_pk_add_f32 v[58:59], v[48:49], v[60:61]
	v_cvt_pk_bf16_f32 v48, v52, v53
	v_cvt_pk_bf16_f32 v49, v54, v55
	v_cvt_pk_bf16_f32 v50, v58, v59
	v_cvt_pk_bf16_f32 v51, v56, v57
	global_store_dwordx4 v[110:111], v[48:51], off offset:256
	s_nop 1
	v_mul_f32_e32 v48, v53, v53
	v_mul_f32_e32 v49, v55, v55
	v_fmac_f32_e32 v48, v52, v52
	v_fmac_f32_e32 v49, v54, v54
	v_add_f32_e32 v48, v48, v49
	v_mul_f32_e32 v49, v59, v59
	v_mul_f32_e32 v50, v57, v57
	v_fmac_f32_e32 v49, v58, v58
	v_fmac_f32_e32 v50, v56, v56
	v_add_f32_e32 v49, v49, v50
	v_add_f32_e32 v48, v48, v49
	v_add_f32_e32 v48, v106, v48
	v_mov_b32_e32 v49, v48
	v_mov_b32_e32 v252, v48
	s_nop 1
	v_permlane16_swap_b32_e32 v49, v252
	s_waitcnt lgkmcnt(0)
	v_add_f32_e32 v48, v49, v252
	v_mov_b32_e32 v49, v48
	v_mov_b32_e32 v252, v48
	s_nop 1
	v_permlane32_swap_b32_e32 v49, v252
	s_and_saveexec_b64 s[10:11], s[40:41]
	s_cbranch_execz .LBB0_488
	s_waitcnt lgkmcnt(0)
	v_add_f32_e32 v50, v49, v252
	v_lshlrev_b64 v[48:49], 6, v[104:105]
	v_lshl_add_u64 v[48:49], s[0:1], 0, v[48:49]
	v_lshl_add_u64 v[48:49], s[28:29], 2, v[48:49]
	s_lshl_b32 s16, s51, 2
	v_lshl_add_u64 v[48:49], v[48:49], 0, s[16:17]
	global_store_dword v[48:49], v50, off
.LBB0_488:
	s_or_b64 exec, exec, s[10:11]
	v_lshlrev_b32_e32 v48, 16, v226
	s_waitcnt lgkmcnt(0)
	v_and_b32_e32 v49, 0xffff0000, v226
	v_lshlrev_b32_e32 v50, 16, v227
	v_and_b32_e32 v51, 0xffff0000, v227
	v_lshlrev_b32_e32 v52, 16, v228
	v_and_b32_e32 v53, 0xffff0000, v228
	v_pk_add_f32 v[44:45], v[44:45], v[48:49]
	v_pk_add_f32 v[46:47], v[46:47], v[50:51]
	v_pk_add_f32 v[50:51], v[40:41], v[52:53]
	v_cvt_pk_bf16_f32 v40, v44, v45
	v_mul_f32_e32 v45, v45, v45
	v_lshlrev_b32_e32 v54, 16, v229
	v_and_b32_e32 v55, 0xffff0000, v229
	v_fmac_f32_e32 v45, v44, v44
	v_mul_f32_e32 v44, v47, v47
	v_pk_add_f32 v[48:49], v[42:43], v[54:55]
	v_fmac_f32_e32 v44, v46, v46
	v_cvt_pk_bf16_f32 v41, v46, v47
	v_add_f32_e32 v44, v45, v44
	v_mul_f32_e32 v45, v51, v51
	v_mul_f32_e32 v46, v49, v49
	v_fmac_f32_e32 v45, v50, v50
	v_fmac_f32_e32 v46, v48, v48
	v_add_f32_e32 v45, v45, v46
	v_add_f32_e32 v52, v44, v45
	v_lshlrev_b32_e32 v44, 16, v230
	v_and_b32_e32 v45, 0xffff0000, v230
	v_lshlrev_b32_e32 v46, 16, v231
	v_and_b32_e32 v47, 0xffff0000, v231
	v_cvt_pk_bf16_f32 v43, v48, v49
	v_lshlrev_b32_e32 v48, 16, v232
	v_and_b32_e32 v49, 0xffff0000, v232
	v_pk_add_f32 v[38:39], v[38:39], v[46:47]
	v_pk_add_f32 v[36:37], v[36:37], v[44:45]
	v_cvt_pk_bf16_f32 v42, v50, v51
	v_lshlrev_b32_e32 v50, 16, v233
	v_and_b32_e32 v51, 0xffff0000, v233
	v_pk_add_f32 v[46:47], v[32:33], v[48:49]
	v_mul_f32_e32 v32, v37, v37
	v_mul_f32_e32 v33, v39, v39
	v_pk_add_f32 v[44:45], v[34:35], v[50:51]
	v_fmac_f32_e32 v32, v36, v36
	v_fmac_f32_e32 v33, v38, v38
	v_add_f32_e32 v32, v32, v33
	v_mul_f32_e32 v33, v47, v47
	v_mul_f32_e32 v34, v45, v45
	v_fmac_f32_e32 v33, v46, v46
	v_fmac_f32_e32 v34, v44, v44
	v_add_f32_e32 v33, v33, v34
	v_add_f32_e32 v32, v32, v33
	v_add_f32_e32 v35, v52, v32
	v_mov_b32_e32 v50, v35
	v_mov_b32_e32 v252, v35
	s_nop 1
	v_permlane16_swap_b32_e32 v50, v252
	v_lshl_add_u64 v[32:33], s[18:19], 0, v[102:103]
	v_lshl_add_u64 v[48:49], v[166:167], 1, v[32:33]
	v_cvt_pk_bf16_f32 v34, v36, v37
	v_cvt_pk_bf16_f32 v36, v46, v47
	s_waitcnt lgkmcnt(0)
	v_add_f32_e32 v32, v50, v252
	v_mov_b32_e32 v33, v32
	v_mov_b32_e32 v252, v32
	s_nop 1
	v_permlane32_swap_b32_e32 v33, v252
	v_cvt_pk_bf16_f32 v35, v38, v39
	v_cvt_pk_bf16_f32 v37, v44, v45
	global_store_dwordx4 v[48:49], v[40:43], off
	global_store_dwordx4 v[48:49], v[34:37], off offset:256
	s_and_saveexec_b64 s[10:11], s[40:41]
	s_cbranch_execz .LBB0_490
	s_waitcnt lgkmcnt(0)
	v_add_f32_e32 v34, v33, v252
	v_lshlrev_b64 v[32:33], 6, v[100:101]
	v_lshl_add_u64 v[32:33], s[0:1], 0, v[32:33]
	v_lshl_add_u64 v[32:33], s[28:29], 2, v[32:33]
	s_lshl_b32 s16, s51, 2
	v_lshl_add_u64 v[32:33], v[32:33], 0, s[16:17]
	global_store_dword v[32:33], v34, off
.LBB0_490:
	s_or_b64 exec, exec, s[10:11]
	v_lshlrev_b32_e32 v32, 16, v234
	s_waitcnt lgkmcnt(0)
	v_and_b32_e32 v33, 0xffff0000, v234
	v_lshlrev_b32_e32 v34, 16, v235
	v_and_b32_e32 v35, 0xffff0000, v235
	v_lshlrev_b32_e32 v36, 16, v236
	v_and_b32_e32 v37, 0xffff0000, v236
	v_pk_add_f32 v[28:29], v[28:29], v[32:33]
	v_pk_add_f32 v[30:31], v[30:31], v[34:35]
	v_pk_add_f32 v[34:35], v[24:25], v[36:37]
	v_cvt_pk_bf16_f32 v24, v28, v29
	v_mul_f32_e32 v29, v29, v29
	v_lshlrev_b32_e32 v38, 16, v237
	v_and_b32_e32 v39, 0xffff0000, v237
	v_fmac_f32_e32 v29, v28, v28
	v_mul_f32_e32 v28, v31, v31
	v_pk_add_f32 v[32:33], v[26:27], v[38:39]
	v_fmac_f32_e32 v28, v30, v30
	v_cvt_pk_bf16_f32 v25, v30, v31
	v_add_f32_e32 v28, v29, v28
	v_mul_f32_e32 v29, v35, v35
	v_mul_f32_e32 v30, v33, v33
	v_fmac_f32_e32 v29, v34, v34
	v_fmac_f32_e32 v30, v32, v32
	v_add_f32_e32 v29, v29, v30
	v_add_f32_e32 v36, v28, v29
	v_lshlrev_b32_e32 v28, 16, v238
	v_and_b32_e32 v29, 0xffff0000, v238
	v_lshlrev_b32_e32 v30, 16, v239
	v_and_b32_e32 v31, 0xffff0000, v239
	v_cvt_pk_bf16_f32 v27, v32, v33
	v_lshlrev_b32_e32 v32, 16, v240
	v_and_b32_e32 v33, 0xffff0000, v240
	v_pk_add_f32 v[22:23], v[22:23], v[30:31]
	v_pk_add_f32 v[20:21], v[20:21], v[28:29]
	v_cvt_pk_bf16_f32 v26, v34, v35
	v_lshlrev_b32_e32 v34, 16, v241
	v_and_b32_e32 v35, 0xffff0000, v241
	v_pk_add_f32 v[30:31], v[16:17], v[32:33]
	v_mul_f32_e32 v16, v21, v21
	v_mul_f32_e32 v17, v23, v23
	v_pk_add_f32 v[28:29], v[18:19], v[34:35]
	v_fmac_f32_e32 v16, v20, v20
	v_fmac_f32_e32 v17, v22, v22
	v_add_f32_e32 v16, v16, v17
	v_mul_f32_e32 v17, v31, v31
	v_mul_f32_e32 v18, v29, v29
	v_fmac_f32_e32 v17, v30, v30
	v_fmac_f32_e32 v18, v28, v28
	v_add_f32_e32 v17, v17, v18
	v_add_f32_e32 v16, v16, v17
	v_add_f32_e32 v19, v36, v16
	v_mov_b32_e32 v34, v19
	v_mov_b32_e32 v252, v19
	s_nop 1
	v_permlane16_swap_b32_e32 v34, v252
	v_lshl_add_u64 v[16:17], s[18:19], 0, v[98:99]
	v_lshl_add_u64 v[32:33], v[166:167], 1, v[16:17]
	v_cvt_pk_bf16_f32 v18, v20, v21
	v_cvt_pk_bf16_f32 v20, v30, v31
	s_waitcnt lgkmcnt(0)
	v_add_f32_e32 v16, v34, v252
	v_mov_b32_e32 v17, v16
	v_mov_b32_e32 v252, v16
	s_nop 1
	v_permlane32_swap_b32_e32 v17, v252
	v_cvt_pk_bf16_f32 v19, v22, v23
	v_cvt_pk_bf16_f32 v21, v28, v29
	global_store_dwordx4 v[32:33], v[24:27], off
	global_store_dwordx4 v[32:33], v[18:21], off offset:256
	s_and_saveexec_b64 s[10:11], s[40:41]
	s_cbranch_execz .LBB0_492
	s_waitcnt lgkmcnt(0)
	v_add_f32_e32 v18, v17, v252
	v_lshlrev_b64 v[16:17], 6, v[96:97]
	v_lshl_add_u64 v[16:17], s[0:1], 0, v[16:17]
	v_lshl_add_u64 v[16:17], s[28:29], 2, v[16:17]
	s_lshl_b32 s16, s51, 2
	v_lshl_add_u64 v[16:17], v[16:17], 0, s[16:17]
	global_store_dword v[16:17], v18, off
.LBB0_492:
	s_or_b64 exec, exec, s[10:11]
	v_lshlrev_b32_e32 v16, 16, v242
	s_waitcnt lgkmcnt(0)
	v_and_b32_e32 v17, 0xffff0000, v242
	v_lshlrev_b32_e32 v18, 16, v243
	v_and_b32_e32 v19, 0xffff0000, v243
	v_lshlrev_b32_e32 v20, 16, v244
	v_and_b32_e32 v21, 0xffff0000, v244
	v_pk_add_f32 v[12:13], v[12:13], v[16:17]
	v_pk_add_f32 v[14:15], v[14:15], v[18:19]
	v_pk_add_f32 v[18:19], v[8:9], v[20:21]
	v_cvt_pk_bf16_f32 v8, v12, v13
	v_mul_f32_e32 v13, v13, v13
	v_lshlrev_b32_e32 v22, 16, v245
	v_and_b32_e32 v23, 0xffff0000, v245
	v_fmac_f32_e32 v13, v12, v12
	v_mul_f32_e32 v12, v15, v15
	v_pk_add_f32 v[16:17], v[10:11], v[22:23]
	v_fmac_f32_e32 v12, v14, v14
	v_cvt_pk_bf16_f32 v9, v14, v15
	v_add_f32_e32 v12, v13, v12
	v_mul_f32_e32 v13, v19, v19
	v_mul_f32_e32 v14, v17, v17
	v_fmac_f32_e32 v13, v18, v18
	v_fmac_f32_e32 v14, v16, v16
	v_add_f32_e32 v13, v13, v14
	v_add_f32_e32 v20, v12, v13
	v_lshlrev_b32_e32 v12, 16, v246
	v_and_b32_e32 v13, 0xffff0000, v246
	v_lshlrev_b32_e32 v14, 16, v247
	v_and_b32_e32 v15, 0xffff0000, v247
	v_cvt_pk_bf16_f32 v11, v16, v17
	v_lshlrev_b32_e32 v16, 16, v248
	v_and_b32_e32 v17, 0xffff0000, v248
	v_pk_add_f32 v[6:7], v[6:7], v[14:15]
	v_pk_add_f32 v[4:5], v[4:5], v[12:13]
	v_cvt_pk_bf16_f32 v10, v18, v19
	v_lshlrev_b32_e32 v18, 16, v249
	v_and_b32_e32 v19, 0xffff0000, v249
	v_pk_add_f32 v[14:15], v[0:1], v[16:17]
	v_mul_f32_e32 v0, v5, v5
	v_mul_f32_e32 v1, v7, v7
	v_pk_add_f32 v[12:13], v[2:3], v[18:19]
	v_fmac_f32_e32 v0, v4, v4
	v_fmac_f32_e32 v1, v6, v6
	v_add_f32_e32 v0, v0, v1
	v_mul_f32_e32 v1, v15, v15
	v_mul_f32_e32 v2, v13, v13
	v_fmac_f32_e32 v1, v14, v14
	v_fmac_f32_e32 v2, v12, v12
	v_add_f32_e32 v1, v1, v2
	v_add_f32_e32 v0, v0, v1
	v_add_f32_e32 v3, v20, v0
	v_mov_b32_e32 v18, v3
	v_mov_b32_e32 v252, v3
	s_nop 1
	v_permlane16_swap_b32_e32 v18, v252
	v_lshl_add_u64 v[0:1], s[18:19], 0, v[94:95]
	v_lshl_add_u64 v[16:17], v[166:167], 1, v[0:1]
	v_cvt_pk_bf16_f32 v2, v4, v5
	v_cvt_pk_bf16_f32 v4, v14, v15
	s_waitcnt lgkmcnt(0)
	v_add_f32_e32 v0, v18, v252
	v_mov_b32_e32 v1, v0
	v_mov_b32_e32 v252, v0
	s_nop 1
	v_permlane32_swap_b32_e32 v1, v252
	v_cvt_pk_bf16_f32 v3, v6, v7
	v_cvt_pk_bf16_f32 v5, v12, v13
	global_store_dwordx4 v[16:17], v[8:11], off
	global_store_dwordx4 v[16:17], v[2:5], off offset:256
	s_and_saveexec_b64 s[10:11], s[40:41]
	s_cbranch_execz .LBB0_494
	s_waitcnt lgkmcnt(0)
	v_add_f32_e32 v2, v1, v252
	v_lshlrev_b64 v[0:1], 6, v[92:93]
	v_lshl_add_u64 v[0:1], s[0:1], 0, v[0:1]
	v_lshl_add_u64 v[0:1], s[28:29], 2, v[0:1]
	s_lshl_b32 s16, s51, 2
	v_lshl_add_u64 v[0:1], v[0:1], 0, s[16:17]
	global_store_dword v[0:1], v2, off

.LBB0_579:
	v_mov_b32_e32 v152, v155
	s_lshl_b32 s0, s11, 8
	v_ashrrev_i32_e32 v128, 31, v152
	v_lshrrev_b32_e32 v128, 30, v128
	v_add_u32_e32 v128, v152, v128
	s_waitcnt vmcnt(0)
	v_ashrrev_i32_e32 v170, 2, v128
	s_add_i32 s0, s0, s66
	v_and_b32_e32 v128, 0x3ffffffc, v128
	v_lshlrev_b32_e32 v130, 1, v170
	v_sub_u32_e32 v128, v152, v128
	v_and_b32_e32 v130, 0xffffff80, v130
	v_and_or_b32 v131, v170, 63, s0
	v_lshlrev_b32_e32 v128, 2, v128
	v_add_u32_e32 v130, v131, v130
	v_ashrrev_i32_e32 v129, 31, v128
	v_ashrrev_i32_e32 v131, 31, v130
	v_lshl_add_u64 v[128:129], v[128:129], 2, s[20:21]
	v_lshlrev_b64 v[160:161], 6, v[130:131]
	v_lshl_add_u64 v[160:161], v[128:129], 0, v[160:161]
	global_load_dwordx4 v[220:223], v[160:161], off offset:1024
	global_load_dwordx4 v[224:227], v[160:161], off offset:2048
	global_load_dwordx4 v[228:231], v[160:161], off offset:3072
	v_add_co_u32_e32 v216, vcc, 0x2000, v160
	v_addc_co_u32_e32 v217, vcc, 0, v161, vcc
	global_load_dwordx4 v[232:235], v[216:217], off
	global_load_dwordx4 v[236:239], v[216:217], off offset:1024
	global_load_dwordx4 v[240:243], v[216:217], off offset:2048
	global_load_dwordx4 v[244:247], v[216:217], off offset:3072
	global_load_dwordx4 v[160:163], v[160:161], off
	v_and_b32_e32 v154, 64, v219
	v_add_u32_e32 v159, 64, v154
	v_add_u32_e32 v130, 0x80, v130
	s_add_i32 s75, s10, s58
	s_add_i32 s64, s75, -2
	s_cmp_eq_u32 s64, 0
	s_mov_b64 s[38:39], -1
	s_mov_b64 s[16:17], 0
	s_mov_b64 s[10:11], 0
	s_waitcnt vmcnt(0)
	v_add_f32_e32 v131, v160, v161
	v_add_f32_e32 v156, v162, v163
	v_add_f32_e32 v131, v131, v156
	v_xor_b32_e32 v156, 1, v219
	v_cmp_lt_i32_e32 vcc, v156, v159
	s_nop 1
	v_cndmask_b32_e32 v156, v219, v156, vcc
	v_lshlrev_b32_e32 v160, 2, v156
	s_nop 1
	s_waitcnt lgkmcnt(0)
	v_add_f32_dpp v131, v131, v131 quad_perm:[1,0,3,2] row_mask:0xf bank_mask:0xf
	v_xor_b32_e32 v156, 2, v219
	v_cmp_lt_i32_e32 vcc, v156, v159
	s_nop 1
	v_cndmask_b32_e32 v156, v219, v156, vcc
	v_lshlrev_b32_e32 v158, 2, v156
	s_nop 1
	s_waitcnt lgkmcnt(0)
	v_add_f32_dpp v131, v131, v131 quad_perm:[2,3,0,1] row_mask:0xf bank_mask:0xf
	v_fmamk_f32 v131, v131, 0x3a800000, v200
	v_rsq_f32_e32 v156, v131
	v_add_u32_e32 v131, 16, v170
	v_lshlrev_b32_e32 v161, 1, v131
	v_and_b32_e32 v161, 0xffffff80, v161
	v_and_or_b32 v131, v131, 63, s0
	v_add_u32_e32 v162, v131, v161
	v_ashrrev_i32_e32 v163, 31, v162
	v_lshlrev_b64 v[162:163], 6, v[162:163]
	v_lshl_add_u64 v[162:163], v[128:129], 0, v[162:163]
	s_waitcnt vmcnt(0)
	v_add_f32_e32 v131, v220, v221
	v_add_f32_e32 v161, v222, v223
	v_add_f32_e32 v131, v131, v161
	s_nop 1
	s_waitcnt lgkmcnt(0)
	v_add_f32_dpp v131, v131, v131 quad_perm:[1,0,3,2] row_mask:0xf bank_mask:0xf
	s_nop 1
	s_waitcnt lgkmcnt(0)
	v_add_f32_dpp v131, v131, v131 quad_perm:[2,3,0,1] row_mask:0xf bank_mask:0xf
	v_fmamk_f32 v131, v131, 0x3a800000, v200
	v_rsq_f32_e32 v161, v131
	v_add_u32_e32 v131, 32, v170
	v_lshlrev_b32_e32 v162, 1, v131
	v_and_b32_e32 v162, 0xffffff80, v162
	v_and_or_b32 v131, v131, 63, s0
	v_add_u32_e32 v162, v131, v162
	v_ashrrev_i32_e32 v163, 31, v162
	v_lshlrev_b64 v[162:163], 6, v[162:163]
	v_lshl_add_u64 v[162:163], v[128:129], 0, v[162:163]
	s_waitcnt vmcnt(0)
	v_add_f32_e32 v131, v224, v225
	v_add_f32_e32 v162, v226, v227
	v_add_f32_e32 v131, v131, v162
	s_nop 1
	s_waitcnt lgkmcnt(0)
	v_add_f32_dpp v131, v131, v131 quad_perm:[1,0,3,2] row_mask:0xf bank_mask:0xf
	s_nop 1
	s_waitcnt lgkmcnt(0)
	v_add_f32_dpp v131, v131, v131 quad_perm:[2,3,0,1] row_mask:0xf bank_mask:0xf
	v_fmamk_f32 v131, v131, 0x3a800000, v200
	v_rsq_f32_e32 v163, v131
	v_add_u32_e32 v131, 48, v170
	v_lshlrev_b32_e32 v162, 1, v131
	v_and_b32_e32 v162, 0xffffff80, v162
	v_and_or_b32 v131, v131, 63, s0
	v_add_u32_e32 v164, v131, v162
	v_ashrrev_i32_e32 v165, 31, v164
	v_lshlrev_b64 v[164:165], 6, v[164:165]
	v_lshl_add_u64 v[164:165], v[128:129], 0, v[164:165]
	s_waitcnt vmcnt(0)
	v_add_f32_e32 v131, v228, v229
	v_add_f32_e32 v162, v230, v231
	v_add_f32_e32 v131, v131, v162
	s_nop 1
	s_waitcnt lgkmcnt(0)
	v_add_f32_dpp v131, v131, v131 quad_perm:[1,0,3,2] row_mask:0xf bank_mask:0xf
	s_nop 1
	s_waitcnt lgkmcnt(0)
	v_add_f32_dpp v131, v131, v131 quad_perm:[2,3,0,1] row_mask:0xf bank_mask:0xf
	v_fmamk_f32 v131, v131, 0x3a800000, v200
	v_rsq_f32_e32 v165, v131
	v_ashrrev_i32_e32 v131, 31, v130
	v_lshlrev_b64 v[130:131], 6, v[130:131]
	v_lshl_add_u64 v[130:131], v[128:129], 0, v[130:131]
	s_waitcnt vmcnt(0)
	v_add_f32_e32 v130, v232, v233
	v_add_f32_e32 v131, v234, v235
	v_add_f32_e32 v130, v130, v131
	s_nop 1
	s_waitcnt lgkmcnt(0)
	v_add_f32_dpp v130, v130, v130 quad_perm:[1,0,3,2] row_mask:0xf bank_mask:0xf
	s_nop 1
	s_waitcnt lgkmcnt(0)
	v_add_f32_dpp v130, v130, v130 quad_perm:[2,3,0,1] row_mask:0xf bank_mask:0xf
	v_fmamk_f32 v130, v130, 0x3a800000, v200
	v_rsq_f32_e32 v171, v130
	v_add_u32_e32 v130, 0x50, v170
	v_lshlrev_b32_e32 v131, 1, v130
	v_and_b32_e32 v131, 0xffffff80, v131
	v_and_or_b32 v130, v130, 63, s0
	v_add_u32_e32 v130, v130, v131
	v_ashrrev_i32_e32 v131, 31, v130
	v_lshlrev_b64 v[130:131], 6, v[130:131]
	v_lshl_add_u64 v[130:131], v[128:129], 0, v[130:131]
	s_waitcnt vmcnt(0)
	v_add_f32_e32 v130, v236, v237
	v_add_f32_e32 v131, v238, v239
	v_add_f32_e32 v130, v130, v131
	s_nop 1
	s_waitcnt lgkmcnt(0)
	v_add_f32_dpp v130, v130, v130 quad_perm:[1,0,3,2] row_mask:0xf bank_mask:0xf
	s_nop 1
	s_waitcnt lgkmcnt(0)
	v_add_f32_dpp v130, v130, v130 quad_perm:[2,3,0,1] row_mask:0xf bank_mask:0xf
	v_fmamk_f32 v130, v130, 0x3a800000, v200
	v_rsq_f32_e32 v172, v130
	v_add_u32_e32 v130, 0x60, v170
	v_lshlrev_b32_e32 v131, 1, v130
	v_and_b32_e32 v131, 0xffffff80, v131
	v_and_or_b32 v130, v130, 63, s0
	v_add_u32_e32 v130, v130, v131
	v_ashrrev_i32_e32 v131, 31, v130
	v_lshlrev_b64 v[130:131], 6, v[130:131]
	v_lshl_add_u64 v[130:131], v[128:129], 0, v[130:131]
	s_waitcnt vmcnt(0)
	v_add_f32_e32 v130, v240, v241
	v_add_f32_e32 v131, v242, v243
	v_add_f32_e32 v130, v130, v131
	s_nop 1
	s_waitcnt lgkmcnt(0)
	v_add_f32_dpp v130, v130, v130 quad_perm:[1,0,3,2] row_mask:0xf bank_mask:0xf
	s_nop 1
	s_waitcnt lgkmcnt(0)
	v_add_f32_dpp v130, v130, v130 quad_perm:[2,3,0,1] row_mask:0xf bank_mask:0xf
	v_fmamk_f32 v130, v130, 0x3a800000, v200
	v_rsq_f32_e32 v166, v130
	v_add_u32_e32 v130, 0x70, v170
	v_lshlrev_b32_e32 v131, 1, v130
	v_and_b32_e32 v131, 0xffffff80, v131
	v_and_or_b32 v130, v130, 63, s0
	v_add_u32_e32 v130, v130, v131
	v_ashrrev_i32_e32 v131, 31, v130
	v_lshlrev_b64 v[130:131], 6, v[130:131]
	v_lshl_add_u64 v[128:129], v[128:129], 0, v[130:131]
	s_waitcnt vmcnt(0)
	v_add_f32_e32 v128, v244, v245
	v_add_f32_e32 v129, v246, v247
	v_add_f32_e32 v128, v128, v129
	s_nop 1
	v_or_b32_e32 v130, s0, v141
	s_cselect_b64 s[0:1], -1, 0
	s_cmp_lt_i32 s75, 1
	s_waitcnt lgkmcnt(0)
	v_add_f32_dpp v128, v128, v128 quad_perm:[1,0,3,2] row_mask:0xf bank_mask:0xf
	s_nop 1
	s_waitcnt lgkmcnt(0)
	v_add_f32_dpp v128, v128, v128 quad_perm:[2,3,0,1] row_mask:0xf bank_mask:0xf
	v_fmamk_f32 v128, v128, 0x3a800000, v200
	v_rsq_f32_e32 v128, v128
	v_lshlrev_b32_e32 v129, 2, v152
	v_and_or_b32 v129, v129, 60, v154
	v_lshlrev_b32_e32 v129, 2, v129
	ds_bpermute_b32 v164, v129, v156
	ds_bpermute_b32 v162, v129, v161
	ds_bpermute_b32 v160, v129, v163
	ds_bpermute_b32 v158, v129, v165
	ds_bpermute_b32 v156, v129, v171
	ds_bpermute_b32 v154, v129, v172
	ds_bpermute_b32 v152, v129, v166
	ds_bpermute_b32 v128, v129, v128
	v_xor_b32_e32 v129, 16, v219
	v_xor_b32_e32 v161, 32, v219
	v_cmp_lt_i32_e64 s[44:45], v129, v159
	v_cmp_lt_i32_e64 s[46:47], v161, v159
	s_cbranch_scc1 .LBB0_585
	s_cmp_eq_u32 s75, 1
	s_mov_b64 s[10:11], -1
	s_cbranch_scc0 .LBB0_584
	s_andn2_b64 vcc, exec, s[94:95]
	s_cbranch_vccnz .LBB0_583
	v_ashrrev_i32_e32 v131, 31, v130
	v_lshlrev_b64 v[166:167], 8, v[130:131]
	v_lshl_add_u64 v[194:195], v[142:143], 0, v[166:167]
	global_load_dwordx4 v[170:173], v[194:195], off offset:32
	global_load_dwordx4 v[174:177], v[194:195], off offset:48
	global_load_dwordx4 v[166:169], v[194:195], off
	s_nop 0
	global_load_dwordx4 v[194:197], v[194:195], off offset:16
	s_waitcnt lgkmcnt(7)
	v_pk_mul_f32 v[202:203], v[118:119], v[164:165] op_sel_hi:[1,0]
	v_pk_mul_f32 v[178:179], v[126:127], v[164:165] op_sel_hi:[1,0]
	v_pk_mul_f32 v[206:207], v[116:117], v[164:165] op_sel_hi:[1,0]
	v_pk_mul_f32 v[198:199], v[124:125], v[164:165] op_sel_hi:[1,0]
	s_waitcnt vmcnt(1)
	v_mov_b32_e32 v212, v167
	s_waitcnt vmcnt(0)
	v_mov_b32_e32 v208, v195
	v_mov_b32_e32 v209, v197
	v_pk_mul_f32 v[210:211], v[202:203], v[208:209]
	v_mov_b32_e32 v213, v169
	v_mov_b32_e32 v195, v196
	v_mov_b32_e32 v167, v168
	v_pk_mul_f32 v[214:215], v[206:207], v[212:213]
	v_pk_fma_f32 v[196:197], v[178:179], v[194:195], v[210:211] neg_lo:[0,0,1] neg_hi:[0,0,1]
	v_pk_mul_f32 v[168:169], v[202:203], v[194:195]
	v_pk_mul_f32 v[194:195], v[206:207], v[166:167]
	v_pk_fma_f32 v[210:211], v[198:199], v[166:167], v[214:215] neg_lo:[0,0,1] neg_hi:[0,0,1]
	v_pk_fma_f32 v[166:167], v[178:179], v[208:209], v[168:169]
	v_pk_fma_f32 v[168:169], v[198:199], v[212:213], v[194:195]
	v_pk_mul_f32 v[198:199], v[114:115], v[164:165] op_sel_hi:[1,0]
	v_pk_mul_f32 v[202:203], v[112:113], v[164:165] op_sel_hi:[1,0]
	v_mov_b32_e32 v206, v175
	v_mov_b32_e32 v207, v177
	v_mov_b32_e32 v212, v171
	v_mov_b32_e32 v213, v173
	v_pk_mul_f32 v[178:179], v[122:123], v[164:165] op_sel_hi:[1,0]
	v_pk_mul_f32 v[194:195], v[120:121], v[164:165] op_sel_hi:[1,0]
	v_pk_mul_f32 v[208:209], v[198:199], v[206:207]
	v_pk_mul_f32 v[214:215], v[202:203], v[212:213]
	v_mov_b32_e32 v175, v176
	v_mov_b32_e32 v171, v172
	v_pk_fma_f32 v[176:177], v[178:179], v[174:175], v[208:209] neg_lo:[0,0,1] neg_hi:[0,0,1]
	v_pk_fma_f32 v[172:173], v[194:195], v[170:171], v[214:215] neg_lo:[0,0,1] neg_hi:[0,0,1]
	v_pk_mul_f32 v[174:175], v[198:199], v[174:175]
	v_pk_mul_f32 v[170:171], v[202:203], v[170:171]
	v_cvt_pk_bf16_f32 v172, v172, v173
	v_cvt_pk_bf16_f32 v173, v176, v177
	v_lshlrev_b64 v[176:177], 7, v[130:131]
	v_pk_fma_f32 v[174:175], v[178:179], v[206:207], v[174:175]
	v_pk_fma_f32 v[178:179], v[194:195], v[212:213], v[170:171]
	v_cvt_pk_bf16_f32 v170, v210, v211
	v_cvt_pk_bf16_f32 v171, v196, v197
	v_lshl_add_u64 v[176:177], v[144:145], 0, v[176:177]
	global_store_dwordx4 v[176:177], v[170:173], off
	v_cvt_pk_bf16_f32 v168, v168, v169
	v_cvt_pk_bf16_f32 v169, v166, v167
	v_cvt_pk_bf16_f32 v170, v178, v179
	v_cvt_pk_bf16_f32 v171, v174, v175
	global_store_dwordx4 v[176:177], v[168:171], off offset:64

.LBB0_847:
	v_mov_b32_e32 v145, v165
	v_and_b32_e32 v157, 64, v219
	v_lshrrev_b32_e32 v146, 31, v145
	v_add_u32_e32 v148, v145, v146
	v_and_b32_e32 v146, 0x3ffffffe, v148
	v_sub_u32_e32 v146, v145, v146
	v_lshlrev_b32_e32 v146, 2, v146
	v_ashrrev_i32_e32 v147, 31, v146
	v_lshl_add_u64 v[150:151], v[146:147], 2, s[18:19]
	v_xor_b32_e32 v146, 1, v219
	v_add_u32_e32 v147, 64, v157
	s_lshl_b32 s0, s34, 8
	v_cmp_lt_i32_e32 vcc, v146, v147
	s_add_i32 s0, s0, s52
	v_ashrrev_i32_e32 v156, 1, v148
	v_cndmask_b32_e32 v146, v219, v146, vcc
	v_lshlrev_b32_e32 v158, 2, v146
	v_and_b32_e32 v146, 0xffffff80, v148
	v_and_or_b32 v147, v156, 63, s0
	v_add_u32_e32 v152, v147, v146
	v_ashrrev_i32_e32 v153, 31, v152
	v_lshlrev_b64 v[146:147], 5, v[152:153]
	v_lshl_add_u64 v[146:147], v[150:151], 0, v[146:147]
	v_add_co_u32_e32 v178, vcc, 0x1000, v146
	v_addc_co_u32_e32 v179, vcc, 0, v147, vcc
	global_load_dwordx4 v[160:163], v[146:147], off offset:1024
	global_load_dwordx4 v[174:177], v[178:179], off
	global_load_dwordx4 v[194:197], v[178:179], off offset:1024
	global_load_dwordx4 v[146:149], v[146:147], off
	v_and_b32_e32 v145, 15, v145
	v_lshlrev_b32_e32 v145, 3, v145
	v_lshl_or_b32 v145, v157, 2, v145
	s_cmp_gt_i32 s62, 3
	v_or_b32_e32 v144, s0, v137
	s_cselect_b64 s[34:35], -1, 0
	s_mov_b64 s[16:17], -1
	v_lshlrev_b32_e32 v180, 1, v136
	s_waitcnt vmcnt(0)
	v_mov_b32_e32 v154, v147
	v_mov_b32_e32 v155, v148
	v_mov_b32_e32 v147, v149
	v_pk_add_f32 v[146:147], v[154:155], v[146:147]
	s_nop 0
	v_add_f32_e32 v146, v146, v147
	s_nop 1
	s_waitcnt lgkmcnt(0)
	v_add_f32_dpp v146, v146, v146 quad_perm:[1,0,3,2] row_mask:0xf bank_mask:0xf
	v_fmamk_f32 v146, v146, 0x3b2aaaab, v200
	v_rsq_f32_e32 v153, v146
	v_add_u32_e32 v146, 32, v156
	v_lshlrev_b32_e32 v147, 1, v146
	v_and_b32_e32 v147, 0xffffff80, v147
	v_and_or_b32 v146, v146, 63, s0
	v_add_u32_e32 v146, v146, v147
	v_ashrrev_i32_e32 v147, 31, v146
	v_lshlrev_b64 v[146:147], 5, v[146:147]
	v_lshl_add_u64 v[146:147], v[150:151], 0, v[146:147]
	ds_bpermute_b32 v173, v145, v153 offset:128
	s_waitcnt vmcnt(0)
	v_mov_b32_e32 v146, v160
	v_mov_b32_e32 v147, v161
	v_mov_b32_e32 v148, v162
	v_mov_b32_e32 v149, v163
	v_add_f32_e32 v146, v146, v147
	v_add_f32_e32 v147, v148, v149
	v_add_f32_e32 v146, v146, v147
	s_nop 1
	s_waitcnt lgkmcnt(0)
	v_add_f32_dpp v146, v146, v146 quad_perm:[1,0,3,2] row_mask:0xf bank_mask:0xf
	v_fmamk_f32 v146, v146, 0x3b2aaaab, v200
	v_rsq_f32_e32 v154, v146
	v_add_u32_e32 v146, 0x80, v152
	v_ashrrev_i32_e32 v147, 31, v146
	v_lshlrev_b64 v[146:147], 5, v[146:147]
	v_lshl_add_u64 v[146:147], v[150:151], 0, v[146:147]
	ds_bpermute_b32 v172, v145, v154
	ds_bpermute_b32 v171, v145, v154 offset:128
	s_waitcnt vmcnt(0)
	v_mov_b32_e32 v146, v174
	v_mov_b32_e32 v147, v175
	v_mov_b32_e32 v148, v176
	v_mov_b32_e32 v149, v177
	v_add_f32_e32 v146, v146, v147
	v_add_f32_e32 v147, v148, v149
	v_add_f32_e32 v146, v146, v147
	s_nop 1
	s_waitcnt lgkmcnt(0)
	v_add_f32_dpp v146, v146, v146 quad_perm:[1,0,3,2] row_mask:0xf bank_mask:0xf
	v_fmamk_f32 v146, v146, 0x3b2aaaab, v200
	v_rsq_f32_e32 v152, v146
	v_add_u32_e32 v146, 0x60, v156
	v_lshlrev_b32_e32 v147, 1, v146
	v_and_b32_e32 v147, 0xffffff80, v147
	v_and_or_b32 v146, v146, 63, s0
	v_add_u32_e32 v146, v146, v147
	v_ashrrev_i32_e32 v147, 31, v146
	v_lshlrev_b64 v[146:147], 5, v[146:147]
	v_lshl_add_u64 v[146:147], v[150:151], 0, v[146:147]
	ds_bpermute_b32 v170, v145, v152
	ds_bpermute_b32 v169, v145, v152 offset:128
	s_lshl_b32 s0, s62, 2
	s_add_i32 s0, s58, s0
	s_mulk_i32 s0, 0xc0
	s_ashr_i32 s1, s0, 31
	s_cmp_lt_i32 s62, 4
	s_waitcnt vmcnt(0)
	v_mov_b32_e32 v146, v194
	v_mov_b32_e32 v147, v195
	v_mov_b32_e32 v148, v196
	v_mov_b32_e32 v149, v197
	v_add_f32_e32 v146, v146, v147
	v_add_f32_e32 v147, v148, v149
	v_add_f32_e32 v146, v146, v147
	s_nop 1
	s_waitcnt lgkmcnt(0)
	v_add_f32_dpp v146, v146, v146 quad_perm:[1,0,3,2] row_mask:0xf bank_mask:0xf
	v_fmamk_f32 v146, v146, 0x3b2aaaab, v200
	v_rsq_f32_e32 v146, v146
	ds_bpermute_b32 v147, v145, v153
	ds_bpermute_b32 v168, v145, v146
	ds_bpermute_b32 v167, v145, v146 offset:128
	s_waitcnt lgkmcnt(2)
	v_mul_f32_e32 v146, 0x3dd53b94, v147
	v_mov_b32_e32 v147, v146
	v_pk_mul_f32 v[126:127], v[126:127], v[146:147] op_sel_hi:[1,0]
	v_pk_mul_f32 v[124:125], v[124:125], v[146:147] op_sel_hi:[1,0]
	v_ashrrev_i32_e32 v145, 31, v144
	v_pk_mul_f32 v[116:117], v[116:117], v[146:147]
	v_pk_mul_f32 v[120:121], v[120:121], v[146:147]
	v_pk_mul_f32 v[112:113], v[112:113], v[146:147]
	s_cbranch_scc1 .LBB0_849
	v_lshlrev_b64 v[148:149], 8, v[144:145]
	v_lshl_add_u64 v[152:153], v[138:139], 0, v[148:149]
	global_load_dwordx4 v[156:159], v[152:153], off offset:32
	global_load_dwordx4 v[174:177], v[152:153], off offset:48
	global_load_dwordx4 v[148:151], v[152:153], off
	global_load_dwordx4 v[160:163], v[152:153], off offset:16
	v_mov_b32_e32 v147, v146
	v_pk_mul_f32 v[178:179], v[118:119], v[146:147]
	s_mov_b64 s[16:17], 0
	s_waitcnt vmcnt(3)
	v_mov_b32_e32 v198, v157
	v_mov_b32_e32 v199, v159
	s_waitcnt vmcnt(1)
	v_mov_b32_e32 v196, v149
	s_waitcnt vmcnt(0)
	v_mov_b32_e32 v194, v161
	v_mov_b32_e32 v195, v163
	v_pk_mul_f32 v[152:153], v[178:179], v[194:195]
	v_mov_b32_e32 v197, v151
	v_mov_b32_e32 v161, v162
	v_mov_b32_e32 v149, v150
	v_pk_mul_f32 v[154:155], v[116:117], v[196:197]
	v_pk_fma_f32 v[152:153], v[126:127], v[160:161], v[152:153] neg_lo:[0,0,1] neg_hi:[0,0,1]
	v_pk_mul_f32 v[150:151], v[178:179], v[160:161]
	v_pk_mul_f32 v[160:161], v[116:117], v[148:149]
	v_pk_fma_f32 v[154:155], v[124:125], v[148:149], v[154:155] neg_lo:[0,0,1] neg_hi:[0,0,1]
	v_pk_fma_f32 v[148:149], v[126:127], v[194:195], v[150:151]
	v_pk_fma_f32 v[150:151], v[124:125], v[196:197], v[160:161]
	v_pk_mul_f32 v[194:195], v[114:115], v[146:147]
	v_mov_b32_e32 v196, v175
	v_mov_b32_e32 v197, v177
	v_pk_mul_f32 v[178:179], v[122:123], v[146:147]
	v_pk_mul_f32 v[160:161], v[194:195], v[196:197]
	v_mov_b32_e32 v175, v176
	v_mov_b32_e32 v157, v158
	v_pk_mul_f32 v[162:163], v[112:113], v[198:199]
	v_pk_fma_f32 v[160:161], v[178:179], v[174:175], v[160:161] neg_lo:[0,0,1] neg_hi:[0,0,1]
	v_pk_mul_f32 v[158:159], v[194:195], v[174:175]
	v_pk_mul_f32 v[174:175], v[112:113], v[156:157]
	v_pk_fma_f32 v[162:163], v[120:121], v[156:157], v[162:163] neg_lo:[0,0,1] neg_hi:[0,0,1]
	v_pk_fma_f32 v[156:157], v[178:179], v[196:197], v[158:159]
	v_pk_fma_f32 v[158:159], v[120:121], v[198:199], v[174:175]
	v_mov_b64_e32 v[174:175], s[20:21]
	v_mad_i64_i32 v[174:175], s[10:11], v144, s50, v[174:175]
	v_lshl_add_u64 v[174:175], s[0:1], 1, v[174:175]
	v_lshl_add_u64 v[178:179], v[174:175], 0, v[180:181]
	v_cvt_pk_bf16_f32 v174, v154, v155
	v_cvt_pk_bf16_f32 v175, v152, v153
	v_cvt_pk_bf16_f32 v176, v162, v163
	v_cvt_pk_bf16_f32 v177, v160, v161
	v_cvt_pk_bf16_f32 v150, v150, v151
	v_cvt_pk_bf16_f32 v151, v148, v149
	v_cvt_pk_bf16_f32 v152, v158, v159
	v_cvt_pk_bf16_f32 v153, v156, v157
	global_store_dwordx4 v[178:179], v[174:177], off offset:256
	global_store_dwordx4 v[178:179], v[150:153], off offset:320

.LBB0_960:
	v_and_b32_e32 v65, 64, v219
	v_xor_b32_e32 v64, 32, v219
	v_add_u32_e32 v65, 64, v65
	v_cmp_lt_i32_e32 vcc, v64, v65
	v_lshlrev_b32_e32 v180, 1, v198
	s_lshl_b32 s64, s52, 1
	v_cndmask_b32_e32 v64, v219, v64, vcc
	v_lshlrev_b32_e32 v205, 2, v64
	v_mov_b32_e32 v64, v206
	v_mov_b32_e32 v251, v206
	s_nop 1
	v_permlane32_swap_b32_e32 v64, v251
	v_readlane_b32 s58, v255, 3
	v_readlane_b32 s60, v253, 16
	s_mov_b32 s36, 2
	s_mov_b32 s40, 63
	s_waitcnt lgkmcnt(0)
	v_add_f32_e32 v66, v64, v251
	v_div_scale_f32 v67, s[0:1], v66, v66, 1.0
	v_rcp_f32_e32 v68, v67
	v_div_scale_f32 v69, vcc, 1.0, v66, 1.0
	v_lshlrev_b64 v[64:65], 11, v[194:195]
	v_fma_f32 v70, -v67, v68, 1.0
	v_fmac_f32_e32 v68, v70, v68
	v_mul_f32_e32 v70, v69, v68
	v_fma_f32 v71, -v67, v70, v69
	v_fmac_f32_e32 v70, v71, v68
	v_fma_f32 v67, -v67, v70, v69
	v_div_fmas_f32 v67, v67, v68, v70
	v_div_fixup_f32 v66, v67, v66, 1.0
	v_pk_mul_f32 v[48:49], v[48:49], v[66:67] op_sel_hi:[1,0]
	v_pk_mul_f32 v[50:51], v[50:51], v[66:67] op_sel_hi:[1,0]
	v_pk_mul_f32 v[32:33], v[32:33], v[66:67] op_sel_hi:[1,0]
	v_pk_mul_f32 v[34:35], v[34:35], v[66:67] op_sel_hi:[1,0]
	v_pk_mul_f32 v[16:17], v[16:17], v[66:67] op_sel_hi:[1,0]
	v_pk_mul_f32 v[18:19], v[18:19], v[66:67] op_sel_hi:[1,0]
	v_pk_mul_f32 v[0:1], v[0:1], v[66:67] op_sel_hi:[1,0]
	v_pk_mul_f32 v[2:3], v[2:3], v[66:67] op_sel_hi:[1,0]
	v_lshl_add_u64 v[64:65], s[14:15], 0, v[64:65]
	s_lshl_b32 s0, s56, 1
	s_mov_b32 s1, s65
	v_cvt_pk_bf16_f32 v48, v48, v49
	v_cvt_pk_bf16_f32 v49, v50, v51
	v_pk_mul_f32 v[50:51], v[52:53], v[66:67] op_sel_hi:[1,0]
	v_pk_mul_f32 v[52:53], v[54:55], v[66:67] op_sel_hi:[1,0]
	v_cvt_pk_bf16_f32 v32, v32, v33
	v_cvt_pk_bf16_f32 v33, v34, v35
	v_pk_mul_f32 v[34:35], v[36:37], v[66:67] op_sel_hi:[1,0]
	v_pk_mul_f32 v[36:37], v[38:39], v[66:67] op_sel_hi:[1,0]
	v_cvt_pk_bf16_f32 v16, v16, v17
	v_cvt_pk_bf16_f32 v17, v18, v19
	v_pk_mul_f32 v[18:19], v[20:21], v[66:67] op_sel_hi:[1,0]
	v_pk_mul_f32 v[20:21], v[22:23], v[66:67] op_sel_hi:[1,0]
	v_cvt_pk_bf16_f32 v0, v0, v1
	v_cvt_pk_bf16_f32 v1, v2, v3
	v_pk_mul_f32 v[2:3], v[4:5], v[66:67] op_sel_hi:[1,0]
	v_pk_mul_f32 v[4:5], v[6:7], v[66:67] op_sel_hi:[1,0]
	v_lshl_add_u64 v[64:65], v[64:65], 0, s[0:1]
	v_cvt_pk_bf16_f32 v50, v50, v51
	v_cvt_pk_bf16_f32 v51, v52, v53
	v_cvt_pk_bf16_f32 v34, v34, v35
	v_cvt_pk_bf16_f32 v35, v36, v37
	v_cvt_pk_bf16_f32 v18, v18, v19
	v_cvt_pk_bf16_f32 v19, v20, v21
	v_cvt_pk_bf16_f32 v2, v2, v3
	v_cvt_pk_bf16_f32 v3, v4, v5
	v_lshl_add_u64 v[64:65], v[64:65], 0, v[180:181]
	v_permlane32_swap_b32_e32 v48, v50
	v_permlane32_swap_b32_e32 v49, v51
	v_permlane32_swap_b32_e32 v32, v34
	v_permlane32_swap_b32_e32 v33, v35
	v_permlane32_swap_b32_e32 v16, v18
	v_permlane32_swap_b32_e32 v17, v19
	v_permlane32_swap_b32_e32 v0, v2
	v_permlane32_swap_b32_e32 v1, v3
	global_store_dwordx4 v[64:65], v[48:51], off
	global_store_dwordx4 v[64:65], v[32:35], off offset:64
	global_store_dwordx4 v[64:65], v[16:19], off offset:128
	v_pk_mul_f32 v[48:49], v[56:57], v[66:67] op_sel_hi:[1,0]
	v_pk_mul_f32 v[50:51], v[58:59], v[66:67] op_sel_hi:[1,0]
	v_pk_mul_f32 v[32:33], v[40:41], v[66:67] op_sel_hi:[1,0]
	v_pk_mul_f32 v[34:35], v[42:43], v[66:67] op_sel_hi:[1,0]
	v_pk_mul_f32 v[16:17], v[24:25], v[66:67] op_sel_hi:[1,0]
	v_pk_mul_f32 v[18:19], v[26:27], v[66:67] op_sel_hi:[1,0]
	global_store_dwordx4 v[64:65], v[0:3], off offset:192
	v_cvt_pk_bf16_f32 v48, v48, v49
	v_cvt_pk_bf16_f32 v49, v50, v51
	v_pk_mul_f32 v[0:1], v[8:9], v[66:67] op_sel_hi:[1,0]
	v_pk_mul_f32 v[2:3], v[10:11], v[66:67] op_sel_hi:[1,0]
	v_pk_mul_f32 v[50:51], v[60:61], v[66:67] op_sel_hi:[1,0]
	v_pk_mul_f32 v[52:53], v[62:63], v[66:67] op_sel_hi:[1,0]
	v_cvt_pk_bf16_f32 v32, v32, v33
	v_cvt_pk_bf16_f32 v33, v34, v35
	v_pk_mul_f32 v[34:35], v[44:45], v[66:67] op_sel_hi:[1,0]
	v_pk_mul_f32 v[36:37], v[46:47], v[66:67] op_sel_hi:[1,0]
	v_cvt_pk_bf16_f32 v16, v16, v17
	v_cvt_pk_bf16_f32 v17, v18, v19
	v_pk_mul_f32 v[18:19], v[28:29], v[66:67] op_sel_hi:[1,0]
	v_pk_mul_f32 v[20:21], v[30:31], v[66:67] op_sel_hi:[1,0]
	v_cvt_pk_bf16_f32 v0, v0, v1
	v_cvt_pk_bf16_f32 v1, v2, v3
	v_pk_mul_f32 v[2:3], v[12:13], v[66:67] op_sel_hi:[1,0]
	v_pk_mul_f32 v[4:5], v[14:15], v[66:67] op_sel_hi:[1,0]
	v_cvt_pk_bf16_f32 v50, v50, v51
	v_cvt_pk_bf16_f32 v51, v52, v53
	v_cvt_pk_bf16_f32 v34, v34, v35
	v_cvt_pk_bf16_f32 v35, v36, v37
	v_cvt_pk_bf16_f32 v18, v18, v19
	v_cvt_pk_bf16_f32 v19, v20, v21
	v_cvt_pk_bf16_f32 v2, v2, v3
	v_cvt_pk_bf16_f32 v3, v4, v5
	v_permlane32_swap_b32_e32 v48, v50
	v_permlane32_swap_b32_e32 v49, v51
	v_permlane32_swap_b32_e32 v32, v34
	v_permlane32_swap_b32_e32 v33, v35
	v_permlane32_swap_b32_e32 v16, v18
	v_permlane32_swap_b32_e32 v17, v19
	v_permlane32_swap_b32_e32 v0, v2
	v_permlane32_swap_b32_e32 v1, v3
	v_mov_b32_e32 v195, v218
	global_store_dwordx4 v[64:65], v[48:51], off offset:32
	global_store_dwordx4 v[64:65], v[32:35], off offset:96
	global_store_dwordx4 v[64:65], v[16:19], off offset:160
	global_store_dwordx4 v[64:65], v[0:3], off offset:224
	v_mov_b32_e32 v48, v181
	v_readfirstlane_b32 s1, v195
	s_ashr_i32 s1, s1, 1
	s_andn2_b32 s1, s1, 31
	v_and_b32_e32 v20, 31, v195
	s_add_i32 s1, s1, s49
	v_or_b32_e32 v198, s1, v20
	v_ashrrev_i32_e32 v199, 31, v198
	v_lshl_add_u64 v[196:197], s[30:31], 0, v[198:199]
	v_mov_b64_e32 v[0:1], s[8:9]
	v_mad_u64_u32 v[0:1], s[10:11], v196, s50, v[0:1]
	v_bfe_u32 v21, v195, 5, 1
	v_mad_i32_i24 v1, v197, s50, v1
	v_lshl_add_u64 v[0:1], v[0:1], 0, s[64:65]
	v_lshlrev_b32_e32 v180, 4, v21
	v_lshl_add_u64 v[0:1], v[0:1], 0, v[180:181]
	global_load_dwordx4 v[112:115], v[0:1], off
	global_load_dwordx4 v[116:119], v[0:1], off offset:32
	global_load_dwordx4 v[120:123], v[0:1], off offset:64
	global_load_dwordx4 v[124:127], v[0:1], off offset:96
	global_load_dwordx4 v[128:131], v[0:1], off offset:128
	global_load_dwordx4 v[132:135], v[0:1], off offset:160
	global_load_dwordx4 v[136:139], v[0:1], off offset:192
	global_load_dwordx4 v[140:143], v[0:1], off offset:224
	global_load_dwordx4 v[144:147], v[0:1], off offset:256
	global_load_dwordx4 v[148:151], v[0:1], off offset:288
	global_load_dwordx4 v[152:155], v[0:1], off offset:320
	global_load_dwordx4 v[156:159], v[0:1], off offset:352
	v_mov_b32_e32 v0, v195
	v_mov_b32_e32 v22, v195
	v_lshrrev_b32_e32 v12, 3, v0
	v_lshlrev_b32_e32 v0, 4, v0
	v_and_b32_e32 v13, 0x70, v0
	v_lshl_or_b32 v4, v12, 11, v13
	v_lshl_or_b32 v8, v12, 7, v13
	global_load_dwordx4 v[0:3], v4, s[22:23]
	s_nop 0
	global_load_dwordx4 v[4:7], v4, s[22:23] offset:128
	s_nop 0
	global_load_dwordx4 v[8:11], v8, s[26:27]
	v_lshl_or_b32 v16, v12, 12, v13
	global_load_dwordx4 v[12:15], v16, s[24:25]
	s_nop 0
	global_load_dwordx4 v[16:19], v16, s[34:35]
	s_addk_i32 s49, 0x100
	v_lshrrev_b32_e32 v23, 3, v22
	v_lshlrev_b32_e32 v25, 4, v22
	v_mul_lo_u32 v24, v23, s51
	v_and_b32_e32 v26, 0x70, v25
	v_mul_lo_u32 v23, v23, s5
	v_lshlrev_b32_e32 v22, 3, v22
	v_add3_u32 v24, 0, v24, v26
	v_and_b32_e32 v25, 0x60, v25
	v_and_b32_e32 v22, 8, v22
	s_waitcnt vmcnt(4)
	ds_write_b128 v24, v[0:3]
	s_waitcnt vmcnt(3)
	ds_write_b128 v24, v[4:7] offset:128
	s_waitcnt vmcnt(2)
	ds_write_b128 v24, v[8:11] offset:256
	v_add_u32_e32 v0, 0, v23
	v_add3_u32 v0, v0, v25, v22
	v_add_u32_e32 v1, 0x6000, v0
	v_add_u32_e32 v0, 0x8800, v0
	s_waitcnt vmcnt(1)
	ds_write2_b64 v1, v[12:13], v[14:15] offset0:128 offset1:130
	s_waitcnt vmcnt(0)
	ds_write2_b64 v0, v[16:17], v[18:19] offset1:2
	v_mad_u32_u24 v0, v20, s51, 0
	v_lshlrev_b32_e32 v1, 8, v20
	v_mov_b32_e32 v2, s63
	v_sub_u32_e32 v1, v0, v1
	v_mad_u32_u24 v2, v20, s5, v2
	v_mov_b32_e32 v49, v181
	v_mov_b32_e32 v62, v181
	v_mov_b32_e32 v63, v181
	v_lshlrev_b32_e32 v194, 3, v21
	s_lshr_b32 s37, s49, 6
	v_lshlrev_b32_e32 v199, 2, v21
	v_mov_b32_e32 v50, v181
	v_mov_b32_e32 v51, v181
	v_mov_b32_e32 v52, v181
	v_mov_b32_e32 v53, v181
	v_mov_b32_e32 v54, v181
	v_mov_b32_e32 v55, v181
	v_mov_b32_e32 v56, v181
	v_mov_b32_e32 v57, v181
	v_mov_b32_e32 v58, v181
	v_mov_b32_e32 v59, v181
	v_mov_b32_e32 v60, v181
	v_mov_b32_e32 v61, v181
	v_add_u32_e32 v207, v0, v180
	v_add_u32_e32 v208, v1, v180
	v_add_u32_e32 v209, v2, v180
	v_mov_b64_e32 v[32:33], v[48:49]
	v_mov_b64_e32 v[16:17], v[48:49]
	v_mov_b64_e32 v[0:1], v[48:49]
	v_mov_b64_e32 v[78:79], v[62:63]
	v_readlane_b32 s56, v255, 1
	s_or_b32 s38, s1, 31
	s_add_i32 s39, s37, -1
	v_mov_b32_e32 v206, 0
	v_mov_b64_e32 v[34:35], v[50:51]
	v_mov_b64_e32 v[36:37], v[52:53]
	v_mov_b64_e32 v[38:39], v[54:55]
	v_mov_b64_e32 v[40:41], v[56:57]
	v_mov_b64_e32 v[42:43], v[58:59]
	v_mov_b64_e32 v[44:45], v[60:61]
	v_mov_b64_e32 v[46:47], v[62:63]
	v_mov_b64_e32 v[18:19], v[50:51]
	v_mov_b64_e32 v[20:21], v[52:53]
	v_mov_b64_e32 v[22:23], v[54:55]
	v_mov_b64_e32 v[24:25], v[56:57]
	v_mov_b64_e32 v[26:27], v[58:59]
	v_mov_b64_e32 v[28:29], v[60:61]
	v_mov_b64_e32 v[30:31], v[62:63]
	v_mov_b64_e32 v[2:3], v[50:51]
	v_mov_b64_e32 v[4:5], v[52:53]
	v_mov_b64_e32 v[6:7], v[54:55]
	v_mov_b64_e32 v[8:9], v[56:57]
	v_mov_b64_e32 v[10:11], v[58:59]
	v_mov_b64_e32 v[12:13], v[60:61]
	v_mov_b64_e32 v[14:15], v[62:63]
	v_mov_b32_e32 v210, 0
	v_mov_b64_e32 v[76:77], v[60:61]
	v_mov_b64_e32 v[74:75], v[58:59]
	v_mov_b64_e32 v[72:73], v[56:57]
	v_mov_b64_e32 v[70:71], v[54:55]
	v_mov_b64_e32 v[68:69], v[52:53]
	v_mov_b64_e32 v[66:67], v[50:51]
	v_mov_b64_e32 v[64:65], v[48:49]
	v_readlane_b32 s57, v255, 2
	v_readlane_b32 s59, v255, 4
	v_readlane_b32 s61, v253, 17
	s_waitcnt lgkmcnt(0)
	s_barrier
	s_branch .LBB0_962

.LBB0_1056:
	v_lshl_or_b32 v166, s60, 8, v205
	v_lshl_add_u32 v170, s61, 8, v198
	v_ashrrev_i32_e32 v167, 31, v166
	v_lshlrev_b64 v[202:203], 1, v[166:167]
	v_ashrrev_i32_e32 v171, 31, v170
	v_lshl_add_u64 v[168:169], s[18:19], 0, v[202:203]
	v_lshlrev_b64 v[214:215], 11, v[170:171]
	v_lshl_add_u64 v[128:129], v[168:169], 0, v[214:215]
	global_load_dwordx4 v[210:213], v[128:129], off
	global_load_dwordx4 v[152:155], v[128:129], off offset:256
	v_or_b32_e32 v194, 16, v170
	v_ashrrev_i32_e32 v195, 31, v194
	v_or_b32_e32 v176, 32, v170
	v_lshlrev_b64 v[196:197], 11, v[194:195]
	v_ashrrev_i32_e32 v177, 31, v176
	v_or_b32_e32 v172, 48, v170
	v_lshl_add_u64 v[128:129], v[168:169], 0, v[196:197]
	v_lshlrev_b64 v[178:179], 11, v[176:177]
	v_ashrrev_i32_e32 v173, 31, v172
	global_load_dwordx4 v[148:151], v[128:129], off
	global_load_dwordx4 v[144:147], v[128:129], off offset:256
	v_lshl_add_u64 v[128:129], v[168:169], 0, v[178:179]
	v_lshlrev_b64 v[174:175], 11, v[172:173]
	global_load_dwordx4 v[140:143], v[128:129], off
	global_load_dwordx4 v[136:139], v[128:129], off offset:256
	v_lshl_add_u64 v[128:129], v[168:169], 0, v[174:175]
	global_load_dwordx4 v[132:135], v[128:129], off
	s_nop 0
	global_load_dwordx4 v[128:131], v[128:129], off offset:256
	v_lshlrev_b32_e32 v250, 2, v218
	v_add_u32_e32 v250, 0x20400, v250
	ds_write_b32 v250, v240
	v_add_u32_e32 v250, 0x80, v170
	v_ashrrev_i32_e32 v251, 31, v250
	v_lshlrev_b64 v[250:251], 11, v[250:251]
	v_lshl_add_u64 v[250:251], v[168:169], 0, v[250:251]
	global_load_dwordx4 v[222:225], v[250:251], off
	global_load_dwordx4 v[226:229], v[250:251], off offset:256
	v_add_u32_e32 v250, 0x90, v170
	v_ashrrev_i32_e32 v251, 31, v250
	v_lshlrev_b64 v[250:251], 11, v[250:251]
	v_lshl_add_u64 v[250:251], v[168:169], 0, v[250:251]
	global_load_dwordx4 v[230:233], v[250:251], off
	global_load_dwordx4 v[234:237], v[250:251], off offset:256
	v_add_u32_e32 v250, 0xa0, v170
	v_ashrrev_i32_e32 v251, 31, v250
	v_lshlrev_b64 v[250:251], 11, v[250:251]
	v_lshl_add_u64 v[250:251], v[168:169], 0, v[250:251]
	global_load_dwordx4 v[238:241], v[250:251], off
	global_load_dwordx4 v[242:245], v[250:251], off offset:256
	v_add_u32_e32 v250, 0xb0, v170
	v_ashrrev_i32_e32 v251, 31, v250
	v_lshlrev_b64 v[250:251], 11, v[250:251]
	v_lshl_add_u64 v[250:251], v[168:169], 0, v[250:251]
	global_load_dwordx4 v[246:249], v[250:251], off
	v_and_b32_e32 v208, 64, v219
	v_xor_b32_e32 v207, 16, v219
	v_add_u32_e32 v208, 64, v208
	v_cmp_lt_i32_e32 vcc, v207, v208
	v_xor_b32_e32 v209, 32, v219
	s_lshl_b32 s28, s60, 2
	v_cndmask_b32_e32 v207, v219, v207, vcc
	v_cmp_lt_i32_e32 vcc, v209, v208
	v_lshlrev_b32_e32 v207, 2, v207
	s_ashr_i32 s29, s28, 31
	v_cndmask_b32_e32 v208, v219, v209, vcc
	v_lshlrev_b32_e32 v208, 2, v208
	s_waitcnt vmcnt(0)
	v_lshlrev_b32_e32 v216, 16, v210
	v_and_b32_e32 v217, 0xffff0000, v210
	v_lshlrev_b32_e32 v210, 16, v211
	v_and_b32_e32 v211, 0xffff0000, v211
	v_lshlrev_b32_e32 v220, 16, v212
	v_and_b32_e32 v221, 0xffff0000, v212
	v_lshlrev_b32_e32 v212, 16, v213
	v_and_b32_e32 v213, 0xffff0000, v213
	v_pk_add_f32 v[210:211], v[122:123], v[210:211]
	v_pk_add_f32 v[216:217], v[120:121], v[216:217]
	v_pk_add_f32 v[126:127], v[126:127], v[212:213]
	v_pk_add_f32 v[124:125], v[124:125], v[220:221]
	v_lshl_add_u64 v[212:213], s[18:19], 0, v[214:215]
	v_cvt_pk_bf16_f32 v120, v216, v217
	v_cvt_pk_bf16_f32 v121, v210, v211
	v_cvt_pk_bf16_f32 v122, v124, v125
	v_cvt_pk_bf16_f32 v123, v126, v127
	v_lshl_add_u64 v[202:203], v[212:213], 0, v[202:203]
	global_store_dwordx4 v[202:203], v[120:123], off
	s_nop 1
	v_mul_f32_e32 v120, v217, v217
	v_mul_f32_e32 v121, v211, v211
	v_fmac_f32_e32 v120, v216, v216
	v_fmac_f32_e32 v121, v210, v210
	v_add_f32_e32 v120, v120, v121
	v_mul_f32_e32 v121, v125, v125
	v_mul_f32_e32 v122, v127, v127
	v_fmac_f32_e32 v121, v124, v124
	v_fmac_f32_e32 v122, v126, v126
	v_add_f32_e32 v121, v121, v122
	v_add_f32_e32 v209, v120, v121
	v_lshlrev_b32_e32 v120, 16, v152
	v_and_b32_e32 v121, 0xffff0000, v152
	v_lshlrev_b32_e32 v122, 16, v153
	v_and_b32_e32 v123, 0xffff0000, v153
	v_lshlrev_b32_e32 v124, 16, v154
	v_and_b32_e32 v125, 0xffff0000, v154
	v_lshlrev_b32_e32 v126, 16, v155
	v_and_b32_e32 v127, 0xffff0000, v155
	v_pk_add_f32 v[118:119], v[118:119], v[122:123]
	v_pk_add_f32 v[116:117], v[116:117], v[120:121]
	v_pk_add_f32 v[120:121], v[114:115], v[126:127]
	v_pk_add_f32 v[122:123], v[112:113], v[124:125]
	v_cvt_pk_bf16_f32 v112, v116, v117
	v_cvt_pk_bf16_f32 v113, v118, v119
	v_cvt_pk_bf16_f32 v114, v122, v123
	v_cvt_pk_bf16_f32 v115, v120, v121
	global_store_dwordx4 v[202:203], v[112:115], off offset:256
	s_nop 1
	v_mul_f32_e32 v112, v117, v117
	v_mul_f32_e32 v113, v119, v119
	v_fmac_f32_e32 v112, v116, v116
	v_fmac_f32_e32 v113, v118, v118
	v_add_f32_e32 v112, v112, v113
	v_mul_f32_e32 v113, v123, v123
	v_mul_f32_e32 v114, v121, v121
	v_fmac_f32_e32 v113, v122, v122
	v_fmac_f32_e32 v114, v120, v120
	v_add_f32_e32 v113, v113, v114
	v_add_f32_e32 v112, v112, v113
	v_add_f32_e32 v112, v209, v112
	v_mov_b32_e32 v113, v112
	v_mov_b32_e32 v251, v112
	s_nop 1
	v_permlane16_swap_b32_e32 v113, v251
	s_waitcnt lgkmcnt(0)
	v_add_f32_e32 v112, v113, v251
	v_mov_b32_e32 v113, v112
	v_mov_b32_e32 v251, v112
	s_nop 1
	v_permlane32_swap_b32_e32 v113, v251
	s_and_saveexec_b64 s[10:11], s[40:41]
	s_cbranch_execz .LBB0_1058
	s_waitcnt lgkmcnt(0)
	v_add_f32_e32 v114, v113, v251
	v_lshlrev_b64 v[112:113], 6, v[170:171]
	v_lshl_add_u64 v[112:113], s[0:1], 0, v[112:113]
	v_lshl_add_u64 v[112:113], s[28:29], 2, v[112:113]
	s_lshl_b32 s64, s47, 2
	v_lshl_add_u64 v[112:113], v[112:113], 0, s[64:65]
	global_store_dword v[112:113], v114, off
.LBB0_1058:
	s_or_b64 exec, exec, s[10:11]
	v_lshlrev_b32_e32 v112, 16, v148
	s_waitcnt lgkmcnt(0)
	v_and_b32_e32 v113, 0xffff0000, v148
	v_lshlrev_b32_e32 v114, 16, v149
	v_and_b32_e32 v115, 0xffff0000, v149
	v_lshlrev_b32_e32 v116, 16, v150
	v_and_b32_e32 v117, 0xffff0000, v150
	v_pk_add_f32 v[108:109], v[108:109], v[112:113]
	v_pk_add_f32 v[110:111], v[110:111], v[114:115]
	v_pk_add_f32 v[114:115], v[104:105], v[116:117]
	v_cvt_pk_bf16_f32 v104, v108, v109
	v_mul_f32_e32 v109, v109, v109
	v_lshlrev_b32_e32 v118, 16, v151
	v_and_b32_e32 v119, 0xffff0000, v151
	v_fmac_f32_e32 v109, v108, v108
	v_mul_f32_e32 v108, v111, v111
	v_pk_add_f32 v[112:113], v[106:107], v[118:119]
	v_fmac_f32_e32 v108, v110, v110
	v_cvt_pk_bf16_f32 v105, v110, v111
	v_add_f32_e32 v108, v109, v108
	v_mul_f32_e32 v109, v115, v115
	v_mul_f32_e32 v110, v113, v113
	v_fmac_f32_e32 v109, v114, v114
	v_fmac_f32_e32 v110, v112, v112
	v_add_f32_e32 v109, v109, v110
	v_add_f32_e32 v116, v108, v109
	v_lshlrev_b32_e32 v108, 16, v144
	v_and_b32_e32 v109, 0xffff0000, v144
	v_lshlrev_b32_e32 v110, 16, v145
	v_and_b32_e32 v111, 0xffff0000, v145
	v_cvt_pk_bf16_f32 v107, v112, v113
	v_lshlrev_b32_e32 v112, 16, v146
	v_and_b32_e32 v113, 0xffff0000, v146
	v_pk_add_f32 v[102:103], v[102:103], v[110:111]
	v_pk_add_f32 v[100:101], v[100:101], v[108:109]
	v_cvt_pk_bf16_f32 v106, v114, v115
	v_lshlrev_b32_e32 v114, 16, v147
	v_and_b32_e32 v115, 0xffff0000, v147
	v_pk_add_f32 v[110:111], v[96:97], v[112:113]
	v_mul_f32_e32 v96, v101, v101
	v_mul_f32_e32 v97, v103, v103
	v_pk_add_f32 v[108:109], v[98:99], v[114:115]
	v_fmac_f32_e32 v96, v100, v100
	v_fmac_f32_e32 v97, v102, v102
	v_add_f32_e32 v96, v96, v97
	v_mul_f32_e32 v97, v111, v111
	v_mul_f32_e32 v98, v109, v109
	v_fmac_f32_e32 v97, v110, v110
	v_fmac_f32_e32 v98, v108, v108
	v_add_f32_e32 v97, v97, v98
	v_add_f32_e32 v96, v96, v97
	v_add_f32_e32 v99, v116, v96
	v_mov_b32_e32 v114, v99
	v_mov_b32_e32 v251, v99
	s_nop 1
	v_permlane16_swap_b32_e32 v114, v251
	v_lshl_add_u64 v[96:97], s[18:19], 0, v[196:197]
	v_lshl_add_u64 v[112:113], v[166:167], 1, v[96:97]
	v_cvt_pk_bf16_f32 v98, v100, v101
	v_cvt_pk_bf16_f32 v100, v110, v111
	s_waitcnt lgkmcnt(0)
	v_add_f32_e32 v96, v114, v251
	v_mov_b32_e32 v97, v96
	v_mov_b32_e32 v251, v96
	s_nop 1
	v_permlane32_swap_b32_e32 v97, v251
	v_cvt_pk_bf16_f32 v99, v102, v103
	v_cvt_pk_bf16_f32 v101, v108, v109
	global_store_dwordx4 v[112:113], v[104:107], off
	global_store_dwordx4 v[112:113], v[98:101], off offset:256
	s_and_saveexec_b64 s[10:11], s[40:41]
	s_cbranch_execz .LBB0_1060
	s_waitcnt lgkmcnt(0)
	v_add_f32_e32 v98, v97, v251
	v_lshlrev_b64 v[96:97], 6, v[194:195]
	v_lshl_add_u64 v[96:97], s[0:1], 0, v[96:97]
	v_lshl_add_u64 v[96:97], s[28:29], 2, v[96:97]
	s_lshl_b32 s64, s47, 2
	v_lshl_add_u64 v[96:97], v[96:97], 0, s[64:65]
	global_store_dword v[96:97], v98, off
.LBB0_1060:
	s_or_b64 exec, exec, s[10:11]
	v_lshlrev_b32_e32 v96, 16, v140
	s_waitcnt lgkmcnt(0)
	v_and_b32_e32 v97, 0xffff0000, v140
	v_lshlrev_b32_e32 v98, 16, v141
	v_and_b32_e32 v99, 0xffff0000, v141
	v_lshlrev_b32_e32 v100, 16, v142
	v_and_b32_e32 v101, 0xffff0000, v142
	v_pk_add_f32 v[92:93], v[92:93], v[96:97]
	v_pk_add_f32 v[94:95], v[94:95], v[98:99]
	v_pk_add_f32 v[98:99], v[88:89], v[100:101]
	v_cvt_pk_bf16_f32 v88, v92, v93
	v_mul_f32_e32 v93, v93, v93
	v_lshlrev_b32_e32 v102, 16, v143
	v_and_b32_e32 v103, 0xffff0000, v143
	v_fmac_f32_e32 v93, v92, v92
	v_mul_f32_e32 v92, v95, v95
	v_pk_add_f32 v[96:97], v[90:91], v[102:103]
	v_fmac_f32_e32 v92, v94, v94
	v_cvt_pk_bf16_f32 v89, v94, v95
	v_add_f32_e32 v92, v93, v92
	v_mul_f32_e32 v93, v99, v99
	v_mul_f32_e32 v94, v97, v97
	v_fmac_f32_e32 v93, v98, v98
	v_fmac_f32_e32 v94, v96, v96
	v_add_f32_e32 v93, v93, v94
	v_add_f32_e32 v100, v92, v93
	v_lshlrev_b32_e32 v92, 16, v136
	v_and_b32_e32 v93, 0xffff0000, v136
	v_lshlrev_b32_e32 v94, 16, v137
	v_and_b32_e32 v95, 0xffff0000, v137
	v_cvt_pk_bf16_f32 v91, v96, v97
	v_lshlrev_b32_e32 v96, 16, v138
	v_and_b32_e32 v97, 0xffff0000, v138
	v_pk_add_f32 v[86:87], v[86:87], v[94:95]
	v_pk_add_f32 v[84:85], v[84:85], v[92:93]
	v_cvt_pk_bf16_f32 v90, v98, v99
	v_lshlrev_b32_e32 v98, 16, v139
	v_and_b32_e32 v99, 0xffff0000, v139
	v_pk_add_f32 v[94:95], v[80:81], v[96:97]
	v_mul_f32_e32 v80, v85, v85
	v_mul_f32_e32 v81, v87, v87
	v_pk_add_f32 v[92:93], v[82:83], v[98:99]
	v_fmac_f32_e32 v80, v84, v84
	v_fmac_f32_e32 v81, v86, v86
	v_add_f32_e32 v80, v80, v81
	v_mul_f32_e32 v81, v95, v95
	v_mul_f32_e32 v82, v93, v93
	v_fmac_f32_e32 v81, v94, v94
	v_fmac_f32_e32 v82, v92, v92
	v_add_f32_e32 v81, v81, v82
	v_add_f32_e32 v80, v80, v81
	v_add_f32_e32 v83, v100, v80
	v_mov_b32_e32 v98, v83
	v_mov_b32_e32 v251, v83
	s_nop 1
	v_permlane16_swap_b32_e32 v98, v251
	v_lshl_add_u64 v[80:81], s[18:19], 0, v[178:179]
	v_lshl_add_u64 v[96:97], v[166:167], 1, v[80:81]
	v_cvt_pk_bf16_f32 v82, v84, v85
	v_cvt_pk_bf16_f32 v84, v94, v95
	s_waitcnt lgkmcnt(0)
	v_add_f32_e32 v80, v98, v251
	v_mov_b32_e32 v81, v80
	v_mov_b32_e32 v251, v80
	s_nop 1
	v_permlane32_swap_b32_e32 v81, v251
	v_cvt_pk_bf16_f32 v83, v86, v87
	v_cvt_pk_bf16_f32 v85, v92, v93
	global_store_dwordx4 v[96:97], v[88:91], off
	global_store_dwordx4 v[96:97], v[82:85], off offset:256
	s_and_saveexec_b64 s[10:11], s[40:41]
	s_cbranch_execz .LBB0_1062
	s_waitcnt lgkmcnt(0)
	v_add_f32_e32 v82, v81, v251
	v_lshlrev_b64 v[80:81], 6, v[176:177]
	v_lshl_add_u64 v[80:81], s[0:1], 0, v[80:81]
	v_lshl_add_u64 v[80:81], s[28:29], 2, v[80:81]
	s_lshl_b32 s64, s47, 2
	v_lshl_add_u64 v[80:81], v[80:81], 0, s[64:65]
	global_store_dword v[80:81], v82, off
.LBB0_1062:
	s_or_b64 exec, exec, s[10:11]
	v_lshlrev_b32_e32 v80, 16, v132
	s_waitcnt lgkmcnt(0)
	v_and_b32_e32 v81, 0xffff0000, v132
	v_lshlrev_b32_e32 v82, 16, v133
	v_and_b32_e32 v83, 0xffff0000, v133
	v_lshlrev_b32_e32 v84, 16, v134
	v_and_b32_e32 v85, 0xffff0000, v134
	v_pk_add_f32 v[76:77], v[76:77], v[80:81]
	v_pk_add_f32 v[78:79], v[78:79], v[82:83]
	v_pk_add_f32 v[82:83], v[72:73], v[84:85]
	v_cvt_pk_bf16_f32 v72, v76, v77
	v_mul_f32_e32 v77, v77, v77
	v_lshlrev_b32_e32 v86, 16, v135
	v_and_b32_e32 v87, 0xffff0000, v135
	v_fmac_f32_e32 v77, v76, v76
	v_mul_f32_e32 v76, v79, v79
	v_pk_add_f32 v[80:81], v[74:75], v[86:87]
	v_fmac_f32_e32 v76, v78, v78
	v_cvt_pk_bf16_f32 v73, v78, v79
	v_add_f32_e32 v76, v77, v76
	v_mul_f32_e32 v77, v83, v83
	v_mul_f32_e32 v78, v81, v81
	v_fmac_f32_e32 v77, v82, v82
	v_fmac_f32_e32 v78, v80, v80
	v_add_f32_e32 v77, v77, v78
	v_add_f32_e32 v84, v76, v77
	v_lshlrev_b32_e32 v76, 16, v128
	v_and_b32_e32 v77, 0xffff0000, v128
	v_lshlrev_b32_e32 v78, 16, v129
	v_and_b32_e32 v79, 0xffff0000, v129
	v_cvt_pk_bf16_f32 v75, v80, v81
	v_lshlrev_b32_e32 v80, 16, v130
	v_and_b32_e32 v81, 0xffff0000, v130
	v_pk_add_f32 v[70:71], v[70:71], v[78:79]
	v_pk_add_f32 v[68:69], v[68:69], v[76:77]
	v_cvt_pk_bf16_f32 v74, v82, v83
	v_lshlrev_b32_e32 v82, 16, v131
	v_and_b32_e32 v83, 0xffff0000, v131
	v_pk_add_f32 v[78:79], v[64:65], v[80:81]
	v_mul_f32_e32 v64, v69, v69
	v_mul_f32_e32 v65, v71, v71
	v_pk_add_f32 v[76:77], v[66:67], v[82:83]
	v_fmac_f32_e32 v64, v68, v68
	v_fmac_f32_e32 v65, v70, v70
	v_add_f32_e32 v64, v64, v65
	v_mul_f32_e32 v65, v79, v79
	v_mul_f32_e32 v66, v77, v77
	v_fmac_f32_e32 v65, v78, v78
	v_fmac_f32_e32 v66, v76, v76
	v_add_f32_e32 v65, v65, v66
	v_add_f32_e32 v64, v64, v65
	v_add_f32_e32 v67, v84, v64
	v_mov_b32_e32 v82, v67
	v_mov_b32_e32 v251, v67
	s_nop 1
	v_permlane16_swap_b32_e32 v82, v251
	v_lshl_add_u64 v[64:65], s[18:19], 0, v[174:175]
	v_lshl_add_u64 v[80:81], v[166:167], 1, v[64:65]
	v_cvt_pk_bf16_f32 v66, v68, v69
	v_cvt_pk_bf16_f32 v68, v78, v79
	s_waitcnt lgkmcnt(0)
	v_add_f32_e32 v64, v82, v251
	v_mov_b32_e32 v65, v64
	v_mov_b32_e32 v251, v64
	s_nop 1
	v_permlane32_swap_b32_e32 v65, v251
	v_cvt_pk_bf16_f32 v67, v70, v71
	v_cvt_pk_bf16_f32 v69, v76, v77
	global_store_dwordx4 v[80:81], v[72:75], off
	global_store_dwordx4 v[80:81], v[66:69], off offset:256
	s_and_saveexec_b64 s[10:11], s[40:41]
	s_cbranch_execz .LBB0_1064
	s_waitcnt lgkmcnt(0)
	v_add_f32_e32 v66, v65, v251
	v_lshlrev_b64 v[64:65], 6, v[172:173]
	v_lshl_add_u64 v[64:65], s[0:1], 0, v[64:65]
	v_lshl_add_u64 v[64:65], s[28:29], 2, v[64:65]
	s_lshl_b32 s64, s47, 2
	v_lshl_add_u64 v[64:65], v[64:65], 0, s[64:65]
	global_store_dword v[64:65], v66, off
.LBB0_1064:
	s_or_b64 exec, exec, s[10:11]
	v_add_u32_e32 v104, 0x80, v170
	v_ashrrev_i32_e32 v105, 31, v104
	v_lshlrev_b64 v[110:111], 11, v[104:105]
	s_waitcnt lgkmcnt(0)
	v_lshl_add_u64 v[64:65], v[168:169], 0, v[110:111]
	v_add_u32_e32 v100, 0x90, v170
	v_ashrrev_i32_e32 v101, 31, v100
	v_add_u32_e32 v96, 0xa0, v170
	v_lshlrev_b64 v[102:103], 11, v[100:101]
	v_ashrrev_i32_e32 v97, 31, v96
	v_add_u32_e32 v92, 0xb0, v170
	v_lshl_add_u64 v[64:65], v[168:169], 0, v[102:103]
	v_lshlrev_b64 v[98:99], 11, v[96:97]
	v_ashrrev_i32_e32 v93, 31, v92
	v_lshl_add_u64 v[64:65], v[168:169], 0, v[98:99]
	v_lshlrev_b64 v[94:95], 11, v[92:93]
	v_lshl_add_u64 v[64:65], v[168:169], 0, v[94:95]
	s_nop 0
	global_load_dwordx4 v[64:67], v[64:65], off offset:256
	v_lshl_add_u64 v[110:111], s[18:19], 0, v[110:111]
	v_lshl_add_u64 v[110:111], v[166:167], 1, v[110:111]
	v_lshlrev_b32_e32 v112, 16, v222
	v_and_b32_e32 v113, 0xffff0000, v222
	v_lshlrev_b32_e32 v106, 16, v223
	v_and_b32_e32 v107, 0xffff0000, v223
	v_lshlrev_b32_e32 v114, 16, v224
	v_and_b32_e32 v115, 0xffff0000, v224
	v_lshlrev_b32_e32 v108, 16, v225
	v_and_b32_e32 v109, 0xffff0000, v225
	v_pk_add_f32 v[62:63], v[62:63], v[106:107]
	v_pk_add_f32 v[60:61], v[60:61], v[112:113]
	v_pk_add_f32 v[106:107], v[58:59], v[108:109]
	v_pk_add_f32 v[108:109], v[56:57], v[114:115]
	v_cvt_pk_bf16_f32 v56, v60, v61
	v_cvt_pk_bf16_f32 v57, v62, v63
	v_cvt_pk_bf16_f32 v58, v108, v109
	v_cvt_pk_bf16_f32 v59, v106, v107
	global_store_dwordx4 v[110:111], v[56:59], off
	s_nop 1
	v_mul_f32_e32 v56, v61, v61
	v_mul_f32_e32 v57, v63, v63
	v_fmac_f32_e32 v56, v60, v60
	v_fmac_f32_e32 v57, v62, v62
	v_add_f32_e32 v56, v56, v57
	v_mul_f32_e32 v57, v109, v109
	v_mul_f32_e32 v58, v107, v107
	v_fmac_f32_e32 v57, v108, v108
	v_fmac_f32_e32 v58, v106, v106
	v_add_f32_e32 v57, v57, v58
	v_add_f32_e32 v106, v56, v57
	v_lshlrev_b32_e32 v56, 16, v226
	v_and_b32_e32 v57, 0xffff0000, v226
	v_lshlrev_b32_e32 v58, 16, v227
	v_and_b32_e32 v59, 0xffff0000, v227
	v_lshlrev_b32_e32 v60, 16, v228
	v_and_b32_e32 v61, 0xffff0000, v228
	v_lshlrev_b32_e32 v62, 16, v229
	v_and_b32_e32 v63, 0xffff0000, v229
	v_pk_add_f32 v[54:55], v[54:55], v[58:59]
	v_pk_add_f32 v[52:53], v[52:53], v[56:57]
	v_pk_add_f32 v[56:57], v[50:51], v[62:63]
	v_pk_add_f32 v[58:59], v[48:49], v[60:61]
	v_cvt_pk_bf16_f32 v48, v52, v53
	v_cvt_pk_bf16_f32 v49, v54, v55
	v_cvt_pk_bf16_f32 v50, v58, v59
	v_cvt_pk_bf16_f32 v51, v56, v57
	global_store_dwordx4 v[110:111], v[48:51], off offset:256
	s_nop 1
	v_mul_f32_e32 v48, v53, v53
	v_mul_f32_e32 v49, v55, v55
	v_fmac_f32_e32 v48, v52, v52
	v_fmac_f32_e32 v49, v54, v54
	v_add_f32_e32 v48, v48, v49
	v_mul_f32_e32 v49, v59, v59
	v_mul_f32_e32 v50, v57, v57
	v_fmac_f32_e32 v49, v58, v58
	v_fmac_f32_e32 v50, v56, v56
	v_add_f32_e32 v49, v49, v50
	v_add_f32_e32 v48, v48, v49
	v_add_f32_e32 v48, v106, v48
	v_mov_b32_e32 v49, v48
	v_mov_b32_e32 v251, v48
	s_nop 1
	v_permlane16_swap_b32_e32 v49, v251
	s_waitcnt lgkmcnt(0)
	v_add_f32_e32 v48, v49, v251
	v_mov_b32_e32 v49, v48
	v_mov_b32_e32 v251, v48
	s_nop 1
	v_permlane32_swap_b32_e32 v49, v251
	s_and_saveexec_b64 s[10:11], s[40:41]
	s_cbranch_execz .LBB0_1066
	s_waitcnt lgkmcnt(0)
	v_add_f32_e32 v50, v49, v251
	v_lshlrev_b64 v[48:49], 6, v[104:105]
	v_lshl_add_u64 v[48:49], s[0:1], 0, v[48:49]
	v_lshl_add_u64 v[48:49], s[28:29], 2, v[48:49]
	s_lshl_b32 s64, s47, 2
	v_lshl_add_u64 v[48:49], v[48:49], 0, s[64:65]
	global_store_dword v[48:49], v50, off
.LBB0_1066:
	s_or_b64 exec, exec, s[10:11]
	v_lshlrev_b32_e32 v48, 16, v230
	s_waitcnt lgkmcnt(0)
	v_and_b32_e32 v49, 0xffff0000, v230
	v_lshlrev_b32_e32 v50, 16, v231
	v_and_b32_e32 v51, 0xffff0000, v231
	v_lshlrev_b32_e32 v52, 16, v232
	v_and_b32_e32 v53, 0xffff0000, v232
	v_pk_add_f32 v[44:45], v[44:45], v[48:49]
	v_pk_add_f32 v[46:47], v[46:47], v[50:51]
	v_pk_add_f32 v[50:51], v[40:41], v[52:53]
	v_cvt_pk_bf16_f32 v40, v44, v45
	v_mul_f32_e32 v45, v45, v45
	v_lshlrev_b32_e32 v54, 16, v233
	v_and_b32_e32 v55, 0xffff0000, v233
	v_fmac_f32_e32 v45, v44, v44
	v_mul_f32_e32 v44, v47, v47
	v_pk_add_f32 v[48:49], v[42:43], v[54:55]
	v_fmac_f32_e32 v44, v46, v46
	v_cvt_pk_bf16_f32 v41, v46, v47
	v_add_f32_e32 v44, v45, v44
	v_mul_f32_e32 v45, v51, v51
	v_mul_f32_e32 v46, v49, v49
	v_fmac_f32_e32 v45, v50, v50
	v_fmac_f32_e32 v46, v48, v48
	v_add_f32_e32 v45, v45, v46
	v_add_f32_e32 v52, v44, v45
	v_lshlrev_b32_e32 v44, 16, v234
	v_and_b32_e32 v45, 0xffff0000, v234
	v_lshlrev_b32_e32 v46, 16, v235
	v_and_b32_e32 v47, 0xffff0000, v235
	v_cvt_pk_bf16_f32 v43, v48, v49
	v_lshlrev_b32_e32 v48, 16, v236
	v_and_b32_e32 v49, 0xffff0000, v236
	v_pk_add_f32 v[38:39], v[38:39], v[46:47]
	v_pk_add_f32 v[36:37], v[36:37], v[44:45]
	v_cvt_pk_bf16_f32 v42, v50, v51
	v_lshlrev_b32_e32 v50, 16, v237
	v_and_b32_e32 v51, 0xffff0000, v237
	v_pk_add_f32 v[46:47], v[32:33], v[48:49]
	v_mul_f32_e32 v32, v37, v37
	v_mul_f32_e32 v33, v39, v39
	v_pk_add_f32 v[44:45], v[34:35], v[50:51]
	v_fmac_f32_e32 v32, v36, v36
	v_fmac_f32_e32 v33, v38, v38
	v_add_f32_e32 v32, v32, v33
	v_mul_f32_e32 v33, v47, v47
	v_mul_f32_e32 v34, v45, v45
	v_fmac_f32_e32 v33, v46, v46
	v_fmac_f32_e32 v34, v44, v44
	v_add_f32_e32 v33, v33, v34
	v_add_f32_e32 v32, v32, v33
	v_add_f32_e32 v35, v52, v32
	v_mov_b32_e32 v50, v35
	v_mov_b32_e32 v251, v35
	s_nop 1
	v_permlane16_swap_b32_e32 v50, v251
	v_lshl_add_u64 v[32:33], s[18:19], 0, v[102:103]
	v_lshl_add_u64 v[48:49], v[166:167], 1, v[32:33]
	v_cvt_pk_bf16_f32 v34, v36, v37
	v_cvt_pk_bf16_f32 v36, v46, v47
	s_waitcnt lgkmcnt(0)
	v_add_f32_e32 v32, v50, v251
	v_mov_b32_e32 v33, v32
	v_mov_b32_e32 v251, v32
	s_nop 1
	v_permlane32_swap_b32_e32 v33, v251
	v_cvt_pk_bf16_f32 v35, v38, v39
	v_cvt_pk_bf16_f32 v37, v44, v45
	global_store_dwordx4 v[48:49], v[40:43], off
	global_store_dwordx4 v[48:49], v[34:37], off offset:256
	s_and_saveexec_b64 s[10:11], s[40:41]
	s_cbranch_execz .LBB0_1068
	s_waitcnt lgkmcnt(0)
	v_add_f32_e32 v34, v33, v251
	v_lshlrev_b64 v[32:33], 6, v[100:101]
	v_lshl_add_u64 v[32:33], s[0:1], 0, v[32:33]
	v_lshl_add_u64 v[32:33], s[28:29], 2, v[32:33]
	s_lshl_b32 s64, s47, 2
	v_lshl_add_u64 v[32:33], v[32:33], 0, s[64:65]
	global_store_dword v[32:33], v34, off
.LBB0_1068:
	s_or_b64 exec, exec, s[10:11]
	v_lshlrev_b32_e32 v32, 16, v238
	s_waitcnt lgkmcnt(0)
	v_and_b32_e32 v33, 0xffff0000, v238
	v_lshlrev_b32_e32 v34, 16, v239
	v_and_b32_e32 v35, 0xffff0000, v239
	v_lshlrev_b32_e32 v36, 16, v240
	v_and_b32_e32 v37, 0xffff0000, v240
	v_pk_add_f32 v[28:29], v[28:29], v[32:33]
	v_pk_add_f32 v[30:31], v[30:31], v[34:35]
	v_pk_add_f32 v[34:35], v[24:25], v[36:37]
	v_cvt_pk_bf16_f32 v24, v28, v29
	v_mul_f32_e32 v29, v29, v29
	v_lshlrev_b32_e32 v38, 16, v241
	v_and_b32_e32 v39, 0xffff0000, v241
	v_fmac_f32_e32 v29, v28, v28
	v_mul_f32_e32 v28, v31, v31
	v_pk_add_f32 v[32:33], v[26:27], v[38:39]
	v_fmac_f32_e32 v28, v30, v30
	v_cvt_pk_bf16_f32 v25, v30, v31
	v_add_f32_e32 v28, v29, v28
	v_mul_f32_e32 v29, v35, v35
	v_mul_f32_e32 v30, v33, v33
	v_fmac_f32_e32 v29, v34, v34
	v_fmac_f32_e32 v30, v32, v32
	v_add_f32_e32 v29, v29, v30
	v_add_f32_e32 v36, v28, v29
	v_lshlrev_b32_e32 v28, 16, v242
	v_and_b32_e32 v29, 0xffff0000, v242
	v_lshlrev_b32_e32 v30, 16, v243
	v_and_b32_e32 v31, 0xffff0000, v243
	v_cvt_pk_bf16_f32 v27, v32, v33
	v_lshlrev_b32_e32 v32, 16, v244
	v_and_b32_e32 v33, 0xffff0000, v244
	v_pk_add_f32 v[22:23], v[22:23], v[30:31]
	v_pk_add_f32 v[20:21], v[20:21], v[28:29]
	v_cvt_pk_bf16_f32 v26, v34, v35
	v_lshlrev_b32_e32 v34, 16, v245
	v_and_b32_e32 v35, 0xffff0000, v245
	v_pk_add_f32 v[30:31], v[16:17], v[32:33]
	v_mul_f32_e32 v16, v21, v21
	v_mul_f32_e32 v17, v23, v23
	v_pk_add_f32 v[28:29], v[18:19], v[34:35]
	v_fmac_f32_e32 v16, v20, v20
	v_fmac_f32_e32 v17, v22, v22
	v_add_f32_e32 v16, v16, v17
	v_mul_f32_e32 v17, v31, v31
	v_mul_f32_e32 v18, v29, v29
	v_fmac_f32_e32 v17, v30, v30
	v_fmac_f32_e32 v18, v28, v28
	v_add_f32_e32 v17, v17, v18
	v_add_f32_e32 v16, v16, v17
	v_add_f32_e32 v19, v36, v16
	v_mov_b32_e32 v34, v19
	v_mov_b32_e32 v251, v19
	s_nop 1
	v_permlane16_swap_b32_e32 v34, v251
	v_lshl_add_u64 v[16:17], s[18:19], 0, v[98:99]
	v_lshl_add_u64 v[32:33], v[166:167], 1, v[16:17]
	v_cvt_pk_bf16_f32 v18, v20, v21
	v_cvt_pk_bf16_f32 v20, v30, v31
	s_waitcnt lgkmcnt(0)
	v_add_f32_e32 v16, v34, v251
	v_mov_b32_e32 v17, v16
	v_mov_b32_e32 v251, v16
	s_nop 1
	v_permlane32_swap_b32_e32 v17, v251
	v_cvt_pk_bf16_f32 v19, v22, v23
	v_cvt_pk_bf16_f32 v21, v28, v29
	global_store_dwordx4 v[32:33], v[24:27], off
	global_store_dwordx4 v[32:33], v[18:21], off offset:256
	s_and_saveexec_b64 s[10:11], s[40:41]
	s_cbranch_execz .LBB0_1070
	s_waitcnt lgkmcnt(0)
	v_add_f32_e32 v18, v17, v251
	v_lshlrev_b64 v[16:17], 6, v[96:97]
	v_lshl_add_u64 v[16:17], s[0:1], 0, v[16:17]
	v_lshl_add_u64 v[16:17], s[28:29], 2, v[16:17]
	s_lshl_b32 s64, s47, 2
	v_lshl_add_u64 v[16:17], v[16:17], 0, s[64:65]
	global_store_dword v[16:17], v18, off
.LBB0_1070:
	s_or_b64 exec, exec, s[10:11]
	v_lshlrev_b32_e32 v16, 16, v246
	s_waitcnt lgkmcnt(0)
	v_and_b32_e32 v17, 0xffff0000, v246
	v_lshlrev_b32_e32 v18, 16, v247
	v_and_b32_e32 v19, 0xffff0000, v247
	v_lshlrev_b32_e32 v20, 16, v248
	v_and_b32_e32 v21, 0xffff0000, v248
	v_pk_add_f32 v[12:13], v[12:13], v[16:17]
	v_pk_add_f32 v[14:15], v[14:15], v[18:19]
	v_pk_add_f32 v[18:19], v[8:9], v[20:21]
	v_cvt_pk_bf16_f32 v8, v12, v13
	v_mul_f32_e32 v13, v13, v13
	v_lshlrev_b32_e32 v22, 16, v249
	v_and_b32_e32 v23, 0xffff0000, v249
	v_fmac_f32_e32 v13, v12, v12
	v_mul_f32_e32 v12, v15, v15
	v_pk_add_f32 v[16:17], v[10:11], v[22:23]
	v_fmac_f32_e32 v12, v14, v14
	v_cvt_pk_bf16_f32 v9, v14, v15
	v_add_f32_e32 v12, v13, v12
	v_mul_f32_e32 v13, v19, v19
	v_mul_f32_e32 v14, v17, v17
	v_fmac_f32_e32 v13, v18, v18
	v_fmac_f32_e32 v14, v16, v16
	v_add_f32_e32 v13, v13, v14
	v_add_f32_e32 v20, v12, v13
	s_waitcnt vmcnt(8)
	v_lshlrev_b32_e32 v12, 16, v64
	v_and_b32_e32 v13, 0xffff0000, v64
	v_lshlrev_b32_e32 v14, 16, v65
	v_and_b32_e32 v15, 0xffff0000, v65
	v_cvt_pk_bf16_f32 v11, v16, v17
	v_lshlrev_b32_e32 v16, 16, v66
	v_and_b32_e32 v17, 0xffff0000, v66
	v_pk_add_f32 v[6:7], v[6:7], v[14:15]
	v_pk_add_f32 v[4:5], v[4:5], v[12:13]
	v_cvt_pk_bf16_f32 v10, v18, v19
	v_lshlrev_b32_e32 v18, 16, v67
	v_and_b32_e32 v19, 0xffff0000, v67
	v_pk_add_f32 v[14:15], v[0:1], v[16:17]
	v_mul_f32_e32 v0, v5, v5
	v_mul_f32_e32 v1, v7, v7
	v_pk_add_f32 v[12:13], v[2:3], v[18:19]
	v_fmac_f32_e32 v0, v4, v4
	v_fmac_f32_e32 v1, v6, v6
	v_add_f32_e32 v0, v0, v1
	v_mul_f32_e32 v1, v15, v15
	v_mul_f32_e32 v2, v13, v13
	v_fmac_f32_e32 v1, v14, v14
	v_fmac_f32_e32 v2, v12, v12
	v_add_f32_e32 v1, v1, v2
	v_add_f32_e32 v0, v0, v1
	v_add_f32_e32 v3, v20, v0
	v_mov_b32_e32 v18, v3
	v_mov_b32_e32 v251, v3
	s_nop 1
	v_permlane16_swap_b32_e32 v18, v251
	v_lshl_add_u64 v[0:1], s[18:19], 0, v[94:95]
	v_lshl_add_u64 v[16:17], v[166:167], 1, v[0:1]
	v_cvt_pk_bf16_f32 v2, v4, v5
	v_cvt_pk_bf16_f32 v4, v14, v15
	s_waitcnt lgkmcnt(0)
	v_add_f32_e32 v0, v18, v251
	v_mov_b32_e32 v1, v0
	v_mov_b32_e32 v251, v0
	s_nop 1
	v_permlane32_swap_b32_e32 v1, v251
	v_cvt_pk_bf16_f32 v3, v6, v7
	v_cvt_pk_bf16_f32 v5, v12, v13
	global_store_dwordx4 v[16:17], v[8:11], off
	global_store_dwordx4 v[16:17], v[2:5], off offset:256
	s_and_saveexec_b64 s[10:11], s[40:41]
	s_cbranch_execz .LBB0_1072
	s_waitcnt lgkmcnt(0)
	v_add_f32_e32 v2, v1, v251
	v_lshlrev_b64 v[0:1], 6, v[92:93]
	v_lshl_add_u64 v[0:1], s[0:1], 0, v[0:1]
	v_lshl_add_u64 v[0:1], s[28:29], 2, v[0:1]
	s_lshl_b32 s64, s47, 2
	v_lshl_add_u64 v[0:1], v[0:1], 0, s[64:65]
	global_store_dword v[0:1], v2, off

.LBB0_1147:
	v_mov_b32_e32 v142, v152
	v_and_b32_e32 v143, 64, v219
	v_ashrrev_i32_e32 v128, 31, v142
	v_lshrrev_b32_e32 v128, 30, v128
	v_add_u32_e32 v128, v142, v128
	s_waitcnt vmcnt(0)
	v_ashrrev_i32_e32 v160, 2, v128
	v_and_b32_e32 v128, 0x3ffffffc, v128
	v_lshlrev_b32_e32 v130, 1, v160
	v_sub_u32_e32 v128, v142, v128
	v_and_b32_e32 v130, 0xffffff80, v130
	v_and_or_b32 v131, v160, 63, s10
	v_lshlrev_b32_e32 v128, 2, v128
	v_add_u32_e32 v130, v131, v130
	v_ashrrev_i32_e32 v129, 31, v128
	v_ashrrev_i32_e32 v131, 31, v130
	v_lshl_add_u64 v[128:129], v[128:129], 2, s[0:1]
	v_lshlrev_b64 v[144:145], 6, v[130:131]
	v_lshl_add_u64 v[144:145], v[128:129], 0, v[144:145]
	global_load_dwordx4 v[164:167], v[144:145], off offset:1024
	global_load_dwordx4 v[168:171], v[144:145], off offset:2048
	global_load_dwordx4 v[172:175], v[144:145], off offset:3072
	v_add_co_u32_e32 v198, vcc, 0x2000, v144
	v_addc_co_u32_e32 v199, vcc, 0, v145, vcc
	global_load_dwordx4 v[176:179], v[198:199], off
	global_load_dwordx4 v[194:197], v[198:199], off offset:1024
	global_load_dwordx4 v[206:209], v[198:199], off offset:2048
	global_load_dwordx4 v[210:213], v[198:199], off offset:3072
	global_load_dwordx4 v[144:147], v[144:145], off
	v_add_u32_e32 v148, 64, v143
	v_add_u32_e32 v130, 0x80, v130
	s_waitcnt vmcnt(0)
	v_add_f32_e32 v131, v144, v145
	v_add_f32_e32 v144, v146, v147
	v_add_f32_e32 v131, v131, v144
	v_xor_b32_e32 v144, 1, v219
	v_cmp_lt_i32_e32 vcc, v144, v148
	s_nop 1
	v_cndmask_b32_e32 v144, v219, v144, vcc
	v_lshlrev_b32_e32 v146, 2, v144
	s_nop 1
	s_waitcnt lgkmcnt(0)
	v_add_f32_dpp v131, v131, v131 quad_perm:[1,0,3,2] row_mask:0xf bank_mask:0xf
	v_xor_b32_e32 v144, 2, v219
	v_cmp_lt_i32_e32 vcc, v144, v148
	s_nop 1
	v_cndmask_b32_e32 v144, v219, v144, vcc
	v_lshlrev_b32_e32 v145, 2, v144
	s_nop 1
	s_waitcnt lgkmcnt(0)
	v_add_f32_dpp v131, v131, v131 quad_perm:[2,3,0,1] row_mask:0xf bank_mask:0xf
	v_fmamk_f32 v131, v131, 0x3a800000, v200
	v_rsq_f32_e32 v144, v131
	v_add_u32_e32 v131, 16, v160
	v_lshlrev_b32_e32 v147, 1, v131
	v_and_b32_e32 v147, 0xffffff80, v147
	v_and_or_b32 v131, v131, 63, s10
	v_add_u32_e32 v148, v131, v147
	v_ashrrev_i32_e32 v149, 31, v148
	v_lshlrev_b64 v[148:149], 6, v[148:149]
	v_lshl_add_u64 v[148:149], v[128:129], 0, v[148:149]
	s_waitcnt vmcnt(0)
	v_add_f32_e32 v131, v164, v165
	v_add_f32_e32 v147, v166, v167
	v_add_f32_e32 v131, v131, v147
	s_nop 1
	s_waitcnt lgkmcnt(0)
	v_add_f32_dpp v131, v131, v131 quad_perm:[1,0,3,2] row_mask:0xf bank_mask:0xf
	s_nop 1
	s_waitcnt lgkmcnt(0)
	v_add_f32_dpp v131, v131, v131 quad_perm:[2,3,0,1] row_mask:0xf bank_mask:0xf
	v_fmamk_f32 v131, v131, 0x3a800000, v200
	v_rsq_f32_e32 v147, v131
	v_add_u32_e32 v131, 32, v160
	v_lshlrev_b32_e32 v148, 1, v131
	v_and_b32_e32 v148, 0xffffff80, v148
	v_and_or_b32 v131, v131, 63, s10
	v_add_u32_e32 v148, v131, v148
	v_ashrrev_i32_e32 v149, 31, v148
	v_lshlrev_b64 v[148:149], 6, v[148:149]
	v_lshl_add_u64 v[148:149], v[128:129], 0, v[148:149]
	s_waitcnt vmcnt(0)
	v_add_f32_e32 v131, v168, v169
	v_add_f32_e32 v148, v170, v171
	v_add_f32_e32 v131, v131, v148
	s_nop 1
	s_waitcnt lgkmcnt(0)
	v_add_f32_dpp v131, v131, v131 quad_perm:[1,0,3,2] row_mask:0xf bank_mask:0xf
	s_nop 1
	s_waitcnt lgkmcnt(0)
	v_add_f32_dpp v131, v131, v131 quad_perm:[2,3,0,1] row_mask:0xf bank_mask:0xf
	v_fmamk_f32 v131, v131, 0x3a800000, v200
	v_rsq_f32_e32 v148, v131
	v_add_u32_e32 v131, 48, v160
	v_lshlrev_b32_e32 v149, 1, v131
	v_and_b32_e32 v149, 0xffffff80, v149
	v_and_or_b32 v131, v131, 63, s10
	v_add_u32_e32 v156, v131, v149
	v_ashrrev_i32_e32 v157, 31, v156
	v_lshlrev_b64 v[156:157], 6, v[156:157]
	v_lshl_add_u64 v[156:157], v[128:129], 0, v[156:157]
	s_waitcnt vmcnt(0)
	v_add_f32_e32 v131, v172, v173
	v_add_f32_e32 v149, v174, v175
	v_add_f32_e32 v131, v131, v149
	s_nop 1
	s_waitcnt lgkmcnt(0)
	v_add_f32_dpp v131, v131, v131 quad_perm:[1,0,3,2] row_mask:0xf bank_mask:0xf
	s_nop 1
	s_waitcnt lgkmcnt(0)
	v_add_f32_dpp v131, v131, v131 quad_perm:[2,3,0,1] row_mask:0xf bank_mask:0xf
	v_fmamk_f32 v131, v131, 0x3a800000, v200
	v_rsq_f32_e32 v149, v131
	v_ashrrev_i32_e32 v131, 31, v130
	v_lshlrev_b64 v[130:131], 6, v[130:131]
	v_lshl_add_u64 v[130:131], v[128:129], 0, v[130:131]
	s_waitcnt vmcnt(0)
	v_add_f32_e32 v130, v176, v177
	v_add_f32_e32 v131, v178, v179
	v_add_f32_e32 v130, v130, v131
	s_nop 1
	s_waitcnt lgkmcnt(0)
	v_add_f32_dpp v130, v130, v130 quad_perm:[1,0,3,2] row_mask:0xf bank_mask:0xf
	s_nop 1
	s_waitcnt lgkmcnt(0)
	v_add_f32_dpp v130, v130, v130 quad_perm:[2,3,0,1] row_mask:0xf bank_mask:0xf
	v_fmamk_f32 v130, v130, 0x3a800000, v200
	v_rsq_f32_e32 v161, v130
	v_add_u32_e32 v130, 0x50, v160
	v_lshlrev_b32_e32 v131, 1, v130
	v_and_b32_e32 v131, 0xffffff80, v131
	v_and_or_b32 v130, v130, 63, s10
	v_add_u32_e32 v130, v130, v131
	v_ashrrev_i32_e32 v131, 31, v130
	v_lshlrev_b64 v[130:131], 6, v[130:131]
	v_lshl_add_u64 v[130:131], v[128:129], 0, v[130:131]
	s_waitcnt vmcnt(0)
	v_add_f32_e32 v130, v194, v195
	v_add_f32_e32 v131, v196, v197
	v_add_f32_e32 v130, v130, v131
	s_nop 1
	s_waitcnt lgkmcnt(0)
	v_add_f32_dpp v130, v130, v130 quad_perm:[1,0,3,2] row_mask:0xf bank_mask:0xf
	s_nop 1
	s_waitcnt lgkmcnt(0)
	v_add_f32_dpp v130, v130, v130 quad_perm:[2,3,0,1] row_mask:0xf bank_mask:0xf
	v_fmamk_f32 v130, v130, 0x3a800000, v200
	v_rsq_f32_e32 v162, v130
	v_add_u32_e32 v130, 0x60, v160
	v_lshlrev_b32_e32 v131, 1, v130
	v_and_b32_e32 v131, 0xffffff80, v131
	v_and_or_b32 v130, v130, 63, s10
	v_add_u32_e32 v130, v130, v131
	v_ashrrev_i32_e32 v131, 31, v130
	v_lshlrev_b64 v[130:131], 6, v[130:131]
	v_lshl_add_u64 v[130:131], v[128:129], 0, v[130:131]
	s_waitcnt vmcnt(0)
	v_add_f32_e32 v130, v206, v207
	v_add_f32_e32 v131, v208, v209
	v_add_f32_e32 v130, v130, v131
	s_nop 1
	s_waitcnt lgkmcnt(0)
	v_add_f32_dpp v130, v130, v130 quad_perm:[1,0,3,2] row_mask:0xf bank_mask:0xf
	s_nop 1
	s_waitcnt lgkmcnt(0)
	v_add_f32_dpp v130, v130, v130 quad_perm:[2,3,0,1] row_mask:0xf bank_mask:0xf
	v_fmamk_f32 v130, v130, 0x3a800000, v200
	v_rsq_f32_e32 v156, v130
	v_add_u32_e32 v130, 0x70, v160
	v_lshlrev_b32_e32 v131, 1, v130
	v_and_b32_e32 v131, 0xffffff80, v131
	v_and_or_b32 v130, v130, 63, s10
	v_add_u32_e32 v130, v130, v131
	v_ashrrev_i32_e32 v131, 31, v130
	v_lshlrev_b64 v[130:131], 6, v[130:131]
	v_lshl_add_u64 v[128:129], v[128:129], 0, v[130:131]
	s_waitcnt vmcnt(0)
	v_add_f32_e32 v128, v210, v211
	v_add_f32_e32 v129, v212, v213
	v_add_f32_e32 v128, v128, v129
	s_nop 1
	s_waitcnt lgkmcnt(0)
	v_add_f32_dpp v128, v128, v128 quad_perm:[1,0,3,2] row_mask:0xf bank_mask:0xf
	s_nop 1
	s_waitcnt lgkmcnt(0)
	v_add_f32_dpp v128, v128, v128 quad_perm:[2,3,0,1] row_mask:0xf bank_mask:0xf
	v_fmamk_f32 v128, v128, 0x3a800000, v200
	v_rsq_f32_e32 v128, v128
	v_lshlrev_b32_e32 v129, 2, v142
	v_and_or_b32 v129, v129, 60, v143
	v_lshlrev_b32_e32 v146, 2, v129
	ds_bpermute_b32 v145, v146, v144
	ds_bpermute_b32 v144, v146, v147
	ds_bpermute_b32 v143, v146, v148
	ds_bpermute_b32 v142, v146, v149
	ds_bpermute_b32 v131, v146, v161
	ds_bpermute_b32 v130, v146, v162
	ds_bpermute_b32 v129, v146, v156
	ds_bpermute_b32 v128, v146, v128
	s_and_saveexec_b64 s[16:17], s[40:41]
	s_cbranch_execz .LBB0_1149
	s_waitcnt lgkmcnt(7)
	v_mul_f32_e32 v146, 0xbfb8aa3b, v145
	v_mul_f32_e32 v145, v145, v145
	s_waitcnt lgkmcnt(6)
	v_mul_f32_e32 v147, 0xbfb8aa3b, v144
	v_mul_f32_e32 v144, v144, v144
	v_rcp_f32_e32 v145, v145
	v_rcp_f32_e32 v144, v144
	ds_write2_b32 v153, v146, v147 offset1:16
	v_add_u32_e32 v146, 0x1000, v153
	ds_write2_b32 v146, v145, v144 offset1:16
	s_waitcnt lgkmcnt(7)
	v_mul_f32_e32 v144, 0xbfb8aa3b, v143
	v_mul_f32_e32 v143, v143, v143
	s_waitcnt lgkmcnt(6)
	v_mul_f32_e32 v145, 0xbfb8aa3b, v142
	v_mul_f32_e32 v142, v142, v142
	v_rcp_f32_e32 v143, v143
	v_rcp_f32_e32 v142, v142
	ds_write2_b32 v153, v144, v145 offset0:32 offset1:48
	ds_write2_b32 v146, v143, v142 offset0:32 offset1:48
	s_waitcnt lgkmcnt(7)
	v_mul_f32_e32 v142, 0xbfb8aa3b, v131
	v_mul_f32_e32 v131, v131, v131
	s_waitcnt lgkmcnt(6)
	v_mul_f32_e32 v143, 0xbfb8aa3b, v130
	v_mul_f32_e32 v130, v130, v130
	v_rcp_f32_e32 v131, v131
	v_rcp_f32_e32 v130, v130
	ds_write2_b32 v153, v142, v143 offset0:64 offset1:80
	ds_write2_b32 v146, v131, v130 offset0:64 offset1:80
	s_waitcnt lgkmcnt(7)
	v_mul_f32_e32 v130, 0xbfb8aa3b, v129
	v_mul_f32_e32 v129, v129, v129
	s_waitcnt lgkmcnt(6)
	v_mul_f32_e32 v131, 0xbfb8aa3b, v128
	v_mul_f32_e32 v128, v128, v128
	v_rcp_f32_e32 v129, v129
	v_rcp_f32_e32 v128, v128
	ds_write2_b32 v153, v130, v131 offset0:96 offset1:112
	ds_write2_b32 v146, v129, v128 offset0:96 offset1:112

.LBB0_1228:
	v_lshl_or_b32 v166, s58, 8, v205
	v_lshl_add_u32 v170, s59, 8, v198
	v_ashrrev_i32_e32 v167, 31, v166
	v_lshlrev_b64 v[202:203], 1, v[166:167]
	v_ashrrev_i32_e32 v171, 31, v170
	v_lshl_add_u64 v[168:169], s[16:17], 0, v[202:203]
	v_lshlrev_b64 v[214:215], 11, v[170:171]
	v_lshl_add_u64 v[128:129], v[168:169], 0, v[214:215]
	global_load_dwordx4 v[210:213], v[128:129], off
	global_load_dwordx4 v[152:155], v[128:129], off offset:256
	v_or_b32_e32 v194, 16, v170
	v_ashrrev_i32_e32 v195, 31, v194
	v_or_b32_e32 v176, 32, v170
	v_lshlrev_b64 v[196:197], 11, v[194:195]
	v_ashrrev_i32_e32 v177, 31, v176
	v_or_b32_e32 v172, 48, v170
	v_lshl_add_u64 v[128:129], v[168:169], 0, v[196:197]
	v_lshlrev_b64 v[178:179], 11, v[176:177]
	v_ashrrev_i32_e32 v173, 31, v172
	global_load_dwordx4 v[148:151], v[128:129], off
	global_load_dwordx4 v[144:147], v[128:129], off offset:256
	v_lshl_add_u64 v[128:129], v[168:169], 0, v[178:179]
	v_lshlrev_b64 v[174:175], 11, v[172:173]
	global_load_dwordx4 v[140:143], v[128:129], off
	global_load_dwordx4 v[136:139], v[128:129], off offset:256
	v_lshl_add_u64 v[128:129], v[168:169], 0, v[174:175]
	global_load_dwordx4 v[132:135], v[128:129], off
	s_nop 0
	global_load_dwordx4 v[128:131], v[128:129], off offset:256
	v_lshlrev_b32_e32 v250, 2, v218
	v_add_u32_e32 v250, 0x20400, v250
	ds_write_b32 v250, v240
	v_add_u32_e32 v250, 0x80, v170
	v_ashrrev_i32_e32 v251, 31, v250
	v_lshlrev_b64 v[250:251], 11, v[250:251]
	v_lshl_add_u64 v[250:251], v[168:169], 0, v[250:251]
	global_load_dwordx4 v[222:225], v[250:251], off
	global_load_dwordx4 v[226:229], v[250:251], off offset:256
	v_add_u32_e32 v250, 0x90, v170
	v_ashrrev_i32_e32 v251, 31, v250
	v_lshlrev_b64 v[250:251], 11, v[250:251]
	v_lshl_add_u64 v[250:251], v[168:169], 0, v[250:251]
	global_load_dwordx4 v[230:233], v[250:251], off
	global_load_dwordx4 v[234:237], v[250:251], off offset:256
	v_add_u32_e32 v250, 0xa0, v170
	v_ashrrev_i32_e32 v251, 31, v250
	v_lshlrev_b64 v[250:251], 11, v[250:251]
	v_lshl_add_u64 v[250:251], v[168:169], 0, v[250:251]
	global_load_dwordx4 v[238:241], v[250:251], off
	global_load_dwordx4 v[242:245], v[250:251], off offset:256
	v_add_u32_e32 v250, 0xb0, v170
	v_ashrrev_i32_e32 v251, 31, v250
	v_lshlrev_b64 v[250:251], 11, v[250:251]
	v_lshl_add_u64 v[250:251], v[168:169], 0, v[250:251]
	global_load_dwordx4 v[246:249], v[250:251], off
	v_and_b32_e32 v208, 64, v219
	v_xor_b32_e32 v207, 16, v219
	v_add_u32_e32 v208, 64, v208
	v_cmp_lt_i32_e32 vcc, v207, v208
	v_xor_b32_e32 v209, 32, v219
	s_lshl_b32 s26, s58, 2
	v_cndmask_b32_e32 v207, v219, v207, vcc
	v_cmp_lt_i32_e32 vcc, v209, v208
	v_lshlrev_b32_e32 v207, 2, v207
	s_ashr_i32 s27, s26, 31
	v_cndmask_b32_e32 v208, v219, v209, vcc
	v_lshlrev_b32_e32 v208, 2, v208
	s_waitcnt vmcnt(0)
	v_lshlrev_b32_e32 v216, 16, v210
	v_and_b32_e32 v217, 0xffff0000, v210
	v_lshlrev_b32_e32 v210, 16, v211
	v_and_b32_e32 v211, 0xffff0000, v211
	v_lshlrev_b32_e32 v220, 16, v212
	v_and_b32_e32 v221, 0xffff0000, v212
	v_lshlrev_b32_e32 v212, 16, v213
	v_and_b32_e32 v213, 0xffff0000, v213
	v_pk_add_f32 v[210:211], v[122:123], v[210:211]
	v_pk_add_f32 v[216:217], v[120:121], v[216:217]
	v_pk_add_f32 v[126:127], v[126:127], v[212:213]
	v_pk_add_f32 v[124:125], v[124:125], v[220:221]
	v_lshl_add_u64 v[212:213], s[16:17], 0, v[214:215]
	v_cvt_pk_bf16_f32 v120, v216, v217
	v_cvt_pk_bf16_f32 v121, v210, v211
	v_cvt_pk_bf16_f32 v122, v124, v125
	v_cvt_pk_bf16_f32 v123, v126, v127
	v_lshl_add_u64 v[202:203], v[212:213], 0, v[202:203]
	global_store_dwordx4 v[202:203], v[120:123], off
	s_nop 1
	v_mul_f32_e32 v120, v217, v217
	v_mul_f32_e32 v121, v211, v211
	v_fmac_f32_e32 v120, v216, v216
	v_fmac_f32_e32 v121, v210, v210
	v_add_f32_e32 v120, v120, v121
	v_mul_f32_e32 v121, v125, v125
	v_mul_f32_e32 v122, v127, v127
	v_fmac_f32_e32 v121, v124, v124
	v_fmac_f32_e32 v122, v126, v126
	v_add_f32_e32 v121, v121, v122
	v_add_f32_e32 v209, v120, v121
	v_lshlrev_b32_e32 v120, 16, v152
	v_and_b32_e32 v121, 0xffff0000, v152
	v_lshlrev_b32_e32 v122, 16, v153
	v_and_b32_e32 v123, 0xffff0000, v153
	v_lshlrev_b32_e32 v124, 16, v154
	v_and_b32_e32 v125, 0xffff0000, v154
	v_lshlrev_b32_e32 v126, 16, v155
	v_and_b32_e32 v127, 0xffff0000, v155
	v_pk_add_f32 v[118:119], v[118:119], v[122:123]
	v_pk_add_f32 v[116:117], v[116:117], v[120:121]
	v_pk_add_f32 v[120:121], v[114:115], v[126:127]
	v_pk_add_f32 v[122:123], v[112:113], v[124:125]
	v_cvt_pk_bf16_f32 v112, v116, v117
	v_cvt_pk_bf16_f32 v113, v118, v119
	v_cvt_pk_bf16_f32 v114, v122, v123
	v_cvt_pk_bf16_f32 v115, v120, v121
	global_store_dwordx4 v[202:203], v[112:115], off offset:256
	s_nop 1
	v_mul_f32_e32 v112, v117, v117
	v_mul_f32_e32 v113, v119, v119
	v_fmac_f32_e32 v112, v116, v116
	v_fmac_f32_e32 v113, v118, v118
	v_add_f32_e32 v112, v112, v113
	v_mul_f32_e32 v113, v123, v123
	v_mul_f32_e32 v114, v121, v121
	v_fmac_f32_e32 v113, v122, v122
	v_fmac_f32_e32 v114, v120, v120
	v_add_f32_e32 v113, v113, v114
	v_add_f32_e32 v112, v112, v113
	v_add_f32_e32 v112, v209, v112
	v_mov_b32_e32 v113, v112
	v_mov_b32_e32 v251, v112
	s_nop 1
	v_permlane16_swap_b32_e32 v113, v251
	s_waitcnt lgkmcnt(0)
	v_add_f32_e32 v112, v113, v251
	v_mov_b32_e32 v113, v112
	v_mov_b32_e32 v251, v112
	s_nop 1
	v_permlane32_swap_b32_e32 v113, v251
	s_and_saveexec_b64 s[10:11], s[40:41]
	s_cbranch_execz .LBB0_1230
	s_waitcnt lgkmcnt(0)
	v_add_f32_e32 v114, v113, v251
	v_lshlrev_b64 v[112:113], 6, v[170:171]
	v_lshl_add_u64 v[112:113], s[0:1], 0, v[112:113]
	v_lshl_add_u64 v[112:113], s[26:27], 2, v[112:113]
	s_lshl_b32 s64, s39, 2
	v_lshl_add_u64 v[112:113], v[112:113], 0, s[64:65]
	global_store_dword v[112:113], v114, off
.LBB0_1230:
	s_or_b64 exec, exec, s[10:11]
	v_lshlrev_b32_e32 v112, 16, v148
	s_waitcnt lgkmcnt(0)
	v_and_b32_e32 v113, 0xffff0000, v148
	v_lshlrev_b32_e32 v114, 16, v149
	v_and_b32_e32 v115, 0xffff0000, v149
	v_lshlrev_b32_e32 v116, 16, v150
	v_and_b32_e32 v117, 0xffff0000, v150
	v_pk_add_f32 v[108:109], v[108:109], v[112:113]
	v_pk_add_f32 v[110:111], v[110:111], v[114:115]
	v_pk_add_f32 v[114:115], v[104:105], v[116:117]
	v_cvt_pk_bf16_f32 v104, v108, v109
	v_mul_f32_e32 v109, v109, v109
	v_lshlrev_b32_e32 v118, 16, v151
	v_and_b32_e32 v119, 0xffff0000, v151
	v_fmac_f32_e32 v109, v108, v108
	v_mul_f32_e32 v108, v111, v111
	v_pk_add_f32 v[112:113], v[106:107], v[118:119]
	v_fmac_f32_e32 v108, v110, v110
	v_cvt_pk_bf16_f32 v105, v110, v111
	v_add_f32_e32 v108, v109, v108
	v_mul_f32_e32 v109, v115, v115
	v_mul_f32_e32 v110, v113, v113
	v_fmac_f32_e32 v109, v114, v114
	v_fmac_f32_e32 v110, v112, v112
	v_add_f32_e32 v109, v109, v110
	v_add_f32_e32 v116, v108, v109
	v_lshlrev_b32_e32 v108, 16, v144
	v_and_b32_e32 v109, 0xffff0000, v144
	v_lshlrev_b32_e32 v110, 16, v145
	v_and_b32_e32 v111, 0xffff0000, v145
	v_cvt_pk_bf16_f32 v107, v112, v113
	v_lshlrev_b32_e32 v112, 16, v146
	v_and_b32_e32 v113, 0xffff0000, v146
	v_pk_add_f32 v[102:103], v[102:103], v[110:111]
	v_pk_add_f32 v[100:101], v[100:101], v[108:109]
	v_cvt_pk_bf16_f32 v106, v114, v115
	v_lshlrev_b32_e32 v114, 16, v147
	v_and_b32_e32 v115, 0xffff0000, v147
	v_pk_add_f32 v[110:111], v[96:97], v[112:113]
	v_mul_f32_e32 v96, v101, v101
	v_mul_f32_e32 v97, v103, v103
	v_pk_add_f32 v[108:109], v[98:99], v[114:115]
	v_fmac_f32_e32 v96, v100, v100
	v_fmac_f32_e32 v97, v102, v102
	v_add_f32_e32 v96, v96, v97
	v_mul_f32_e32 v97, v111, v111
	v_mul_f32_e32 v98, v109, v109
	v_fmac_f32_e32 v97, v110, v110
	v_fmac_f32_e32 v98, v108, v108
	v_add_f32_e32 v97, v97, v98
	v_add_f32_e32 v96, v96, v97
	v_add_f32_e32 v99, v116, v96
	v_mov_b32_e32 v114, v99
	v_mov_b32_e32 v251, v99
	s_nop 1
	v_permlane16_swap_b32_e32 v114, v251
	v_lshl_add_u64 v[96:97], s[16:17], 0, v[196:197]
	v_lshl_add_u64 v[112:113], v[166:167], 1, v[96:97]
	v_cvt_pk_bf16_f32 v98, v100, v101
	v_cvt_pk_bf16_f32 v100, v110, v111
	s_waitcnt lgkmcnt(0)
	v_add_f32_e32 v96, v114, v251
	v_mov_b32_e32 v97, v96
	v_mov_b32_e32 v251, v96
	s_nop 1
	v_permlane32_swap_b32_e32 v97, v251
	v_cvt_pk_bf16_f32 v99, v102, v103
	v_cvt_pk_bf16_f32 v101, v108, v109
	global_store_dwordx4 v[112:113], v[104:107], off
	global_store_dwordx4 v[112:113], v[98:101], off offset:256
	s_and_saveexec_b64 s[10:11], s[40:41]
	s_cbranch_execz .LBB0_1232
	s_waitcnt lgkmcnt(0)
	v_add_f32_e32 v98, v97, v251
	v_lshlrev_b64 v[96:97], 6, v[194:195]
	v_lshl_add_u64 v[96:97], s[0:1], 0, v[96:97]
	v_lshl_add_u64 v[96:97], s[26:27], 2, v[96:97]
	s_lshl_b32 s64, s39, 2
	v_lshl_add_u64 v[96:97], v[96:97], 0, s[64:65]
	global_store_dword v[96:97], v98, off
.LBB0_1232:
	s_or_b64 exec, exec, s[10:11]
	v_lshlrev_b32_e32 v96, 16, v140
	s_waitcnt lgkmcnt(0)
	v_and_b32_e32 v97, 0xffff0000, v140
	v_lshlrev_b32_e32 v98, 16, v141
	v_and_b32_e32 v99, 0xffff0000, v141
	v_lshlrev_b32_e32 v100, 16, v142
	v_and_b32_e32 v101, 0xffff0000, v142
	v_pk_add_f32 v[92:93], v[92:93], v[96:97]
	v_pk_add_f32 v[94:95], v[94:95], v[98:99]
	v_pk_add_f32 v[98:99], v[88:89], v[100:101]
	v_cvt_pk_bf16_f32 v88, v92, v93
	v_mul_f32_e32 v93, v93, v93
	v_lshlrev_b32_e32 v102, 16, v143
	v_and_b32_e32 v103, 0xffff0000, v143
	v_fmac_f32_e32 v93, v92, v92
	v_mul_f32_e32 v92, v95, v95
	v_pk_add_f32 v[96:97], v[90:91], v[102:103]
	v_fmac_f32_e32 v92, v94, v94
	v_cvt_pk_bf16_f32 v89, v94, v95
	v_add_f32_e32 v92, v93, v92
	v_mul_f32_e32 v93, v99, v99
	v_mul_f32_e32 v94, v97, v97
	v_fmac_f32_e32 v93, v98, v98
	v_fmac_f32_e32 v94, v96, v96
	v_add_f32_e32 v93, v93, v94
	v_add_f32_e32 v100, v92, v93
	v_lshlrev_b32_e32 v92, 16, v136
	v_and_b32_e32 v93, 0xffff0000, v136
	v_lshlrev_b32_e32 v94, 16, v137
	v_and_b32_e32 v95, 0xffff0000, v137
	v_cvt_pk_bf16_f32 v91, v96, v97
	v_lshlrev_b32_e32 v96, 16, v138
	v_and_b32_e32 v97, 0xffff0000, v138
	v_pk_add_f32 v[86:87], v[86:87], v[94:95]
	v_pk_add_f32 v[84:85], v[84:85], v[92:93]
	v_cvt_pk_bf16_f32 v90, v98, v99
	v_lshlrev_b32_e32 v98, 16, v139
	v_and_b32_e32 v99, 0xffff0000, v139
	v_pk_add_f32 v[94:95], v[80:81], v[96:97]
	v_mul_f32_e32 v80, v85, v85
	v_mul_f32_e32 v81, v87, v87
	v_pk_add_f32 v[92:93], v[82:83], v[98:99]
	v_fmac_f32_e32 v80, v84, v84
	v_fmac_f32_e32 v81, v86, v86
	v_add_f32_e32 v80, v80, v81
	v_mul_f32_e32 v81, v95, v95
	v_mul_f32_e32 v82, v93, v93
	v_fmac_f32_e32 v81, v94, v94
	v_fmac_f32_e32 v82, v92, v92
	v_add_f32_e32 v81, v81, v82
	v_add_f32_e32 v80, v80, v81
	v_add_f32_e32 v83, v100, v80
	v_mov_b32_e32 v98, v83
	v_mov_b32_e32 v251, v83
	s_nop 1
	v_permlane16_swap_b32_e32 v98, v251
	v_lshl_add_u64 v[80:81], s[16:17], 0, v[178:179]
	v_lshl_add_u64 v[96:97], v[166:167], 1, v[80:81]
	v_cvt_pk_bf16_f32 v82, v84, v85
	v_cvt_pk_bf16_f32 v84, v94, v95
	s_waitcnt lgkmcnt(0)
	v_add_f32_e32 v80, v98, v251
	v_mov_b32_e32 v81, v80
	v_mov_b32_e32 v251, v80
	s_nop 1
	v_permlane32_swap_b32_e32 v81, v251
	v_cvt_pk_bf16_f32 v83, v86, v87
	v_cvt_pk_bf16_f32 v85, v92, v93
	global_store_dwordx4 v[96:97], v[88:91], off
	global_store_dwordx4 v[96:97], v[82:85], off offset:256
	s_and_saveexec_b64 s[10:11], s[40:41]
	s_cbranch_execz .LBB0_1234
	s_waitcnt lgkmcnt(0)
	v_add_f32_e32 v82, v81, v251
	v_lshlrev_b64 v[80:81], 6, v[176:177]
	v_lshl_add_u64 v[80:81], s[0:1], 0, v[80:81]
	v_lshl_add_u64 v[80:81], s[26:27], 2, v[80:81]
	s_lshl_b32 s64, s39, 2
	v_lshl_add_u64 v[80:81], v[80:81], 0, s[64:65]
	global_store_dword v[80:81], v82, off
.LBB0_1234:
	s_or_b64 exec, exec, s[10:11]
	v_lshlrev_b32_e32 v80, 16, v132
	s_waitcnt lgkmcnt(0)
	v_and_b32_e32 v81, 0xffff0000, v132
	v_lshlrev_b32_e32 v82, 16, v133
	v_and_b32_e32 v83, 0xffff0000, v133
	v_lshlrev_b32_e32 v84, 16, v134
	v_and_b32_e32 v85, 0xffff0000, v134
	v_pk_add_f32 v[76:77], v[76:77], v[80:81]
	v_pk_add_f32 v[78:79], v[78:79], v[82:83]
	v_pk_add_f32 v[82:83], v[72:73], v[84:85]
	v_cvt_pk_bf16_f32 v72, v76, v77
	v_mul_f32_e32 v77, v77, v77
	v_lshlrev_b32_e32 v86, 16, v135
	v_and_b32_e32 v87, 0xffff0000, v135
	v_fmac_f32_e32 v77, v76, v76
	v_mul_f32_e32 v76, v79, v79
	v_pk_add_f32 v[80:81], v[74:75], v[86:87]
	v_fmac_f32_e32 v76, v78, v78
	v_cvt_pk_bf16_f32 v73, v78, v79
	v_add_f32_e32 v76, v77, v76
	v_mul_f32_e32 v77, v83, v83
	v_mul_f32_e32 v78, v81, v81
	v_fmac_f32_e32 v77, v82, v82
	v_fmac_f32_e32 v78, v80, v80
	v_add_f32_e32 v77, v77, v78
	v_add_f32_e32 v84, v76, v77
	v_lshlrev_b32_e32 v76, 16, v128
	v_and_b32_e32 v77, 0xffff0000, v128
	v_lshlrev_b32_e32 v78, 16, v129
	v_and_b32_e32 v79, 0xffff0000, v129
	v_cvt_pk_bf16_f32 v75, v80, v81
	v_lshlrev_b32_e32 v80, 16, v130
	v_and_b32_e32 v81, 0xffff0000, v130
	v_pk_add_f32 v[70:71], v[70:71], v[78:79]
	v_pk_add_f32 v[68:69], v[68:69], v[76:77]
	v_cvt_pk_bf16_f32 v74, v82, v83
	v_lshlrev_b32_e32 v82, 16, v131
	v_and_b32_e32 v83, 0xffff0000, v131
	v_pk_add_f32 v[78:79], v[64:65], v[80:81]
	v_mul_f32_e32 v64, v69, v69
	v_mul_f32_e32 v65, v71, v71
	v_pk_add_f32 v[76:77], v[66:67], v[82:83]
	v_fmac_f32_e32 v64, v68, v68
	v_fmac_f32_e32 v65, v70, v70
	v_add_f32_e32 v64, v64, v65
	v_mul_f32_e32 v65, v79, v79
	v_mul_f32_e32 v66, v77, v77
	v_fmac_f32_e32 v65, v78, v78
	v_fmac_f32_e32 v66, v76, v76
	v_add_f32_e32 v65, v65, v66
	v_add_f32_e32 v64, v64, v65
	v_add_f32_e32 v67, v84, v64
	v_mov_b32_e32 v82, v67
	v_mov_b32_e32 v251, v67
	s_nop 1
	v_permlane16_swap_b32_e32 v82, v251
	v_lshl_add_u64 v[64:65], s[16:17], 0, v[174:175]
	v_lshl_add_u64 v[80:81], v[166:167], 1, v[64:65]
	v_cvt_pk_bf16_f32 v66, v68, v69
	v_cvt_pk_bf16_f32 v68, v78, v79
	s_waitcnt lgkmcnt(0)
	v_add_f32_e32 v64, v82, v251
	v_mov_b32_e32 v65, v64
	v_mov_b32_e32 v251, v64
	s_nop 1
	v_permlane32_swap_b32_e32 v65, v251
	v_cvt_pk_bf16_f32 v67, v70, v71
	v_cvt_pk_bf16_f32 v69, v76, v77
	global_store_dwordx4 v[80:81], v[72:75], off
	global_store_dwordx4 v[80:81], v[66:69], off offset:256
	s_and_saveexec_b64 s[10:11], s[40:41]
	s_cbranch_execz .LBB0_1236
	s_waitcnt lgkmcnt(0)
	v_add_f32_e32 v66, v65, v251
	v_lshlrev_b64 v[64:65], 6, v[172:173]
	v_lshl_add_u64 v[64:65], s[0:1], 0, v[64:65]
	v_lshl_add_u64 v[64:65], s[26:27], 2, v[64:65]
	s_lshl_b32 s64, s39, 2
	v_lshl_add_u64 v[64:65], v[64:65], 0, s[64:65]
	global_store_dword v[64:65], v66, off
.LBB0_1236:
	s_or_b64 exec, exec, s[10:11]
	v_add_u32_e32 v104, 0x80, v170
	v_ashrrev_i32_e32 v105, 31, v104
	v_lshlrev_b64 v[110:111], 11, v[104:105]
	s_waitcnt lgkmcnt(0)
	v_lshl_add_u64 v[64:65], v[168:169], 0, v[110:111]
	v_add_u32_e32 v100, 0x90, v170
	v_ashrrev_i32_e32 v101, 31, v100
	v_add_u32_e32 v96, 0xa0, v170
	v_lshlrev_b64 v[102:103], 11, v[100:101]
	v_ashrrev_i32_e32 v97, 31, v96
	v_add_u32_e32 v92, 0xb0, v170
	v_lshl_add_u64 v[64:65], v[168:169], 0, v[102:103]
	v_lshlrev_b64 v[98:99], 11, v[96:97]
	v_ashrrev_i32_e32 v93, 31, v92
	v_lshl_add_u64 v[64:65], v[168:169], 0, v[98:99]
	v_lshlrev_b64 v[94:95], 11, v[92:93]
	v_lshl_add_u64 v[64:65], v[168:169], 0, v[94:95]
	s_nop 0
	global_load_dwordx4 v[64:67], v[64:65], off offset:256
	v_lshl_add_u64 v[110:111], s[16:17], 0, v[110:111]
	v_lshl_add_u64 v[110:111], v[166:167], 1, v[110:111]
	v_lshlrev_b32_e32 v112, 16, v222
	v_and_b32_e32 v113, 0xffff0000, v222
	v_lshlrev_b32_e32 v106, 16, v223
	v_and_b32_e32 v107, 0xffff0000, v223
	v_lshlrev_b32_e32 v114, 16, v224
	v_and_b32_e32 v115, 0xffff0000, v224
	v_lshlrev_b32_e32 v108, 16, v225
	v_and_b32_e32 v109, 0xffff0000, v225
	v_pk_add_f32 v[62:63], v[62:63], v[106:107]
	v_pk_add_f32 v[60:61], v[60:61], v[112:113]
	v_pk_add_f32 v[106:107], v[58:59], v[108:109]
	v_pk_add_f32 v[108:109], v[56:57], v[114:115]
	v_cvt_pk_bf16_f32 v56, v60, v61
	v_cvt_pk_bf16_f32 v57, v62, v63
	v_cvt_pk_bf16_f32 v58, v108, v109
	v_cvt_pk_bf16_f32 v59, v106, v107
	global_store_dwordx4 v[110:111], v[56:59], off
	s_nop 1
	v_mul_f32_e32 v56, v61, v61
	v_mul_f32_e32 v57, v63, v63
	v_fmac_f32_e32 v56, v60, v60
	v_fmac_f32_e32 v57, v62, v62
	v_add_f32_e32 v56, v56, v57
	v_mul_f32_e32 v57, v109, v109
	v_mul_f32_e32 v58, v107, v107
	v_fmac_f32_e32 v57, v108, v108
	v_fmac_f32_e32 v58, v106, v106
	v_add_f32_e32 v57, v57, v58
	v_add_f32_e32 v106, v56, v57
	v_lshlrev_b32_e32 v56, 16, v226
	v_and_b32_e32 v57, 0xffff0000, v226
	v_lshlrev_b32_e32 v58, 16, v227
	v_and_b32_e32 v59, 0xffff0000, v227
	v_lshlrev_b32_e32 v60, 16, v228
	v_and_b32_e32 v61, 0xffff0000, v228
	v_lshlrev_b32_e32 v62, 16, v229
	v_and_b32_e32 v63, 0xffff0000, v229
	v_pk_add_f32 v[54:55], v[54:55], v[58:59]
	v_pk_add_f32 v[52:53], v[52:53], v[56:57]
	v_pk_add_f32 v[56:57], v[50:51], v[62:63]
	v_pk_add_f32 v[58:59], v[48:49], v[60:61]
	v_cvt_pk_bf16_f32 v48, v52, v53
	v_cvt_pk_bf16_f32 v49, v54, v55
	v_cvt_pk_bf16_f32 v50, v58, v59
	v_cvt_pk_bf16_f32 v51, v56, v57
	global_store_dwordx4 v[110:111], v[48:51], off offset:256
	s_nop 1
	v_mul_f32_e32 v48, v53, v53
	v_mul_f32_e32 v49, v55, v55
	v_fmac_f32_e32 v48, v52, v52
	v_fmac_f32_e32 v49, v54, v54
	v_add_f32_e32 v48, v48, v49
	v_mul_f32_e32 v49, v59, v59
	v_mul_f32_e32 v50, v57, v57
	v_fmac_f32_e32 v49, v58, v58
	v_fmac_f32_e32 v50, v56, v56
	v_add_f32_e32 v49, v49, v50
	v_add_f32_e32 v48, v48, v49
	v_add_f32_e32 v48, v106, v48
	v_mov_b32_e32 v49, v48
	v_mov_b32_e32 v251, v48
	s_nop 1
	v_permlane16_swap_b32_e32 v49, v251
	s_waitcnt lgkmcnt(0)
	v_add_f32_e32 v48, v49, v251
	v_mov_b32_e32 v49, v48
	v_mov_b32_e32 v251, v48
	s_nop 1
	v_permlane32_swap_b32_e32 v49, v251
	s_and_saveexec_b64 s[10:11], s[40:41]
	s_cbranch_execz .LBB0_1238
	s_waitcnt lgkmcnt(0)
	v_add_f32_e32 v50, v49, v251
	v_lshlrev_b64 v[48:49], 6, v[104:105]
	v_lshl_add_u64 v[48:49], s[0:1], 0, v[48:49]
	v_lshl_add_u64 v[48:49], s[26:27], 2, v[48:49]
	s_lshl_b32 s64, s39, 2
	v_lshl_add_u64 v[48:49], v[48:49], 0, s[64:65]
	global_store_dword v[48:49], v50, off
.LBB0_1238:
	s_or_b64 exec, exec, s[10:11]
	v_lshlrev_b32_e32 v48, 16, v230
	s_waitcnt lgkmcnt(0)
	v_and_b32_e32 v49, 0xffff0000, v230
	v_lshlrev_b32_e32 v50, 16, v231
	v_and_b32_e32 v51, 0xffff0000, v231
	v_lshlrev_b32_e32 v52, 16, v232
	v_and_b32_e32 v53, 0xffff0000, v232
	v_pk_add_f32 v[44:45], v[44:45], v[48:49]
	v_pk_add_f32 v[46:47], v[46:47], v[50:51]
	v_pk_add_f32 v[50:51], v[40:41], v[52:53]
	v_cvt_pk_bf16_f32 v40, v44, v45
	v_mul_f32_e32 v45, v45, v45
	v_lshlrev_b32_e32 v54, 16, v233
	v_and_b32_e32 v55, 0xffff0000, v233
	v_fmac_f32_e32 v45, v44, v44
	v_mul_f32_e32 v44, v47, v47
	v_pk_add_f32 v[48:49], v[42:43], v[54:55]
	v_fmac_f32_e32 v44, v46, v46
	v_cvt_pk_bf16_f32 v41, v46, v47
	v_add_f32_e32 v44, v45, v44
	v_mul_f32_e32 v45, v51, v51
	v_mul_f32_e32 v46, v49, v49
	v_fmac_f32_e32 v45, v50, v50
	v_fmac_f32_e32 v46, v48, v48
	v_add_f32_e32 v45, v45, v46
	v_add_f32_e32 v52, v44, v45
	v_lshlrev_b32_e32 v44, 16, v234
	v_and_b32_e32 v45, 0xffff0000, v234
	v_lshlrev_b32_e32 v46, 16, v235
	v_and_b32_e32 v47, 0xffff0000, v235
	v_cvt_pk_bf16_f32 v43, v48, v49
	v_lshlrev_b32_e32 v48, 16, v236
	v_and_b32_e32 v49, 0xffff0000, v236
	v_pk_add_f32 v[38:39], v[38:39], v[46:47]
	v_pk_add_f32 v[36:37], v[36:37], v[44:45]
	v_cvt_pk_bf16_f32 v42, v50, v51
	v_lshlrev_b32_e32 v50, 16, v237
	v_and_b32_e32 v51, 0xffff0000, v237
	v_pk_add_f32 v[46:47], v[32:33], v[48:49]
	v_mul_f32_e32 v32, v37, v37
	v_mul_f32_e32 v33, v39, v39
	v_pk_add_f32 v[44:45], v[34:35], v[50:51]
	v_fmac_f32_e32 v32, v36, v36
	v_fmac_f32_e32 v33, v38, v38
	v_add_f32_e32 v32, v32, v33
	v_mul_f32_e32 v33, v47, v47
	v_mul_f32_e32 v34, v45, v45
	v_fmac_f32_e32 v33, v46, v46
	v_fmac_f32_e32 v34, v44, v44
	v_add_f32_e32 v33, v33, v34
	v_add_f32_e32 v32, v32, v33
	v_add_f32_e32 v35, v52, v32
	v_mov_b32_e32 v50, v35
	v_mov_b32_e32 v251, v35
	s_nop 1
	v_permlane16_swap_b32_e32 v50, v251
	v_lshl_add_u64 v[32:33], s[16:17], 0, v[102:103]
	v_lshl_add_u64 v[48:49], v[166:167], 1, v[32:33]
	v_cvt_pk_bf16_f32 v34, v36, v37
	v_cvt_pk_bf16_f32 v36, v46, v47
	s_waitcnt lgkmcnt(0)
	v_add_f32_e32 v32, v50, v251
	v_mov_b32_e32 v33, v32
	v_mov_b32_e32 v251, v32
	s_nop 1
	v_permlane32_swap_b32_e32 v33, v251
	v_cvt_pk_bf16_f32 v35, v38, v39
	v_cvt_pk_bf16_f32 v37, v44, v45
	global_store_dwordx4 v[48:49], v[40:43], off
	global_store_dwordx4 v[48:49], v[34:37], off offset:256
	s_and_saveexec_b64 s[10:11], s[40:41]
	s_cbranch_execz .LBB0_1240
	s_waitcnt lgkmcnt(0)
	v_add_f32_e32 v34, v33, v251
	v_lshlrev_b64 v[32:33], 6, v[100:101]
	v_lshl_add_u64 v[32:33], s[0:1], 0, v[32:33]
	v_lshl_add_u64 v[32:33], s[26:27], 2, v[32:33]
	s_lshl_b32 s64, s39, 2
	v_lshl_add_u64 v[32:33], v[32:33], 0, s[64:65]
	global_store_dword v[32:33], v34, off
.LBB0_1240:
	s_or_b64 exec, exec, s[10:11]
	v_lshlrev_b32_e32 v32, 16, v238
	s_waitcnt lgkmcnt(0)
	v_and_b32_e32 v33, 0xffff0000, v238
	v_lshlrev_b32_e32 v34, 16, v239
	v_and_b32_e32 v35, 0xffff0000, v239
	v_lshlrev_b32_e32 v36, 16, v240
	v_and_b32_e32 v37, 0xffff0000, v240
	v_pk_add_f32 v[28:29], v[28:29], v[32:33]
	v_pk_add_f32 v[30:31], v[30:31], v[34:35]
	v_pk_add_f32 v[34:35], v[24:25], v[36:37]
	v_cvt_pk_bf16_f32 v24, v28, v29
	v_mul_f32_e32 v29, v29, v29
	v_lshlrev_b32_e32 v38, 16, v241
	v_and_b32_e32 v39, 0xffff0000, v241
	v_fmac_f32_e32 v29, v28, v28
	v_mul_f32_e32 v28, v31, v31
	v_pk_add_f32 v[32:33], v[26:27], v[38:39]
	v_fmac_f32_e32 v28, v30, v30
	v_cvt_pk_bf16_f32 v25, v30, v31
	v_add_f32_e32 v28, v29, v28
	v_mul_f32_e32 v29, v35, v35
	v_mul_f32_e32 v30, v33, v33
	v_fmac_f32_e32 v29, v34, v34
	v_fmac_f32_e32 v30, v32, v32
	v_add_f32_e32 v29, v29, v30
	v_add_f32_e32 v36, v28, v29
	v_lshlrev_b32_e32 v28, 16, v242
	v_and_b32_e32 v29, 0xffff0000, v242
	v_lshlrev_b32_e32 v30, 16, v243
	v_and_b32_e32 v31, 0xffff0000, v243
	v_cvt_pk_bf16_f32 v27, v32, v33
	v_lshlrev_b32_e32 v32, 16, v244
	v_and_b32_e32 v33, 0xffff0000, v244
	v_pk_add_f32 v[22:23], v[22:23], v[30:31]
	v_pk_add_f32 v[20:21], v[20:21], v[28:29]
	v_cvt_pk_bf16_f32 v26, v34, v35
	v_lshlrev_b32_e32 v34, 16, v245
	v_and_b32_e32 v35, 0xffff0000, v245
	v_pk_add_f32 v[30:31], v[16:17], v[32:33]
	v_mul_f32_e32 v16, v21, v21
	v_mul_f32_e32 v17, v23, v23
	v_pk_add_f32 v[28:29], v[18:19], v[34:35]
	v_fmac_f32_e32 v16, v20, v20
	v_fmac_f32_e32 v17, v22, v22
	v_add_f32_e32 v16, v16, v17
	v_mul_f32_e32 v17, v31, v31
	v_mul_f32_e32 v18, v29, v29
	v_fmac_f32_e32 v17, v30, v30
	v_fmac_f32_e32 v18, v28, v28
	v_add_f32_e32 v17, v17, v18
	v_add_f32_e32 v16, v16, v17
	v_add_f32_e32 v19, v36, v16
	v_mov_b32_e32 v34, v19
	v_mov_b32_e32 v251, v19
	s_nop 1
	v_permlane16_swap_b32_e32 v34, v251
	v_lshl_add_u64 v[16:17], s[16:17], 0, v[98:99]
	v_lshl_add_u64 v[32:33], v[166:167], 1, v[16:17]
	v_cvt_pk_bf16_f32 v18, v20, v21
	v_cvt_pk_bf16_f32 v20, v30, v31
	s_waitcnt lgkmcnt(0)
	v_add_f32_e32 v16, v34, v251
	v_mov_b32_e32 v17, v16
	v_mov_b32_e32 v251, v16
	s_nop 1
	v_permlane32_swap_b32_e32 v17, v251
	v_cvt_pk_bf16_f32 v19, v22, v23
	v_cvt_pk_bf16_f32 v21, v28, v29
	global_store_dwordx4 v[32:33], v[24:27], off
	global_store_dwordx4 v[32:33], v[18:21], off offset:256
	s_and_saveexec_b64 s[10:11], s[40:41]
	s_cbranch_execz .LBB0_1242
	s_waitcnt lgkmcnt(0)
	v_add_f32_e32 v18, v17, v251
	v_lshlrev_b64 v[16:17], 6, v[96:97]
	v_lshl_add_u64 v[16:17], s[0:1], 0, v[16:17]
	v_lshl_add_u64 v[16:17], s[26:27], 2, v[16:17]
	s_lshl_b32 s64, s39, 2
	v_lshl_add_u64 v[16:17], v[16:17], 0, s[64:65]
	global_store_dword v[16:17], v18, off
.LBB0_1242:
	s_or_b64 exec, exec, s[10:11]
	v_lshlrev_b32_e32 v16, 16, v246
	s_waitcnt lgkmcnt(0)
	v_and_b32_e32 v17, 0xffff0000, v246
	v_lshlrev_b32_e32 v18, 16, v247
	v_and_b32_e32 v19, 0xffff0000, v247
	v_lshlrev_b32_e32 v20, 16, v248
	v_and_b32_e32 v21, 0xffff0000, v248
	v_pk_add_f32 v[12:13], v[12:13], v[16:17]
	v_pk_add_f32 v[14:15], v[14:15], v[18:19]
	v_pk_add_f32 v[18:19], v[8:9], v[20:21]
	v_cvt_pk_bf16_f32 v8, v12, v13
	v_mul_f32_e32 v13, v13, v13
	v_lshlrev_b32_e32 v22, 16, v249
	v_and_b32_e32 v23, 0xffff0000, v249
	v_fmac_f32_e32 v13, v12, v12
	v_mul_f32_e32 v12, v15, v15
	v_pk_add_f32 v[16:17], v[10:11], v[22:23]
	v_fmac_f32_e32 v12, v14, v14
	v_cvt_pk_bf16_f32 v9, v14, v15
	v_add_f32_e32 v12, v13, v12
	v_mul_f32_e32 v13, v19, v19
	v_mul_f32_e32 v14, v17, v17
	v_fmac_f32_e32 v13, v18, v18
	v_fmac_f32_e32 v14, v16, v16
	v_add_f32_e32 v13, v13, v14
	v_add_f32_e32 v20, v12, v13
	s_waitcnt vmcnt(8)
	v_lshlrev_b32_e32 v12, 16, v64
	v_and_b32_e32 v13, 0xffff0000, v64
	v_lshlrev_b32_e32 v14, 16, v65
	v_and_b32_e32 v15, 0xffff0000, v65
	v_cvt_pk_bf16_f32 v11, v16, v17
	v_lshlrev_b32_e32 v16, 16, v66
	v_and_b32_e32 v17, 0xffff0000, v66
	v_pk_add_f32 v[6:7], v[6:7], v[14:15]
	v_pk_add_f32 v[4:5], v[4:5], v[12:13]
	v_cvt_pk_bf16_f32 v10, v18, v19
	v_lshlrev_b32_e32 v18, 16, v67
	v_and_b32_e32 v19, 0xffff0000, v67
	v_pk_add_f32 v[14:15], v[0:1], v[16:17]
	v_mul_f32_e32 v0, v5, v5
	v_mul_f32_e32 v1, v7, v7
	v_pk_add_f32 v[12:13], v[2:3], v[18:19]
	v_fmac_f32_e32 v0, v4, v4
	v_fmac_f32_e32 v1, v6, v6
	v_add_f32_e32 v0, v0, v1
	v_mul_f32_e32 v1, v15, v15
	v_mul_f32_e32 v2, v13, v13
	v_fmac_f32_e32 v1, v14, v14
	v_fmac_f32_e32 v2, v12, v12
	v_add_f32_e32 v1, v1, v2
	v_add_f32_e32 v0, v0, v1
	v_add_f32_e32 v3, v20, v0
	v_mov_b32_e32 v18, v3
	v_mov_b32_e32 v251, v3
	s_nop 1
	v_permlane16_swap_b32_e32 v18, v251
	v_lshl_add_u64 v[0:1], s[16:17], 0, v[94:95]
	v_lshl_add_u64 v[16:17], v[166:167], 1, v[0:1]
	v_cvt_pk_bf16_f32 v2, v4, v5
	v_cvt_pk_bf16_f32 v4, v14, v15
	s_waitcnt lgkmcnt(0)
	v_add_f32_e32 v0, v18, v251
	v_mov_b32_e32 v1, v0
	v_mov_b32_e32 v251, v0
	s_nop 1
	v_permlane32_swap_b32_e32 v1, v251
	v_cvt_pk_bf16_f32 v3, v6, v7
	v_cvt_pk_bf16_f32 v5, v12, v13
	global_store_dwordx4 v[16:17], v[8:11], off
	global_store_dwordx4 v[16:17], v[2:5], off offset:256
	s_and_saveexec_b64 s[10:11], s[40:41]
	s_cbranch_execz .LBB0_1244
	s_waitcnt lgkmcnt(0)
	v_add_f32_e32 v2, v1, v251
	v_lshlrev_b64 v[0:1], 6, v[92:93]
	v_lshl_add_u64 v[0:1], s[0:1], 0, v[0:1]
	v_lshl_add_u64 v[0:1], s[26:27], 2, v[0:1]
	s_lshl_b32 s64, s39, 2
	v_lshl_add_u64 v[0:1], v[0:1], 0, s[64:65]
	global_store_dword v[0:1], v2, off
